# one static s_setprio 1 for waves 4-7 before each GEMM K-loop, reset to 0 at the top of the phase loop
# baseline (speedup 1.0000x reference)
; __device__ __forceinline__ void xcd_barrier(const XcdBarrier& b) {
;     asm volatile("s_waitcnt vmcnt(0)" ::: "memory");
;     __syncthreads();
;     if (threadIdx.x == 0) {
;         unsigned* bar = b.bar;
;         __builtin_amdgcn_s_waitcnt(0);
;         unsigned nloc = b.st[0], nx = b.st[1];
;         if (nloc == 0u) { xcd_barrier_complete(bar, b.x, nloc, nx); b.st[0] = nloc; b.st[1] = nx; }
; __global__ void __launch_bounds__(NTHR, 2) mk_fwd(Params p) {
;     ...
;     for (int ph = p.ph_lo; ph < p.ph_hi; ++ph) {
;         if (ph == p.ph_lo + 1) cg::this_grid().sync();
;         else if (ph > p.ph_lo) xcd_barrier(bar);
.LBB0_9:
	s_setprio 0
	s_mov_b64 s[4:5], 0
	s_mov_b64 s[0:1], -1
	s_mov_b64 s[0:1], 0
	s_cmp_gt_i32 s85, s62
	s_cbranch_scc0 .LBB0_64
	s_waitcnt vmcnt(0)
	s_barrier
	s_mov_b64 s[4:5], exec
	v_readlane_b32 s6, v253, 8
	v_readlane_b32 s7, v253, 9
	s_and_b64 s[6:7], s[4:5], s[6:7]
	s_mov_b64 exec, s[6:7]
	s_cbranch_execz .LBB0_63
	v_readlane_b32 s6, v254, 21
	s_waitcnt vmcnt(0) expcnt(0) lgkmcnt(0)
	s_nop 0
	v_mov_b32_e32 v0, s6
	ds_read_b32 v2, v0
	v_readlane_b32 s6, v254, 22
	s_waitcnt lgkmcnt(0)
	v_cmp_ne_u32_e32 vcc, 0, v2
	v_mov_b32_e32 v0, s6
	ds_read_b32 v0, v0
	s_cbranch_vccnz .LBB0_27
	s_load_dwordx2 s[6:7], s[52:53], 0x0
	s_load_dword s8, s[52:53], 0x8
	s_mov_b32 s13, 1
	s_waitcnt lgkmcnt(0)
	s_mul_i32 s12, s7, s6
	s_mul_i32 s12, s12, s8
	s_branch .LBB0_15

; #define PG8_STAGE(bufoff, gbase, voff) do { _Pragma("unroll") for (int _i = 0; _i < 2; ++_i) \
;         __builtin_amdgcn_global_load_lds((const unsigned*)((const char*)(gbase) + (voff)[_i]), (PG8_LAS unsigned*)(lds + (bufoff) + ldsw + _i * 8192), 16, 0, 0); } while (0)
; #define PG8_LDA(dst, b, h) do { _Pragma("unroll") for (int m = 0; m < 4; ++m) _Pragma("unroll") for (int k = 0; k < 2; ++k) dst[m][k] = *(const PG8_LAS bf16x8*)(lds + PG8_SA(b, h) + aoff + m * 2048 + k * 1024); } while (0)
; #define PG8_LDB(dst, b, h) do { _Pragma("unroll") for (int n = 0; n < 2; ++n) _Pragma("unroll") for (int k = 0; k < 2; ++k) dst[n][k] = *(const PG8_LAS bf16x8*)(lds + PG8_SB(b, h) + boff + n * 2048 + k * 1024); } while (0)
; #define PG8_WAIT_L(n) asm volatile("s_waitcnt lgkmcnt(" #n ")" ::: "memory")
; #define PG8_BAR __builtin_amdgcn_s_barrier()
; #define PG8_SCHED __builtin_amdgcn_sched_barrier(0)
; template <class Epi, class Sched>
; __device__ __forceinline__ void gemm_phase(PG8_LAS unsigned char* lds, const Gemm g, const Sched& S, const Epi& E) {
;     ...
;         const bool has_next = S.next(ui + 1, nxt);
;         const char* nA = has_next ? (const char*)g.A + (size_t)nxt.pm * tstep : cA; const char* nB = has_next ? (const char*)g.Bt + (size_t)nxt.pn * tstep : cB;
;         for (int t = 0; t < nt; t += 2) {
;             const bool last = (t == nt - 2);
;             const char* a1 = cA + (size_t)(t + 1) * kstep;
;             const char* a2 = last ? nA : cA + (size_t)(t + 2) * kstep; const char* b2 = last ? nB : cB + (size_t)(t + 2) * kstep;
;             const char* a3 = a2 + kstep; const char* b3 = b2 + kstep;
;             if (last && has_next) S.a_ready(nxt);
;             PG8_LDB(B0, 0, 0); PG8_SCHED; PG8_LDA(At, 0, 0); PG8_STAGE(PG8_SA(1, 1), a1 + hstep, voffA);
;             PG8_WAIT_L(8); PG8_BAR; PG8_WAIT_L(0); PG8_MMA(0, 0, At, B0); PG8_BAR; PG8_SCHED;
;             PG8_LDB(B1, 0, 1); PG8_STAGE(PG8_SB(0, 0), b2, voffB);
;             PG8_BAR; PG8_WAIT_L(0); PG8_MMA(0, 1, At, B1); PG8_BAR;
;     ...
; #pragma unroll
;         for (int a = 0; a < 2; ++a)
; #pragma unroll
;             for (int b = 0; b < 2; ++b)
; #pragma unroll
;                 for (int m = 0; m < 4; ++m)
; #pragma unroll
;                     for (int n = 0; n < 2; ++n) acc[a][b][m][n] = (f32x4){0.f, 0.f, 0.f, 0.f};
;         cur = nxt; cA = nA; cB = nB; ++ui;
.LBB0_95:
	s_add_u32 s43, s10, 0x100
	v_mov_b32_e32 v0, 0
	s_addc_u32 s44, s11, 0
	s_mov_b32 s45, -2
	v_mov_b32_e32 v1, v0
	v_mov_b32_e32 v2, v0
	v_mov_b32_e32 v3, v0
	v_mov_b32_e32 v4, v0
	v_mov_b32_e32 v5, v0
	v_mov_b32_e32 v6, v0
	v_mov_b32_e32 v7, v0
	v_mov_b32_e32 v8, v0
	v_mov_b32_e32 v9, v0
	v_mov_b32_e32 v10, v0
	v_mov_b32_e32 v11, v0
	v_mov_b32_e32 v12, v0
	v_mov_b32_e32 v13, v0
	v_mov_b32_e32 v14, v0
	v_mov_b32_e32 v15, v0
	v_mov_b32_e32 v24, v0
	v_mov_b32_e32 v25, v0
	v_mov_b32_e32 v26, v0
	v_mov_b32_e32 v27, v0
	v_mov_b32_e32 v28, v0
	v_mov_b32_e32 v29, v0
	v_mov_b32_e32 v30, v0
	v_mov_b32_e32 v31, v0
	v_mov_b32_e32 v40, v0
	v_mov_b32_e32 v41, v0
	v_mov_b32_e32 v42, v0
	v_mov_b32_e32 v43, v0
	v_mov_b32_e32 v44, v0
	v_mov_b32_e32 v45, v0
	v_mov_b32_e32 v46, v0
	v_mov_b32_e32 v47, v0
	v_mov_b32_e32 v16, v0
	v_mov_b32_e32 v17, v0
	v_mov_b32_e32 v18, v0
	v_mov_b32_e32 v19, v0
	v_mov_b32_e32 v20, v0
	v_mov_b32_e32 v21, v0
	v_mov_b32_e32 v22, v0
	v_mov_b32_e32 v23, v0
	v_mov_b32_e32 v32, v0
	v_mov_b32_e32 v33, v0
	v_mov_b32_e32 v34, v0
	v_mov_b32_e32 v35, v0
	v_mov_b32_e32 v36, v0
	v_mov_b32_e32 v37, v0
	v_mov_b32_e32 v38, v0
	v_mov_b32_e32 v39, v0
	v_mov_b32_e32 v48, v0
	v_mov_b32_e32 v49, v0
	v_mov_b32_e32 v50, v0
	v_mov_b32_e32 v51, v0
	v_mov_b32_e32 v52, v0
	v_mov_b32_e32 v53, v0
	v_mov_b32_e32 v54, v0
	v_mov_b32_e32 v55, v0
	v_mov_b32_e32 v56, v0
	v_mov_b32_e32 v57, v0
	v_mov_b32_e32 v58, v0
	v_mov_b32_e32 v59, v0
	v_mov_b32_e32 v60, v0
	v_mov_b32_e32 v61, v0
	v_mov_b32_e32 v62, v0
	v_mov_b32_e32 v63, v0
	v_mov_b32_e32 v64, v0
	v_mov_b32_e32 v65, v0
	v_mov_b32_e32 v66, v0
	v_mov_b32_e32 v67, v0
	v_mov_b32_e32 v68, v0
	v_mov_b32_e32 v69, v0
	v_mov_b32_e32 v70, v0
	v_mov_b32_e32 v71, v0
	v_mov_b32_e32 v72, v0
	v_mov_b32_e32 v73, v0
	v_mov_b32_e32 v74, v0
	v_mov_b32_e32 v75, v0
	v_mov_b32_e32 v76, v0
	v_mov_b32_e32 v77, v0
	v_mov_b32_e32 v78, v0
	v_mov_b32_e32 v79, v0
	v_mov_b32_e32 v88, v0
	v_mov_b32_e32 v89, v0
	v_mov_b32_e32 v90, v0
	v_mov_b32_e32 v91, v0
	v_mov_b32_e32 v92, v0
	v_mov_b32_e32 v93, v0
	v_mov_b32_e32 v94, v0
	v_mov_b32_e32 v95, v0
	v_mov_b32_e32 v104, v0
	v_mov_b32_e32 v105, v0
	v_mov_b32_e32 v106, v0
	v_mov_b32_e32 v107, v0
	v_mov_b32_e32 v108, v0
	v_mov_b32_e32 v109, v0
	v_mov_b32_e32 v110, v0
	v_mov_b32_e32 v111, v0
	v_mov_b32_e32 v80, v0
	v_mov_b32_e32 v81, v0
	v_mov_b32_e32 v82, v0
	v_mov_b32_e32 v83, v0
	v_mov_b32_e32 v84, v0
	v_mov_b32_e32 v85, v0
	v_mov_b32_e32 v86, v0
	v_mov_b32_e32 v87, v0
	v_mov_b32_e32 v96, v0
	v_mov_b32_e32 v97, v0
	v_mov_b32_e32 v98, v0
	v_mov_b32_e32 v99, v0
	v_mov_b32_e32 v100, v0
	v_mov_b32_e32 v101, v0
	v_mov_b32_e32 v102, v0
	v_mov_b32_e32 v103, v0
	v_mov_b32_e32 v112, v0
	v_mov_b32_e32 v113, v0
	v_mov_b32_e32 v114, v0
	v_mov_b32_e32 v115, v0
	v_mov_b32_e32 v116, v0
	v_mov_b32_e32 v117, v0
	v_mov_b32_e32 v118, v0
	v_mov_b32_e32 v119, v0
	v_mov_b32_e32 v120, v0
	v_mov_b32_e32 v121, v0
	v_mov_b32_e32 v122, v0
	v_mov_b32_e32 v123, v0
	v_mov_b32_e32 v124, v0
	v_mov_b32_e32 v125, v0
	v_mov_b32_e32 v126, v0
	v_mov_b32_e32 v127, v0
	v_readfirstlane_b32 s98, v245
	s_nop 3
	s_cmpk_lt_u32 s98, 0x100
	s_cbranch_scc1 .Lprio_skip0
	s_setprio 1
.Lprio_skip0:
.LBB0_96:
	s_add_u32 s10, s8, 0x100
	s_addc_u32 s11, s9, 0
	v_add_u32_e32 v154, 0x10000, v139
	ds_read_b128 v[142:145], v154
	ds_read_b128 v[146:149], v154 offset:1024
	ds_read_b128 v[150:153], v154 offset:2048
	ds_read_b128 v[154:157], v154 offset:3072
	s_cmp_eq_u32 s45, 40
	s_cselect_b32 s15, s1, s11
	s_cselect_b32 s14, s0, s10
	s_cselect_b32 s13, s5, s44
	s_cselect_b32 s12, s4, s43
	s_add_i32 m0, s20, 0xc000
	ds_read_b128 v[158:161], v141
	ds_read_b128 v[162:165], v141 offset:1024
	ds_read_b128 v[166:169], v141 offset:2048
	ds_read_b128 v[170:173], v141 offset:3072
	ds_read_b128 v[178:181], v141 offset:4096
	ds_read_b128 v[182:185], v141 offset:5120
	ds_read_b128 v[186:189], v141 offset:6144
	global_load_lds_dwordx4 v134, s[8:9]
	s_add_i32 m0, s20, 0xe000
	ds_read_b128 v[190:193], v141 offset:7168
	global_load_lds_dwordx4 v136, s[8:9]
	s_waitcnt lgkmcnt(8)
	s_barrier
	s_waitcnt lgkmcnt(0)
	v_mfma_f32_16x16x32_bf16 v[124:127], v[142:145], v[158:161], v[124:127]
	v_mfma_f32_16x16x32_bf16 v[120:123], v[150:153], v[158:161], v[120:123]
	v_mfma_f32_16x16x32_bf16 v[116:119], v[142:145], v[166:169], v[116:119]
	v_mfma_f32_16x16x32_bf16 v[112:115], v[150:153], v[166:169], v[112:115]
	v_mfma_f32_16x16x32_bf16 v[100:103], v[142:145], v[178:181], v[100:103]
	v_mfma_f32_16x16x32_bf16 v[96:99], v[150:153], v[178:181], v[96:99]
	v_mfma_f32_16x16x32_bf16 v[84:87], v[142:145], v[186:189], v[84:87]
	v_mfma_f32_16x16x32_bf16 v[80:83], v[150:153], v[186:189], v[80:83]
	v_mfma_f32_16x16x32_bf16 v[124:127], v[146:149], v[162:165], v[124:127]
	v_mfma_f32_16x16x32_bf16 v[120:123], v[154:157], v[162:165], v[120:123]
	v_mfma_f32_16x16x32_bf16 v[116:119], v[146:149], v[170:173], v[116:119]
	v_mfma_f32_16x16x32_bf16 v[112:115], v[154:157], v[170:173], v[112:115]
	v_mfma_f32_16x16x32_bf16 v[100:103], v[146:149], v[182:185], v[100:103]
	v_mfma_f32_16x16x32_bf16 v[96:99], v[154:157], v[182:185], v[96:99]
	v_mfma_f32_16x16x32_bf16 v[84:87], v[146:149], v[190:193], v[84:87]
	v_mfma_f32_16x16x32_bf16 v[80:83], v[154:157], v[190:193], v[80:83]
	s_barrier
	s_add_i32 s47, 0, 0x14000
	v_add_u32_e32 v174, 0x14000, v139
	ds_read_b128 v[194:197], v174
	ds_read_b128 v[198:201], v174 offset:1024
	s_add_u32 s98, s12, 0x80
	s_addc_u32 s99, s13, 0
	s_add_i32 m0, s18, 0x10000
	ds_read_b128 v[202:205], v174 offset:2048
	global_load_lds_dwordx4 v176, s[12:13]
	s_add_i32 m0, s18, 0x12000
	ds_read_b128 v[206:209], v174 offset:3072
	global_load_lds_dwordx4 v128, s[12:13]
	s_barrier
; #define PG8_STAGE(bufoff, gbase, voff) do { _Pragma("unroll") for (int _i = 0; _i < 2; ++_i) \
;         __builtin_amdgcn_global_load_lds((const unsigned*)((const char*)(gbase) + (voff)[_i]), (PG8_LAS unsigned*)(lds + (bufoff) + ldsw + _i * 8192), 16, 0, 0); } while (0)
; #define PG8_LDA(dst, b, h) do { _Pragma("unroll") for (int m = 0; m < 4; ++m) _Pragma("unroll") for (int k = 0; k < 2; ++k) dst[m][k] = *(const PG8_LAS bf16x8*)(lds + PG8_SA(b, h) + aoff + m * 2048 + k * 1024); } while (0)
; #define PG8_LDB(dst, b, h) do { _Pragma("unroll") for (int n = 0; n < 2; ++n) _Pragma("unroll") for (int k = 0; k < 2; ++k) dst[n][k] = *(const PG8_LAS bf16x8*)(lds + PG8_SB(b, h) + boff + n * 2048 + k * 1024); } while (0)
; #define PG8_MMA(ai, bj, At, Bt) do { __builtin_amdgcn_s_setprio(1); _Pragma("unroll") for (int m = 0; m < 4; ++m) _Pragma("unroll") for (int n = 0; n < 2; ++n) _Pragma("unroll") for (int k = 0; k < 2; ++k) \
;         acc[ai][bj][m][n] = __builtin_amdgcn_mfma_f32_16x16x32_bf16(Bt[n][k], At[m][k], acc[ai][bj][m][n], 0, 0, 0); __builtin_amdgcn_s_setprio(0); } while (0)
; #define PG8_WAIT_V(n) asm volatile("s_waitcnt vmcnt(" #n ")" ::: "memory")
; #define PG8_WAIT_L(n) asm volatile("s_waitcnt lgkmcnt(" #n ")" ::: "memory")
; #define PG8_BAR __builtin_amdgcn_s_barrier()
; #define PG8_SCHED __builtin_amdgcn_sched_barrier(0)
; template <class Epi, class Sched>
; __device__ __forceinline__ void gemm_phase(PG8_LAS unsigned char* lds, const Gemm g, const Sched& S, const Epi& E) {
;     ...
;             PG8_BAR; PG8_WAIT_L(0); PG8_MMA(0, 1, At, B1); PG8_BAR;
;             PG8_LDA(At, 0, 1); PG8_STAGE(PG8_SA(0, 0), a2, voffA);
;             PG8_BAR; PG8_WAIT_L(0); PG8_MMA(1, 0, At, B0); PG8_BAR; PG8_SCHED;
;             PG8_STAGE(PG8_SB(0, 1), b2 + hstep, voffB);
;             PG8_WAIT_V(6); PG8_BAR; PG8_MMA(1, 1, At, B1); PG8_BAR;
;             PG8_LDB(B0, 1, 0); PG8_SCHED; PG8_LDA(At, 1, 0); PG8_STAGE(PG8_SA(0, 1), a2 + hstep, voffA);
;             PG8_WAIT_L(8); PG8_BAR; PG8_WAIT_L(0); PG8_MMA(0, 0, At, B0); PG8_BAR; PG8_SCHED;
	s_waitcnt lgkmcnt(0)
	v_mfma_f32_16x16x32_bf16 v[108:111], v[194:197], v[158:161], v[108:111]
	v_mfma_f32_16x16x32_bf16 v[104:107], v[202:205], v[158:161], v[104:107]
	v_mfma_f32_16x16x32_bf16 v[92:95], v[194:197], v[166:169], v[92:95]
	v_mfma_f32_16x16x32_bf16 v[88:91], v[202:205], v[166:169], v[88:91]
	v_mfma_f32_16x16x32_bf16 v[76:79], v[194:197], v[178:181], v[76:79]
	v_mfma_f32_16x16x32_bf16 v[72:75], v[202:205], v[178:181], v[72:75]
	v_mfma_f32_16x16x32_bf16 v[68:71], v[194:197], v[186:189], v[68:71]
	v_mfma_f32_16x16x32_bf16 v[64:67], v[202:205], v[186:189], v[64:67]
	v_mfma_f32_16x16x32_bf16 v[108:111], v[198:201], v[162:165], v[108:111]
	v_mfma_f32_16x16x32_bf16 v[104:107], v[206:209], v[162:165], v[104:107]
	v_mfma_f32_16x16x32_bf16 v[92:95], v[198:201], v[170:173], v[92:95]
	v_mfma_f32_16x16x32_bf16 v[88:91], v[206:209], v[170:173], v[88:91]
	v_mfma_f32_16x16x32_bf16 v[76:79], v[198:201], v[182:185], v[76:79]
	v_mfma_f32_16x16x32_bf16 v[72:75], v[206:209], v[182:185], v[72:75]
	v_mfma_f32_16x16x32_bf16 v[68:71], v[198:201], v[190:193], v[68:71]
	v_mfma_f32_16x16x32_bf16 v[64:67], v[206:209], v[190:193], v[64:67]
	s_mov_b32 m0, s20
	s_add_u32 s100, s14, 0x80
	s_addc_u32 s101, s15, 0
	s_barrier
	ds_read_b128 v[158:161], v141 offset:16384
	ds_read_b128 v[162:165], v141 offset:17408
	ds_read_b128 v[166:169], v141 offset:18432
	ds_read_b128 v[170:173], v141 offset:19456
	ds_read_b128 v[178:181], v141 offset:20480
	ds_read_b128 v[182:185], v141 offset:21504
	ds_read_b128 v[186:189], v141 offset:22528
	global_load_lds_dwordx4 v132, s[14:15]
	s_mov_b32 m0, s21
	ds_read_b128 v[190:193], v141 offset:23552
	global_load_lds_dwordx4 v130, s[14:15]
	s_barrier
	s_waitcnt lgkmcnt(0)
	v_mfma_f32_16x16x32_bf16 v[60:63], v[142:145], v[158:161], v[60:63]
	v_mfma_f32_16x16x32_bf16 v[56:59], v[150:153], v[158:161], v[56:59]
	v_mfma_f32_16x16x32_bf16 v[52:55], v[142:145], v[166:169], v[52:55]
	v_mfma_f32_16x16x32_bf16 v[48:51], v[150:153], v[166:169], v[48:51]
	v_mfma_f32_16x16x32_bf16 v[36:39], v[142:145], v[178:181], v[36:39]
	v_mfma_f32_16x16x32_bf16 v[32:35], v[150:153], v[178:181], v[32:35]
	v_mfma_f32_16x16x32_bf16 v[20:23], v[142:145], v[186:189], v[20:23]
	v_mfma_f32_16x16x32_bf16 v[16:19], v[150:153], v[186:189], v[16:19]
	v_mfma_f32_16x16x32_bf16 v[60:63], v[146:149], v[162:165], v[60:63]
	v_mfma_f32_16x16x32_bf16 v[56:59], v[154:157], v[162:165], v[56:59]
	v_mfma_f32_16x16x32_bf16 v[52:55], v[146:149], v[170:173], v[52:55]
	v_mfma_f32_16x16x32_bf16 v[48:51], v[154:157], v[170:173], v[48:51]
	v_mfma_f32_16x16x32_bf16 v[36:39], v[146:149], v[182:185], v[36:39]
	v_mfma_f32_16x16x32_bf16 v[32:35], v[154:157], v[182:185], v[32:35]
	v_mfma_f32_16x16x32_bf16 v[20:23], v[146:149], v[190:193], v[20:23]
	v_mfma_f32_16x16x32_bf16 v[16:19], v[154:157], v[190:193], v[16:19]
	s_barrier
	s_add_u32 s8, s12, 0xb0000
	s_addc_u32 s9, s13, 0
	s_add_i32 m0, s18, 0x14000
	s_nop 0
	global_load_lds_dwordx4 v176, s[8:9]
	s_add_i32 m0, s18, 0x16000
	s_nop 0
	global_load_lds_dwordx4 v128, s[8:9]
	s_waitcnt vmcnt(6)
	s_barrier
	v_mfma_f32_16x16x32_bf16 v[44:47], v[194:197], v[158:161], v[44:47]
	v_mfma_f32_16x16x32_bf16 v[40:43], v[202:205], v[158:161], v[40:43]
	v_mfma_f32_16x16x32_bf16 v[28:31], v[194:197], v[166:169], v[28:31]
	v_mfma_f32_16x16x32_bf16 v[24:27], v[202:205], v[166:169], v[24:27]
	v_mfma_f32_16x16x32_bf16 v[12:15], v[194:197], v[178:181], v[12:15]
	v_mfma_f32_16x16x32_bf16 v[8:11], v[202:205], v[178:181], v[8:11]
	v_mfma_f32_16x16x32_bf16 v[4:7], v[194:197], v[186:189], v[4:7]
	v_mfma_f32_16x16x32_bf16 v[0:3], v[202:205], v[186:189], v[0:3]
	v_mfma_f32_16x16x32_bf16 v[44:47], v[198:201], v[162:165], v[44:47]
	v_mfma_f32_16x16x32_bf16 v[40:43], v[206:209], v[162:165], v[40:43]
	v_mfma_f32_16x16x32_bf16 v[28:31], v[198:201], v[170:173], v[28:31]
	v_mfma_f32_16x16x32_bf16 v[24:27], v[206:209], v[170:173], v[24:27]
	v_mfma_f32_16x16x32_bf16 v[12:15], v[198:201], v[182:185], v[12:15]
	v_mfma_f32_16x16x32_bf16 v[8:11], v[206:209], v[182:185], v[8:11]
	v_mfma_f32_16x16x32_bf16 v[4:7], v[198:201], v[190:193], v[4:7]
	v_mfma_f32_16x16x32_bf16 v[0:3], v[206:209], v[190:193], v[0:3]
	s_add_i32 s46, 0, 0x18000
	v_add_u32_e32 v154, 0x18000, v139
	s_barrier
	ds_read_b128 v[142:145], v154
	ds_read_b128 v[146:149], v154 offset:1024
	ds_read_b128 v[150:153], v154 offset:2048
	ds_read_b128 v[154:157], v154 offset:3072
	s_add_u32 s8, s14, 0xb0000
	s_addc_u32 s9, s15, 0
	s_mov_b32 m0, s22
	ds_read_b128 v[158:161], v141 offset:32768
	ds_read_b128 v[162:165], v141 offset:33792
	ds_read_b128 v[166:169], v141 offset:34816
	ds_read_b128 v[170:173], v141 offset:35840
	ds_read_b128 v[178:181], v141 offset:36864
	ds_read_b128 v[182:185], v141 offset:37888
	ds_read_b128 v[186:189], v141 offset:38912
	global_load_lds_dwordx4 v132, s[8:9]
	s_mov_b32 m0, s23
	ds_read_b128 v[190:193], v141 offset:39936
	global_load_lds_dwordx4 v130, s[8:9]
	s_waitcnt lgkmcnt(8)
	s_barrier
	s_waitcnt lgkmcnt(0)
	v_mfma_f32_16x16x32_bf16 v[124:127], v[142:145], v[158:161], v[124:127]
	v_mfma_f32_16x16x32_bf16 v[120:123], v[150:153], v[158:161], v[120:123]
	v_mfma_f32_16x16x32_bf16 v[116:119], v[142:145], v[166:169], v[116:119]
	v_mfma_f32_16x16x32_bf16 v[112:115], v[150:153], v[166:169], v[112:115]
	v_mfma_f32_16x16x32_bf16 v[100:103], v[142:145], v[178:181], v[100:103]
	v_mfma_f32_16x16x32_bf16 v[96:99], v[150:153], v[178:181], v[96:99]
	v_mfma_f32_16x16x32_bf16 v[84:87], v[142:145], v[186:189], v[84:87]
	v_mfma_f32_16x16x32_bf16 v[80:83], v[150:153], v[186:189], v[80:83]
	v_mfma_f32_16x16x32_bf16 v[124:127], v[146:149], v[162:165], v[124:127]
	v_mfma_f32_16x16x32_bf16 v[120:123], v[154:157], v[162:165], v[120:123]
	v_mfma_f32_16x16x32_bf16 v[116:119], v[146:149], v[170:173], v[116:119]
	v_mfma_f32_16x16x32_bf16 v[112:115], v[154:157], v[170:173], v[112:115]
	v_mfma_f32_16x16x32_bf16 v[100:103], v[146:149], v[182:185], v[100:103]
	v_mfma_f32_16x16x32_bf16 v[96:99], v[154:157], v[182:185], v[96:99]
	v_mfma_f32_16x16x32_bf16 v[84:87], v[146:149], v[190:193], v[84:87]
	v_mfma_f32_16x16x32_bf16 v[80:83], v[154:157], v[190:193], v[80:83]
	s_barrier
; #define PG8_STAGE(bufoff, gbase, voff) do { _Pragma("unroll") for (int _i = 0; _i < 2; ++_i) \
;         __builtin_amdgcn_global_load_lds((const unsigned*)((const char*)(gbase) + (voff)[_i]), (PG8_LAS unsigned*)(lds + (bufoff) + ldsw + _i * 8192), 16, 0, 0); } while (0)
; #define PG8_LDA(dst, b, h) do { _Pragma("unroll") for (int m = 0; m < 4; ++m) _Pragma("unroll") for (int k = 0; k < 2; ++k) dst[m][k] = *(const PG8_LAS bf16x8*)(lds + PG8_SA(b, h) + aoff + m * 2048 + k * 1024); } while (0)
; #define PG8_LDB(dst, b, h) do { _Pragma("unroll") for (int n = 0; n < 2; ++n) _Pragma("unroll") for (int k = 0; k < 2; ++k) dst[n][k] = *(const PG8_LAS bf16x8*)(lds + PG8_SB(b, h) + boff + n * 2048 + k * 1024); } while (0)
; #define PG8_MMA(ai, bj, At, Bt) do { __builtin_amdgcn_s_setprio(1); _Pragma("unroll") for (int m = 0; m < 4; ++m) _Pragma("unroll") for (int n = 0; n < 2; ++n) _Pragma("unroll") for (int k = 0; k < 2; ++k) \
;         acc[ai][bj][m][n] = __builtin_amdgcn_mfma_f32_16x16x32_bf16(Bt[n][k], At[m][k], acc[ai][bj][m][n], 0, 0, 0); __builtin_amdgcn_s_setprio(0); } while (0)
; #define PG8_WAIT_V(n) asm volatile("s_waitcnt vmcnt(" #n ")" ::: "memory")
; #define PG8_WAIT_L(n) asm volatile("s_waitcnt lgkmcnt(" #n ")" ::: "memory")
; #define PG8_BAR __builtin_amdgcn_s_barrier()
; #define PG8_SCHED __builtin_amdgcn_sched_barrier(0)
; template <class Epi, class Sched>
; __device__ __forceinline__ void gemm_phase(PG8_LAS unsigned char* lds, const Gemm g, const Sched& S, const Epi& E) {
;     ...
;             PG8_LDB(B1, 1, 1); PG8_STAGE(PG8_SB(1, 0), b3, voffB);
;             PG8_BAR; PG8_WAIT_L(0); PG8_MMA(0, 1, At, B1); PG8_BAR;
;             PG8_LDA(At, 1, 1); PG8_STAGE(PG8_SA(1, 0), a3, voffA);
;             PG8_BAR; PG8_WAIT_L(0); PG8_MMA(1, 0, At, B0); PG8_BAR; PG8_SCHED;
;             PG8_STAGE(PG8_SB(1, 1), b3 + hstep, voffB);
;             PG8_WAIT_V(6); PG8_BAR; PG8_MMA(1, 1, At, B1); PG8_BAR;
;         }
	v_add_u32_e32 v206, 0x1c000, v139
	s_add_i32 m0, s18, 0x18000
	ds_read_b128 v[194:197], v206
	ds_read_b128 v[198:201], v206 offset:1024
	ds_read_b128 v[202:205], v206 offset:2048
	global_load_lds_dwordx4 v176, s[98:99]
	s_add_i32 m0, s18, 0x1a000
	ds_read_b128 v[206:209], v206 offset:3072
	global_load_lds_dwordx4 v128, s[98:99]
	s_barrier
	s_waitcnt lgkmcnt(0)
	v_mfma_f32_16x16x32_bf16 v[108:111], v[194:197], v[158:161], v[108:111]
	v_mfma_f32_16x16x32_bf16 v[104:107], v[202:205], v[158:161], v[104:107]
	v_mfma_f32_16x16x32_bf16 v[92:95], v[194:197], v[166:169], v[92:95]
	v_mfma_f32_16x16x32_bf16 v[88:91], v[202:205], v[166:169], v[88:91]
	v_mfma_f32_16x16x32_bf16 v[76:79], v[194:197], v[178:181], v[76:79]
	v_mfma_f32_16x16x32_bf16 v[72:75], v[202:205], v[178:181], v[72:75]
	v_mfma_f32_16x16x32_bf16 v[68:71], v[194:197], v[186:189], v[68:71]
	v_mfma_f32_16x16x32_bf16 v[64:67], v[202:205], v[186:189], v[64:67]
	v_mfma_f32_16x16x32_bf16 v[108:111], v[198:201], v[162:165], v[108:111]
	v_mfma_f32_16x16x32_bf16 v[104:107], v[206:209], v[162:165], v[104:107]
	v_mfma_f32_16x16x32_bf16 v[92:95], v[198:201], v[170:173], v[92:95]
	v_mfma_f32_16x16x32_bf16 v[88:91], v[206:209], v[170:173], v[88:91]
	v_mfma_f32_16x16x32_bf16 v[76:79], v[198:201], v[182:185], v[76:79]
	v_mfma_f32_16x16x32_bf16 v[72:75], v[206:209], v[182:185], v[72:75]
	v_mfma_f32_16x16x32_bf16 v[68:71], v[198:201], v[190:193], v[68:71]
	v_mfma_f32_16x16x32_bf16 v[64:67], v[206:209], v[190:193], v[64:67]
	s_mov_b32 m0, s27
	s_barrier
	ds_read_b128 v[158:161], v141 offset:49152
	ds_read_b128 v[162:165], v141 offset:50176
	ds_read_b128 v[166:169], v141 offset:51200
	ds_read_b128 v[170:173], v141 offset:52224
	ds_read_b128 v[178:181], v141 offset:53248
	ds_read_b128 v[182:185], v141 offset:54272
	ds_read_b128 v[186:189], v141 offset:55296
	global_load_lds_dwordx4 v132, s[100:101]
	s_mov_b32 m0, s28
	ds_read_b128 v[190:193], v141 offset:56320
	global_load_lds_dwordx4 v130, s[100:101]
	s_barrier
	s_waitcnt lgkmcnt(0)
	v_mfma_f32_16x16x32_bf16 v[60:63], v[142:145], v[158:161], v[60:63]
	v_mfma_f32_16x16x32_bf16 v[56:59], v[150:153], v[158:161], v[56:59]
	v_mfma_f32_16x16x32_bf16 v[52:55], v[142:145], v[166:169], v[52:55]
	v_mfma_f32_16x16x32_bf16 v[48:51], v[150:153], v[166:169], v[48:51]
	v_mfma_f32_16x16x32_bf16 v[36:39], v[142:145], v[178:181], v[36:39]
	v_mfma_f32_16x16x32_bf16 v[32:35], v[150:153], v[178:181], v[32:35]
	v_mfma_f32_16x16x32_bf16 v[20:23], v[142:145], v[186:189], v[20:23]
	v_mfma_f32_16x16x32_bf16 v[16:19], v[150:153], v[186:189], v[16:19]
	v_mfma_f32_16x16x32_bf16 v[60:63], v[146:149], v[162:165], v[60:63]
	v_mfma_f32_16x16x32_bf16 v[56:59], v[154:157], v[162:165], v[56:59]
	v_mfma_f32_16x16x32_bf16 v[52:55], v[146:149], v[170:173], v[52:55]
	v_mfma_f32_16x16x32_bf16 v[48:51], v[154:157], v[170:173], v[48:51]
	v_mfma_f32_16x16x32_bf16 v[36:39], v[146:149], v[182:185], v[36:39]
	v_mfma_f32_16x16x32_bf16 v[32:35], v[154:157], v[182:185], v[32:35]
	v_mfma_f32_16x16x32_bf16 v[20:23], v[146:149], v[190:193], v[20:23]
	v_mfma_f32_16x16x32_bf16 v[16:19], v[154:157], v[190:193], v[16:19]
	s_barrier
	s_add_u32 s8, s12, 0xb0080
	s_addc_u32 s9, s13, 0
	s_add_i32 m0, s18, 0x1c000
	s_nop 0
	global_load_lds_dwordx4 v176, s[8:9]
	s_add_i32 m0, s18, 0x1e000
	s_nop 0
	global_load_lds_dwordx4 v128, s[8:9]
	s_waitcnt vmcnt(6)
	s_barrier
	v_mfma_f32_16x16x32_bf16 v[44:47], v[194:197], v[158:161], v[44:47]
	v_mfma_f32_16x16x32_bf16 v[40:43], v[202:205], v[158:161], v[40:43]
	v_mfma_f32_16x16x32_bf16 v[28:31], v[194:197], v[166:169], v[28:31]
	v_mfma_f32_16x16x32_bf16 v[24:27], v[202:205], v[166:169], v[24:27]
	v_mfma_f32_16x16x32_bf16 v[12:15], v[194:197], v[178:181], v[12:15]
	v_mfma_f32_16x16x32_bf16 v[8:11], v[202:205], v[178:181], v[8:11]
	v_mfma_f32_16x16x32_bf16 v[4:7], v[194:197], v[186:189], v[4:7]
	v_mfma_f32_16x16x32_bf16 v[0:3], v[202:205], v[186:189], v[0:3]
	v_mfma_f32_16x16x32_bf16 v[44:47], v[198:201], v[162:165], v[44:47]
	v_mfma_f32_16x16x32_bf16 v[40:43], v[206:209], v[162:165], v[40:43]
	v_mfma_f32_16x16x32_bf16 v[28:31], v[198:201], v[170:173], v[28:31]
	v_mfma_f32_16x16x32_bf16 v[24:27], v[206:209], v[170:173], v[24:27]
	v_mfma_f32_16x16x32_bf16 v[12:15], v[198:201], v[182:185], v[12:15]
	v_mfma_f32_16x16x32_bf16 v[8:11], v[206:209], v[182:185], v[8:11]
	v_mfma_f32_16x16x32_bf16 v[4:7], v[198:201], v[190:193], v[4:7]
	v_mfma_f32_16x16x32_bf16 v[0:3], v[206:209], v[190:193], v[0:3]
	s_add_i32 s45, s45, 2
	s_add_u32 s43, s43, 0x100
	s_addc_u32 s44, s44, 0
	s_cmp_gt_u32 s45, 41
	s_mov_b64 s[8:9], s[10:11]
	s_barrier
	s_cbranch_scc0 .LBB0_96
; __device__ __forceinline__ unsigned cvtpk(float lo, float hi) { const f32x2 v = (f32x2){lo, hi}; const bf16v2 b = __builtin_convertvector(v, bf16v2); return __builtin_bit_cast(unsigned, b); }
; #define PG8_WAIT_V(n) asm volatile("s_waitcnt vmcnt(" #n ")" ::: "memory")
; #define PG8_BAR __builtin_amdgcn_s_barrier()
; template <class Epi, class Sched>
; __device__ __forceinline__ void gemm_phase(PG8_LAS unsigned char* lds, const Gemm g, const Sched& S, const Epi& E) {
;     ...
;         if constexpr (!Epi::AFTER_DRAIN) { E(acc, cur, wr, wc, fr, fq); S.done(cur); }
;         if (!has_next) break;
; #pragma unroll
;         for (int a = 0; a < 2; ++a)
; #pragma unroll
;             for (int b = 0; b < 2; ++b)
; #pragma unroll
;                 for (int m = 0; m < 4; ++m)
; #pragma unroll
;                     for (int n = 0; n < 2; ++n) acc[a][b][m][n] = (f32x4){0.f, 0.f, 0.f, 0.f};
;         cur = nxt; cA = nA; cB = nB; ++ui;
;     }
;     PG8_WAIT_V(0);
;     if (wr == 0) PG8_BAR;
;     PG8_BAR;
;     __device__ __forceinline__ void operator()(const f32x4 (&acc)[2][2][4][2], const pg8::Unit& u, int wr, int wc, int fr, int fq) const {
;         const int row0 = u.pm * 256 + wr * 64 + fr, col0 = u.pn * 256 + wc * 32 + 8 * fq;
; #pragma unroll
;         for (int ai = 0; ai < 2; ++ai)
; #pragma unroll
;             for (int m = 0; m < 4; ++m) { bf16_t* rowp = O + (size_t)(row0 + ai * 128 + m * 16) * ldc + col0;
; #pragma unroll
;                 for (int bj = 0; bj < 2; ++bj) { const f32x4 v0 = acc[ai][bj][m][0], v1 = acc[ai][bj][m][1];
;                     u32x4 w; w.x = cvtpk(v0[0], v0[1]); w.y = cvtpk(v0[2], v0[3]); w.z = cvtpk(v1[0], v1[1]); w.w = cvtpk(v1[2], v1[3]);
;                     *(u32x4*)(rowp + bj * 128) = w; } }
	v_lshl_add_u32 v142, s29, 8, v138
	v_lshl_or_b32 v144, s34, 8, v140
	v_ashrrev_i32_e32 v143, 31, v142
	v_readlane_b32 s8, v253, 18
	v_cvt_pk_bf16_f32 v108, v108, v109
	v_cvt_pk_bf16_f32 v109, v110, v111
	v_cvt_pk_bf16_f32 v110, v104, v105
	v_or_b32_e32 v104, 16, v142
	v_cvt_pk_bf16_f32 v92, v92, v93
	v_cvt_pk_bf16_f32 v93, v94, v95
	v_cvt_pk_bf16_f32 v94, v88, v89
	v_or_b32_e32 v88, 32, v142
	v_cvt_pk_bf16_f32 v76, v76, v77
	v_cvt_pk_bf16_f32 v77, v78, v79
	v_cvt_pk_bf16_f32 v78, v72, v73
	v_or_b32_e32 v72, 48, v142
	v_ashrrev_i32_e32 v145, 31, v144
	v_lshlrev_b64 v[146:147], 11, v[142:143]
	v_readlane_b32 s9, v253, 19
	v_ashrrev_i32_e32 v105, 31, v104
	v_ashrrev_i32_e32 v89, 31, v88
	v_ashrrev_i32_e32 v73, 31, v72
	v_lshl_add_u64 v[146:147], s[8:9], 0, v[146:147]
	v_lshlrev_b64 v[144:145], 1, v[144:145]
	v_lshlrev_b64 v[104:105], 11, v[104:105]
	v_lshlrev_b64 v[88:89], 11, v[88:89]
	v_lshlrev_b64 v[72:73], 11, v[72:73]
	v_lshl_add_u64 v[146:147], v[146:147], 0, v[144:145]
	v_lshl_add_u64 v[104:105], s[8:9], 0, v[104:105]
	v_lshl_add_u64 v[88:89], s[8:9], 0, v[88:89]
	v_lshl_add_u64 v[72:73], s[8:9], 0, v[72:73]
	s_mov_b64 s[8:9], 0x40000
	v_cvt_pk_bf16_f32 v68, v68, v69
	v_cvt_pk_bf16_f32 v69, v70, v71
	v_cvt_pk_bf16_f32 v70, v64, v65
	v_lshl_add_u64 v[64:65], v[146:147], 0, s[8:9]
	v_cvt_pk_bf16_f32 v60, v60, v61
	v_cvt_pk_bf16_f32 v61, v62, v63
	v_cvt_pk_bf16_f32 v62, v56, v57
	v_add_co_u32_e32 v56, vcc, s2, v146
	v_cvt_pk_bf16_f32 v44, v44, v45
	v_cvt_pk_bf16_f32 v45, v46, v47
	v_cvt_pk_bf16_f32 v46, v40, v41
	v_cvt_pk_bf16_f32 v47, v42, v43
	s_mov_b64 s[8:9], 0x48000
	v_addc_co_u32_e32 v57, vcc, 0, v147, vcc
	global_store_dwordx4 v[64:65], v[44:47], off offset:256
	v_cvt_pk_bf16_f32 v28, v28, v29
	v_cvt_pk_bf16_f32 v29, v30, v31
	v_lshl_add_u64 v[44:45], v[146:147], 0, s[8:9]
	s_mov_b32 s8, 0x48000
	v_add_co_u32_e32 v46, vcc, s8, v146
	v_cvt_pk_bf16_f32 v30, v24, v25
	v_cvt_pk_bf16_f32 v31, v26, v27
	s_mov_b64 s[8:9], 0x50000
	v_addc_co_u32_e32 v47, vcc, 0, v147, vcc
	global_store_dwordx4 v[44:45], v[28:31], off offset:256
	v_cvt_pk_bf16_f32 v12, v12, v13
	v_cvt_pk_bf16_f32 v13, v14, v15
	v_lshl_add_u64 v[28:29], v[146:147], 0, s[8:9]
	s_mov_b32 s8, 0x50000
	v_add_co_u32_e32 v30, vcc, s8, v146
	v_cvt_pk_bf16_f32 v14, v8, v9
	v_cvt_pk_bf16_f32 v15, v10, v11
	s_mov_b64 s[8:9], 0x58000
	v_cvt_pk_bf16_f32 v111, v106, v107
	v_addc_co_u32_e32 v31, vcc, 0, v147, vcc
	global_store_dwordx4 v[28:29], v[12:15], off offset:256
	global_store_dwordx4 v[146:147], v[108:111], off offset:256
	v_cvt_pk_bf16_f32 v95, v90, v91
	v_lshl_add_u64 v[12:13], v[146:147], 0, s[8:9]
	s_mov_b32 s8, 0x58000
	v_lshl_add_u64 v[108:109], v[104:105], 0, v[144:145]
	v_add_co_u32_e32 v14, vcc, s8, v146
	global_store_dwordx4 v[108:109], v[92:95], off offset:256
	v_cvt_pk_bf16_f32 v79, v74, v75
	v_addc_co_u32_e32 v15, vcc, 0, v147, vcc
	v_lshl_add_u64 v[92:93], v[88:89], 0, v[144:145]
	v_cvt_pk_bf16_f32 v124, v124, v125
	v_cvt_pk_bf16_f32 v125, v126, v127
	v_cvt_pk_bf16_f32 v126, v120, v121
	v_cvt_pk_bf16_f32 v127, v122, v123
	v_cvt_pk_bf16_f32 v104, v116, v117
	v_cvt_pk_bf16_f32 v105, v118, v119
	v_cvt_pk_bf16_f32 v106, v112, v113
	v_cvt_pk_bf16_f32 v107, v114, v115
	v_cvt_pk_bf16_f32 v88, v100, v101
	v_cvt_pk_bf16_f32 v89, v102, v103
	v_cvt_pk_bf16_f32 v90, v96, v97
	v_cvt_pk_bf16_f32 v91, v98, v99
	global_store_dwordx4 v[92:93], v[76:79], off offset:256
	v_cvt_pk_bf16_f32 v74, v80, v81
	v_cvt_pk_bf16_f32 v75, v82, v83
	v_lshl_add_u64 v[76:77], v[72:73], 0, v[144:145]
	v_cvt_pk_bf16_f32 v72, v84, v85
	v_cvt_pk_bf16_f32 v73, v86, v87
	v_cvt_pk_bf16_f32 v71, v66, v67
	v_cvt_pk_bf16_f32 v63, v58, v59
	v_cvt_pk_bf16_f32 v40, v52, v53
	v_cvt_pk_bf16_f32 v41, v54, v55
	v_cvt_pk_bf16_f32 v42, v48, v49
	v_cvt_pk_bf16_f32 v43, v50, v51
	v_cvt_pk_bf16_f32 v24, v36, v37
	v_cvt_pk_bf16_f32 v25, v38, v39
	v_cvt_pk_bf16_f32 v26, v32, v33
	v_cvt_pk_bf16_f32 v27, v34, v35
	v_cvt_pk_bf16_f32 v8, v20, v21
	v_cvt_pk_bf16_f32 v9, v22, v23
	v_cvt_pk_bf16_f32 v10, v16, v17
	v_cvt_pk_bf16_f32 v11, v18, v19
	v_cvt_pk_bf16_f32 v4, v4, v5
	v_cvt_pk_bf16_f32 v5, v6, v7
	v_cvt_pk_bf16_f32 v6, v0, v1
	v_cvt_pk_bf16_f32 v7, v2, v3
	s_and_b64 vcc, exec, s[38:39]
	s_mov_b32 s34, s40
	s_mov_b32 s29, s41
	s_mov_b64 s[10:11], s[4:5]
	s_mov_b64 s[8:9], s[0:1]
	global_store_dwordx4 v[146:147], v[124:127], off
	global_store_dwordx4 v[108:109], v[104:107], off
	global_store_dwordx4 v[92:93], v[88:91], off
	global_store_dwordx4 v[76:77], v[72:75], off
	global_store_dwordx4 v[76:77], v[68:71], off offset:256
	global_store_dwordx4 v[56:57], v[60:63], off
	global_store_dwordx4 v[46:47], v[40:43], off
	global_store_dwordx4 v[30:31], v[24:27], off
	global_store_dwordx4 v[14:15], v[8:11], off
	global_store_dwordx4 v[12:13], v[4:7], off offset:256
	s_cbranch_vccz .LBB0_89
	s_waitcnt vmcnt(0)
	s_cmpk_gt_u32 s17, 0xff
	v_readlane_b32 s2, v254, 59
	s_cbranch_scc1 .LBB0_100
	s_barrier

; #define PG8_STAGE(bufoff, gbase, voff) do { _Pragma("unroll") for (int _i = 0; _i < 2; ++_i) \
;         __builtin_amdgcn_global_load_lds((const unsigned*)((const char*)(gbase) + (voff)[_i]), (PG8_LAS unsigned*)(lds + (bufoff) + ldsw + _i * 8192), 16, 0, 0); } while (0)
; #define PG8_LDA(dst, b, h) do { _Pragma("unroll") for (int m = 0; m < 4; ++m) _Pragma("unroll") for (int k = 0; k < 2; ++k) dst[m][k] = *(const PG8_LAS bf16x8*)(lds + PG8_SA(b, h) + aoff + m * 2048 + k * 1024); } while (0)
; #define PG8_LDB(dst, b, h) do { _Pragma("unroll") for (int n = 0; n < 2; ++n) _Pragma("unroll") for (int k = 0; k < 2; ++k) dst[n][k] = *(const PG8_LAS bf16x8*)(lds + PG8_SB(b, h) + boff + n * 2048 + k * 1024); } while (0)
; #define PG8_WAIT_L(n) asm volatile("s_waitcnt lgkmcnt(" #n ")" ::: "memory")
; #define PG8_BAR __builtin_amdgcn_s_barrier()
; #define PG8_SCHED __builtin_amdgcn_sched_barrier(0)
; template <class Epi, class Sched>
; __device__ __forceinline__ void gemm_phase(PG8_LAS unsigned char* lds, const Gemm g, const Sched& S, const Epi& E) {
;     ...
;         const bool has_next = S.next(ui + 1, nxt);
;         const char* nA = has_next ? (const char*)g.A + (size_t)nxt.pm * tstep : cA; const char* nB = has_next ? (const char*)g.Bt + (size_t)nxt.pn * tstep : cB;
;         for (int t = 0; t < nt; t += 2) {
;             const bool last = (t == nt - 2);
;             const char* a1 = cA + (size_t)(t + 1) * kstep;
;             const char* a2 = last ? nA : cA + (size_t)(t + 2) * kstep; const char* b2 = last ? nB : cB + (size_t)(t + 2) * kstep;
;             const char* a3 = a2 + kstep; const char* b3 = b2 + kstep;
;             if (last && has_next) S.a_ready(nxt);
;             PG8_LDB(B0, 0, 0); PG8_SCHED; PG8_LDA(At, 0, 0); PG8_STAGE(PG8_SA(1, 1), a1 + hstep, voffA);
;             PG8_WAIT_L(8); PG8_BAR; PG8_WAIT_L(0); PG8_MMA(0, 0, At, B0); PG8_BAR; PG8_SCHED;
;     ...
; #pragma unroll
;         for (int a = 0; a < 2; ++a)
; #pragma unroll
;             for (int b = 0; b < 2; ++b)
; #pragma unroll
;                 for (int m = 0; m < 4; ++m)
; #pragma unroll
;                     for (int n = 0; n < 2; ++n) acc[a][b][m][n] = (f32x4){0.f, 0.f, 0.f, 0.f};
;         cur = nxt; cA = nA; cB = nB; ++ui;
.LBB0_113:
	v_mov_b64_e32 v[0:1], 0x580
	s_ashr_i32 s5, s4, 31
	v_cmp_lt_i64_e32 vcc, s[6:7], v[0:1]
	s_lshl_b64 s[6:7], s[4:5], 19
	s_add_u32 s6, s94, s6
	s_addc_u32 s7, s95, s7
	s_and_b64 s[8:9], vcc, exec
	s_cselect_b32 s5, s7, s13
	s_cselect_b32 s40, s6, s12
	s_ashr_i32 s1, s0, 31
	s_lshl_b64 s[8:9], s[0:1], 19
	v_readlane_b32 s16, v253, 12
	v_readlane_b32 s17, v253, 13
	s_add_u32 s8, s16, s8
	s_addc_u32 s9, s17, s9
	s_and_b64 s[16:17], vcc, exec
	s_cselect_b32 s1, s9, s15
	s_cselect_b32 s41, s8, s14
	s_add_u32 s12, s12, 0x40080
	s_addc_u32 s13, s13, 0
	s_add_u32 s43, s14, 0x100
	v_mov_b32_e32 v0, 0
	s_addc_u32 s44, s15, 0
	s_mov_b32 s45, -2
	v_mov_b32_e32 v1, v0
	v_mov_b32_e32 v2, v0
	v_mov_b32_e32 v3, v0
	v_mov_b32_e32 v8, v0
	v_mov_b32_e32 v9, v0
	v_mov_b32_e32 v10, v0
	v_mov_b32_e32 v11, v0
	v_mov_b32_e32 v16, v0
	v_mov_b32_e32 v17, v0
	v_mov_b32_e32 v18, v0
	v_mov_b32_e32 v19, v0
	v_mov_b32_e32 v24, v0
	v_mov_b32_e32 v25, v0
	v_mov_b32_e32 v26, v0
	v_mov_b32_e32 v27, v0
	v_mov_b32_e32 v32, v0
	v_mov_b32_e32 v33, v0
	v_mov_b32_e32 v34, v0
	v_mov_b32_e32 v35, v0
	v_mov_b32_e32 v40, v0
	v_mov_b32_e32 v41, v0
	v_mov_b32_e32 v42, v0
	v_mov_b32_e32 v43, v0
	v_mov_b32_e32 v48, v0
	v_mov_b32_e32 v49, v0
	v_mov_b32_e32 v50, v0
	v_mov_b32_e32 v51, v0
	v_mov_b32_e32 v56, v0
	v_mov_b32_e32 v57, v0
	v_mov_b32_e32 v58, v0
	v_mov_b32_e32 v59, v0
	v_mov_b32_e32 v4, v0
	v_mov_b32_e32 v5, v0
	v_mov_b32_e32 v6, v0
	v_mov_b32_e32 v7, v0
	v_mov_b32_e32 v12, v0
	v_mov_b32_e32 v13, v0
	v_mov_b32_e32 v14, v0
	v_mov_b32_e32 v15, v0
	v_mov_b32_e32 v20, v0
	v_mov_b32_e32 v21, v0
	v_mov_b32_e32 v22, v0
	v_mov_b32_e32 v23, v0
	v_mov_b32_e32 v28, v0
	v_mov_b32_e32 v29, v0
	v_mov_b32_e32 v30, v0
	v_mov_b32_e32 v31, v0
	v_mov_b32_e32 v36, v0
	v_mov_b32_e32 v37, v0
	v_mov_b32_e32 v38, v0
	v_mov_b32_e32 v39, v0
	v_mov_b32_e32 v44, v0
	v_mov_b32_e32 v45, v0
	v_mov_b32_e32 v46, v0
	v_mov_b32_e32 v47, v0
	v_mov_b32_e32 v52, v0
	v_mov_b32_e32 v53, v0
	v_mov_b32_e32 v54, v0
	v_mov_b32_e32 v55, v0
	v_mov_b32_e32 v60, v0
	v_mov_b32_e32 v61, v0
	v_mov_b32_e32 v62, v0
	v_mov_b32_e32 v63, v0
	v_mov_b32_e32 v64, v0
	v_mov_b32_e32 v65, v0
	v_mov_b32_e32 v66, v0
	v_mov_b32_e32 v67, v0
	v_mov_b32_e32 v72, v0
	v_mov_b32_e32 v73, v0
	v_mov_b32_e32 v74, v0
	v_mov_b32_e32 v75, v0
	v_mov_b32_e32 v80, v0
	v_mov_b32_e32 v81, v0
	v_mov_b32_e32 v82, v0
	v_mov_b32_e32 v83, v0
	v_mov_b32_e32 v88, v0
	v_mov_b32_e32 v89, v0
	v_mov_b32_e32 v90, v0
	v_mov_b32_e32 v91, v0
	v_mov_b32_e32 v96, v0
	v_mov_b32_e32 v97, v0
	v_mov_b32_e32 v98, v0
	v_mov_b32_e32 v99, v0
	v_mov_b32_e32 v104, v0
	v_mov_b32_e32 v105, v0
	v_mov_b32_e32 v106, v0
	v_mov_b32_e32 v107, v0
	v_mov_b32_e32 v112, v0
	v_mov_b32_e32 v113, v0
	v_mov_b32_e32 v114, v0
	v_mov_b32_e32 v115, v0
	v_mov_b32_e32 v120, v0
	v_mov_b32_e32 v121, v0
	v_mov_b32_e32 v122, v0
	v_mov_b32_e32 v123, v0
	v_mov_b32_e32 v68, v0
	v_mov_b32_e32 v69, v0
	v_mov_b32_e32 v70, v0
	v_mov_b32_e32 v71, v0
	v_mov_b32_e32 v76, v0
	v_mov_b32_e32 v77, v0
	v_mov_b32_e32 v78, v0
	v_mov_b32_e32 v79, v0
	v_mov_b32_e32 v84, v0
	v_mov_b32_e32 v85, v0
	v_mov_b32_e32 v86, v0
	v_mov_b32_e32 v87, v0
	v_mov_b32_e32 v92, v0
	v_mov_b32_e32 v93, v0
	v_mov_b32_e32 v94, v0
	v_mov_b32_e32 v95, v0
	v_mov_b32_e32 v100, v0
	v_mov_b32_e32 v101, v0
	v_mov_b32_e32 v102, v0
	v_mov_b32_e32 v103, v0
	v_mov_b32_e32 v108, v0
	v_mov_b32_e32 v109, v0
	v_mov_b32_e32 v110, v0
	v_mov_b32_e32 v111, v0
	v_mov_b32_e32 v116, v0
	v_mov_b32_e32 v117, v0
	v_mov_b32_e32 v118, v0
	v_mov_b32_e32 v119, v0
	v_mov_b32_e32 v124, v0
	v_mov_b32_e32 v125, v0
	v_mov_b32_e32 v126, v0
	v_mov_b32_e32 v127, v0
	v_readfirstlane_b32 s98, v245
	s_nop 3
	s_cmpk_lt_u32 s98, 0x100
	s_cbranch_scc1 .Lprio_skip1
	s_setprio 1
.Lprio_skip1:
.LBB0_114:
	s_add_u32 s14, s12, 0xfffc0080
	s_addc_u32 s15, s13, -1
	v_add_u32_e32 v154, 0x10000, v143
	ds_read_b128 v[138:141], v154
	ds_read_b128 v[146:149], v154 offset:1024
	ds_read_b128 v[150:153], v154 offset:2048
	ds_read_b128 v[154:157], v154 offset:3072
	s_cmp_eq_u32 s45, 12
	s_cselect_b32 s17, s5, s15
	s_cselect_b32 s16, s40, s14
	s_cselect_b32 s15, s1, s44
	s_cselect_b32 s14, s41, s43
	s_add_i32 m0, s11, 0xc000
	ds_read_b128 v[158:161], v145
	ds_read_b128 v[162:165], v145 offset:1024
	ds_read_b128 v[166:169], v145 offset:2048
	ds_read_b128 v[170:173], v145 offset:3072
	ds_read_b128 v[178:181], v145 offset:4096
	ds_read_b128 v[182:185], v145 offset:5120
	ds_read_b128 v[186:189], v145 offset:6144
	global_load_lds_dwordx4 v134, s[12:13]
	s_add_i32 m0, s11, 0xe000
	ds_read_b128 v[190:193], v145 offset:7168
	global_load_lds_dwordx4 v136, s[12:13]
	s_waitcnt lgkmcnt(8)
	s_barrier
	s_waitcnt lgkmcnt(0)
	v_mfma_f32_16x16x32_bf16 v[124:127], v[138:141], v[158:161], v[124:127]
	v_mfma_f32_16x16x32_bf16 v[116:119], v[150:153], v[158:161], v[116:119]
	v_mfma_f32_16x16x32_bf16 v[108:111], v[138:141], v[166:169], v[108:111]
	v_mfma_f32_16x16x32_bf16 v[100:103], v[150:153], v[166:169], v[100:103]
	v_mfma_f32_16x16x32_bf16 v[92:95], v[138:141], v[178:181], v[92:95]
	v_mfma_f32_16x16x32_bf16 v[84:87], v[150:153], v[178:181], v[84:87]
	v_mfma_f32_16x16x32_bf16 v[76:79], v[138:141], v[186:189], v[76:79]
	v_mfma_f32_16x16x32_bf16 v[68:71], v[150:153], v[186:189], v[68:71]
	v_mfma_f32_16x16x32_bf16 v[124:127], v[146:149], v[162:165], v[124:127]
	v_mfma_f32_16x16x32_bf16 v[116:119], v[154:157], v[162:165], v[116:119]
	v_mfma_f32_16x16x32_bf16 v[108:111], v[146:149], v[170:173], v[108:111]
	v_mfma_f32_16x16x32_bf16 v[100:103], v[154:157], v[170:173], v[100:103]
	v_mfma_f32_16x16x32_bf16 v[92:95], v[146:149], v[182:185], v[92:95]
	v_mfma_f32_16x16x32_bf16 v[84:87], v[154:157], v[182:185], v[84:87]
	v_mfma_f32_16x16x32_bf16 v[76:79], v[146:149], v[190:193], v[76:79]
	v_mfma_f32_16x16x32_bf16 v[68:71], v[154:157], v[190:193], v[68:71]
	s_barrier
; #define PG8_STAGE(bufoff, gbase, voff) do { _Pragma("unroll") for (int _i = 0; _i < 2; ++_i) \
;         __builtin_amdgcn_global_load_lds((const unsigned*)((const char*)(gbase) + (voff)[_i]), (PG8_LAS unsigned*)(lds + (bufoff) + ldsw + _i * 8192), 16, 0, 0); } while (0)
; #define PG8_LDA(dst, b, h) do { _Pragma("unroll") for (int m = 0; m < 4; ++m) _Pragma("unroll") for (int k = 0; k < 2; ++k) dst[m][k] = *(const PG8_LAS bf16x8*)(lds + PG8_SA(b, h) + aoff + m * 2048 + k * 1024); } while (0)
; #define PG8_LDB(dst, b, h) do { _Pragma("unroll") for (int n = 0; n < 2; ++n) _Pragma("unroll") for (int k = 0; k < 2; ++k) dst[n][k] = *(const PG8_LAS bf16x8*)(lds + PG8_SB(b, h) + boff + n * 2048 + k * 1024); } while (0)
; #define PG8_MMA(ai, bj, At, Bt) do { __builtin_amdgcn_s_setprio(1); _Pragma("unroll") for (int m = 0; m < 4; ++m) _Pragma("unroll") for (int n = 0; n < 2; ++n) _Pragma("unroll") for (int k = 0; k < 2; ++k) \
;         acc[ai][bj][m][n] = __builtin_amdgcn_mfma_f32_16x16x32_bf16(Bt[n][k], At[m][k], acc[ai][bj][m][n], 0, 0, 0); __builtin_amdgcn_s_setprio(0); } while (0)
; #define PG8_WAIT_V(n) asm volatile("s_waitcnt vmcnt(" #n ")" ::: "memory")
; #define PG8_WAIT_L(n) asm volatile("s_waitcnt lgkmcnt(" #n ")" ::: "memory")
; #define PG8_BAR __builtin_amdgcn_s_barrier()
; #define PG8_SCHED __builtin_amdgcn_sched_barrier(0)
; template <class Epi, class Sched>
; __device__ __forceinline__ void gemm_phase(PG8_LAS unsigned char* lds, const Gemm g, const Sched& S, const Epi& E) {
;     ...
;             PG8_LDB(B1, 0, 1); PG8_STAGE(PG8_SB(0, 0), b2, voffB);
;             PG8_BAR; PG8_WAIT_L(0); PG8_MMA(0, 1, At, B1); PG8_BAR;
;             PG8_LDA(At, 0, 1); PG8_STAGE(PG8_SA(0, 0), a2, voffA);
;             PG8_BAR; PG8_WAIT_L(0); PG8_MMA(1, 0, At, B0); PG8_BAR; PG8_SCHED;
;             PG8_STAGE(PG8_SB(0, 1), b2 + hstep, voffB);
;             PG8_WAIT_V(6); PG8_BAR; PG8_MMA(1, 1, At, B1); PG8_BAR;
;             PG8_LDB(B0, 1, 0); PG8_SCHED; PG8_LDA(At, 1, 0); PG8_STAGE(PG8_SA(0, 1), a2 + hstep, voffA);
	s_add_i32 s48, 0, 0x14000
	v_add_u32_e32 v174, 0x14000, v143
	ds_read_b128 v[194:197], v174
	ds_read_b128 v[198:201], v174 offset:1024
	s_add_u32 s98, s14, 0x80
	s_addc_u32 s99, s15, 0
	s_add_i32 m0, s20, 0x10000
	ds_read_b128 v[202:205], v174 offset:2048
	global_load_lds_dwordx4 v176, s[14:15]
	s_add_i32 m0, s20, 0x12000
	ds_read_b128 v[206:209], v174 offset:3072
	global_load_lds_dwordx4 v128, s[14:15]
	s_barrier
	s_waitcnt lgkmcnt(0)
	v_mfma_f32_16x16x32_bf16 v[120:123], v[194:197], v[158:161], v[120:123]
	v_mfma_f32_16x16x32_bf16 v[112:115], v[202:205], v[158:161], v[112:115]
	v_mfma_f32_16x16x32_bf16 v[104:107], v[194:197], v[166:169], v[104:107]
	v_mfma_f32_16x16x32_bf16 v[96:99], v[202:205], v[166:169], v[96:99]
	v_mfma_f32_16x16x32_bf16 v[88:91], v[194:197], v[178:181], v[88:91]
	v_mfma_f32_16x16x32_bf16 v[80:83], v[202:205], v[178:181], v[80:83]
	v_mfma_f32_16x16x32_bf16 v[72:75], v[194:197], v[186:189], v[72:75]
	v_mfma_f32_16x16x32_bf16 v[64:67], v[202:205], v[186:189], v[64:67]
	v_mfma_f32_16x16x32_bf16 v[120:123], v[198:201], v[162:165], v[120:123]
	v_mfma_f32_16x16x32_bf16 v[112:115], v[206:209], v[162:165], v[112:115]
	v_mfma_f32_16x16x32_bf16 v[104:107], v[198:201], v[170:173], v[104:107]
	v_mfma_f32_16x16x32_bf16 v[96:99], v[206:209], v[170:173], v[96:99]
	v_mfma_f32_16x16x32_bf16 v[88:91], v[198:201], v[182:185], v[88:91]
	v_mfma_f32_16x16x32_bf16 v[80:83], v[206:209], v[182:185], v[80:83]
	v_mfma_f32_16x16x32_bf16 v[72:75], v[198:201], v[190:193], v[72:75]
	v_mfma_f32_16x16x32_bf16 v[64:67], v[206:209], v[190:193], v[64:67]
	s_mov_b32 m0, s11
	s_add_u32 s100, s16, 0x80
	s_addc_u32 s101, s17, 0
	s_barrier
	ds_read_b128 v[158:161], v145 offset:16384
	ds_read_b128 v[162:165], v145 offset:17408
	ds_read_b128 v[166:169], v145 offset:18432
	ds_read_b128 v[170:173], v145 offset:19456
	ds_read_b128 v[178:181], v145 offset:20480
	ds_read_b128 v[182:185], v145 offset:21504
	ds_read_b128 v[186:189], v145 offset:22528
	global_load_lds_dwordx4 v132, s[16:17]
	s_mov_b32 m0, s22
	ds_read_b128 v[190:193], v145 offset:23552
	global_load_lds_dwordx4 v130, s[16:17]
	s_barrier
	s_waitcnt lgkmcnt(0)
	v_mfma_f32_16x16x32_bf16 v[60:63], v[138:141], v[158:161], v[60:63]
	v_mfma_f32_16x16x32_bf16 v[52:55], v[150:153], v[158:161], v[52:55]
	v_mfma_f32_16x16x32_bf16 v[44:47], v[138:141], v[166:169], v[44:47]
	v_mfma_f32_16x16x32_bf16 v[36:39], v[150:153], v[166:169], v[36:39]
	v_mfma_f32_16x16x32_bf16 v[28:31], v[138:141], v[178:181], v[28:31]
	v_mfma_f32_16x16x32_bf16 v[20:23], v[150:153], v[178:181], v[20:23]
	v_mfma_f32_16x16x32_bf16 v[12:15], v[138:141], v[186:189], v[12:15]
	v_mfma_f32_16x16x32_bf16 v[4:7], v[150:153], v[186:189], v[4:7]
	v_mfma_f32_16x16x32_bf16 v[60:63], v[146:149], v[162:165], v[60:63]
	v_mfma_f32_16x16x32_bf16 v[52:55], v[154:157], v[162:165], v[52:55]
	v_mfma_f32_16x16x32_bf16 v[44:47], v[146:149], v[170:173], v[44:47]
	v_mfma_f32_16x16x32_bf16 v[36:39], v[154:157], v[170:173], v[36:39]
	v_mfma_f32_16x16x32_bf16 v[28:31], v[146:149], v[182:185], v[28:31]
	v_mfma_f32_16x16x32_bf16 v[20:23], v[154:157], v[182:185], v[20:23]
	v_mfma_f32_16x16x32_bf16 v[12:15], v[146:149], v[190:193], v[12:15]
	v_mfma_f32_16x16x32_bf16 v[4:7], v[154:157], v[190:193], v[4:7]
	s_barrier
	s_add_u32 s46, s14, 0x40000
	s_addc_u32 s47, s15, 0
	s_add_i32 m0, s20, 0x14000
	s_nop 0
	global_load_lds_dwordx4 v176, s[46:47]
	s_add_i32 m0, s20, 0x16000
	s_nop 0
	global_load_lds_dwordx4 v128, s[46:47]
	s_waitcnt vmcnt(6)
	s_barrier
	v_mfma_f32_16x16x32_bf16 v[56:59], v[194:197], v[158:161], v[56:59]
	v_mfma_f32_16x16x32_bf16 v[48:51], v[202:205], v[158:161], v[48:51]
	v_mfma_f32_16x16x32_bf16 v[40:43], v[194:197], v[166:169], v[40:43]
	v_mfma_f32_16x16x32_bf16 v[32:35], v[202:205], v[166:169], v[32:35]
	v_mfma_f32_16x16x32_bf16 v[24:27], v[194:197], v[178:181], v[24:27]
	v_mfma_f32_16x16x32_bf16 v[16:19], v[202:205], v[178:181], v[16:19]
	v_mfma_f32_16x16x32_bf16 v[8:11], v[194:197], v[186:189], v[8:11]
	v_mfma_f32_16x16x32_bf16 v[0:3], v[202:205], v[186:189], v[0:3]
	v_mfma_f32_16x16x32_bf16 v[56:59], v[198:201], v[162:165], v[56:59]
	v_mfma_f32_16x16x32_bf16 v[48:51], v[206:209], v[162:165], v[48:51]
	v_mfma_f32_16x16x32_bf16 v[40:43], v[198:201], v[170:173], v[40:43]
	v_mfma_f32_16x16x32_bf16 v[32:35], v[206:209], v[170:173], v[32:35]
	v_mfma_f32_16x16x32_bf16 v[24:27], v[198:201], v[182:185], v[24:27]
	v_mfma_f32_16x16x32_bf16 v[16:19], v[206:209], v[182:185], v[16:19]
	v_mfma_f32_16x16x32_bf16 v[8:11], v[198:201], v[190:193], v[8:11]
	v_mfma_f32_16x16x32_bf16 v[0:3], v[206:209], v[190:193], v[0:3]
	v_add_u32_e32 v154, 0x18000, v143
	s_barrier
	ds_read_b128 v[138:141], v154
	ds_read_b128 v[146:149], v154 offset:1024
	ds_read_b128 v[150:153], v154 offset:2048
	ds_read_b128 v[154:157], v154 offset:3072
	s_add_u32 s16, s16, 0x40000
	s_addc_u32 s17, s17, 0
	s_mov_b32 m0, s23
	ds_read_b128 v[158:161], v145 offset:32768
	ds_read_b128 v[162:165], v145 offset:33792
	ds_read_b128 v[166:169], v145 offset:34816
	ds_read_b128 v[170:173], v145 offset:35840
	ds_read_b128 v[178:181], v145 offset:36864
	ds_read_b128 v[182:185], v145 offset:37888
	ds_read_b128 v[186:189], v145 offset:38912
	global_load_lds_dwordx4 v132, s[16:17]
	s_mov_b32 m0, s26
	ds_read_b128 v[190:193], v145 offset:39936
	global_load_lds_dwordx4 v130, s[16:17]
	s_waitcnt lgkmcnt(8)
	s_barrier
; #define PG8_STAGE(bufoff, gbase, voff) do { _Pragma("unroll") for (int _i = 0; _i < 2; ++_i) \
;         __builtin_amdgcn_global_load_lds((const unsigned*)((const char*)(gbase) + (voff)[_i]), (PG8_LAS unsigned*)(lds + (bufoff) + ldsw + _i * 8192), 16, 0, 0); } while (0)
; #define PG8_LDA(dst, b, h) do { _Pragma("unroll") for (int m = 0; m < 4; ++m) _Pragma("unroll") for (int k = 0; k < 2; ++k) dst[m][k] = *(const PG8_LAS bf16x8*)(lds + PG8_SA(b, h) + aoff + m * 2048 + k * 1024); } while (0)
; #define PG8_LDB(dst, b, h) do { _Pragma("unroll") for (int n = 0; n < 2; ++n) _Pragma("unroll") for (int k = 0; k < 2; ++k) dst[n][k] = *(const PG8_LAS bf16x8*)(lds + PG8_SB(b, h) + boff + n * 2048 + k * 1024); } while (0)
; #define PG8_MMA(ai, bj, At, Bt) do { __builtin_amdgcn_s_setprio(1); _Pragma("unroll") for (int m = 0; m < 4; ++m) _Pragma("unroll") for (int n = 0; n < 2; ++n) _Pragma("unroll") for (int k = 0; k < 2; ++k) \
;         acc[ai][bj][m][n] = __builtin_amdgcn_mfma_f32_16x16x32_bf16(Bt[n][k], At[m][k], acc[ai][bj][m][n], 0, 0, 0); __builtin_amdgcn_s_setprio(0); } while (0)
; #define PG8_WAIT_V(n) asm volatile("s_waitcnt vmcnt(" #n ")" ::: "memory")
; #define PG8_WAIT_L(n) asm volatile("s_waitcnt lgkmcnt(" #n ")" ::: "memory")
; #define PG8_BAR __builtin_amdgcn_s_barrier()
; #define PG8_SCHED __builtin_amdgcn_sched_barrier(0)
; template <class Epi, class Sched>
; __device__ __forceinline__ void gemm_phase(PG8_LAS unsigned char* lds, const Gemm g, const Sched& S, const Epi& E) {
;     ...
;             PG8_WAIT_L(8); PG8_BAR; PG8_WAIT_L(0); PG8_MMA(0, 0, At, B0); PG8_BAR; PG8_SCHED;
;             PG8_LDB(B1, 1, 1); PG8_STAGE(PG8_SB(1, 0), b3, voffB);
;             PG8_BAR; PG8_WAIT_L(0); PG8_MMA(0, 1, At, B1); PG8_BAR;
;             PG8_LDA(At, 1, 1); PG8_STAGE(PG8_SA(1, 0), a3, voffA);
;             PG8_BAR; PG8_WAIT_L(0); PG8_MMA(1, 0, At, B0); PG8_BAR; PG8_SCHED;
;             PG8_STAGE(PG8_SB(1, 1), b3 + hstep, voffB);
;             PG8_WAIT_V(6); PG8_BAR; PG8_MMA(1, 1, At, B1); PG8_BAR;
	s_waitcnt lgkmcnt(0)
	v_mfma_f32_16x16x32_bf16 v[124:127], v[138:141], v[158:161], v[124:127]
	v_mfma_f32_16x16x32_bf16 v[116:119], v[150:153], v[158:161], v[116:119]
	v_mfma_f32_16x16x32_bf16 v[108:111], v[138:141], v[166:169], v[108:111]
	v_mfma_f32_16x16x32_bf16 v[100:103], v[150:153], v[166:169], v[100:103]
	v_mfma_f32_16x16x32_bf16 v[92:95], v[138:141], v[178:181], v[92:95]
	v_mfma_f32_16x16x32_bf16 v[84:87], v[150:153], v[178:181], v[84:87]
	v_mfma_f32_16x16x32_bf16 v[76:79], v[138:141], v[186:189], v[76:79]
	v_mfma_f32_16x16x32_bf16 v[68:71], v[150:153], v[186:189], v[68:71]
	v_mfma_f32_16x16x32_bf16 v[124:127], v[146:149], v[162:165], v[124:127]
	v_mfma_f32_16x16x32_bf16 v[116:119], v[154:157], v[162:165], v[116:119]
	v_mfma_f32_16x16x32_bf16 v[108:111], v[146:149], v[170:173], v[108:111]
	v_mfma_f32_16x16x32_bf16 v[100:103], v[154:157], v[170:173], v[100:103]
	v_mfma_f32_16x16x32_bf16 v[92:95], v[146:149], v[182:185], v[92:95]
	v_mfma_f32_16x16x32_bf16 v[84:87], v[154:157], v[182:185], v[84:87]
	v_mfma_f32_16x16x32_bf16 v[76:79], v[146:149], v[190:193], v[76:79]
	v_mfma_f32_16x16x32_bf16 v[68:71], v[154:157], v[190:193], v[68:71]
	s_barrier
	v_add_u32_e32 v206, 0x1c000, v143
	s_add_i32 m0, s20, 0x18000
	ds_read_b128 v[194:197], v206
	ds_read_b128 v[198:201], v206 offset:1024
	ds_read_b128 v[202:205], v206 offset:2048
	global_load_lds_dwordx4 v176, s[98:99]
	s_add_i32 m0, s20, 0x1a000
	ds_read_b128 v[206:209], v206 offset:3072
	global_load_lds_dwordx4 v128, s[98:99]
	s_barrier
	s_waitcnt lgkmcnt(0)
	v_mfma_f32_16x16x32_bf16 v[120:123], v[194:197], v[158:161], v[120:123]
	v_mfma_f32_16x16x32_bf16 v[112:115], v[202:205], v[158:161], v[112:115]
	v_mfma_f32_16x16x32_bf16 v[104:107], v[194:197], v[166:169], v[104:107]
	v_mfma_f32_16x16x32_bf16 v[96:99], v[202:205], v[166:169], v[96:99]
	v_mfma_f32_16x16x32_bf16 v[88:91], v[194:197], v[178:181], v[88:91]
	v_mfma_f32_16x16x32_bf16 v[80:83], v[202:205], v[178:181], v[80:83]
	v_mfma_f32_16x16x32_bf16 v[72:75], v[194:197], v[186:189], v[72:75]
	v_mfma_f32_16x16x32_bf16 v[64:67], v[202:205], v[186:189], v[64:67]
	v_mfma_f32_16x16x32_bf16 v[120:123], v[198:201], v[162:165], v[120:123]
	v_mfma_f32_16x16x32_bf16 v[112:115], v[206:209], v[162:165], v[112:115]
	v_mfma_f32_16x16x32_bf16 v[104:107], v[198:201], v[170:173], v[104:107]
	v_mfma_f32_16x16x32_bf16 v[96:99], v[206:209], v[170:173], v[96:99]
	v_mfma_f32_16x16x32_bf16 v[88:91], v[198:201], v[182:185], v[88:91]
	v_mfma_f32_16x16x32_bf16 v[80:83], v[206:209], v[182:185], v[80:83]
	v_mfma_f32_16x16x32_bf16 v[72:75], v[198:201], v[190:193], v[72:75]
	v_mfma_f32_16x16x32_bf16 v[64:67], v[206:209], v[190:193], v[64:67]
	s_mov_b32 m0, s28
	s_barrier
	ds_read_b128 v[158:161], v145 offset:49152
	ds_read_b128 v[162:165], v145 offset:50176
	ds_read_b128 v[166:169], v145 offset:51200
	ds_read_b128 v[170:173], v145 offset:52224
	ds_read_b128 v[178:181], v145 offset:53248
	ds_read_b128 v[182:185], v145 offset:54272
	ds_read_b128 v[186:189], v145 offset:55296
	global_load_lds_dwordx4 v132, s[100:101]
	s_mov_b32 m0, s29
	ds_read_b128 v[190:193], v145 offset:56320
	global_load_lds_dwordx4 v130, s[100:101]
	s_barrier
	s_waitcnt lgkmcnt(0)
	v_mfma_f32_16x16x32_bf16 v[60:63], v[138:141], v[158:161], v[60:63]
	v_mfma_f32_16x16x32_bf16 v[52:55], v[150:153], v[158:161], v[52:55]
	v_mfma_f32_16x16x32_bf16 v[44:47], v[138:141], v[166:169], v[44:47]
	v_mfma_f32_16x16x32_bf16 v[36:39], v[150:153], v[166:169], v[36:39]
	v_mfma_f32_16x16x32_bf16 v[28:31], v[138:141], v[178:181], v[28:31]
	v_mfma_f32_16x16x32_bf16 v[20:23], v[150:153], v[178:181], v[20:23]
	v_mfma_f32_16x16x32_bf16 v[12:15], v[138:141], v[186:189], v[12:15]
	v_mfma_f32_16x16x32_bf16 v[4:7], v[150:153], v[186:189], v[4:7]
	v_mfma_f32_16x16x32_bf16 v[60:63], v[146:149], v[162:165], v[60:63]
	v_mfma_f32_16x16x32_bf16 v[52:55], v[154:157], v[162:165], v[52:55]
	v_mfma_f32_16x16x32_bf16 v[44:47], v[146:149], v[170:173], v[44:47]
	v_mfma_f32_16x16x32_bf16 v[36:39], v[154:157], v[170:173], v[36:39]
	v_mfma_f32_16x16x32_bf16 v[28:31], v[146:149], v[182:185], v[28:31]
	v_mfma_f32_16x16x32_bf16 v[20:23], v[154:157], v[182:185], v[20:23]
	v_mfma_f32_16x16x32_bf16 v[12:15], v[146:149], v[190:193], v[12:15]
	v_mfma_f32_16x16x32_bf16 v[4:7], v[154:157], v[190:193], v[4:7]
	s_barrier
	s_add_u32 s14, s14, 0x40080
	s_addc_u32 s15, s15, 0
	s_add_i32 m0, s20, 0x1c000
	s_nop 0
	global_load_lds_dwordx4 v176, s[14:15]
	s_add_i32 m0, s20, 0x1e000
	s_nop 0
	global_load_lds_dwordx4 v128, s[14:15]
	s_waitcnt vmcnt(6)
	s_barrier
	v_mfma_f32_16x16x32_bf16 v[56:59], v[194:197], v[158:161], v[56:59]
	v_mfma_f32_16x16x32_bf16 v[48:51], v[202:205], v[158:161], v[48:51]
	v_mfma_f32_16x16x32_bf16 v[40:43], v[194:197], v[166:169], v[40:43]
	v_mfma_f32_16x16x32_bf16 v[32:35], v[202:205], v[166:169], v[32:35]
	v_mfma_f32_16x16x32_bf16 v[24:27], v[194:197], v[178:181], v[24:27]
	v_mfma_f32_16x16x32_bf16 v[16:19], v[202:205], v[178:181], v[16:19]
	v_mfma_f32_16x16x32_bf16 v[8:11], v[194:197], v[186:189], v[8:11]
	v_mfma_f32_16x16x32_bf16 v[0:3], v[202:205], v[186:189], v[0:3]
	v_mfma_f32_16x16x32_bf16 v[56:59], v[198:201], v[162:165], v[56:59]
	v_mfma_f32_16x16x32_bf16 v[48:51], v[206:209], v[162:165], v[48:51]
	v_mfma_f32_16x16x32_bf16 v[40:43], v[198:201], v[170:173], v[40:43]
	v_mfma_f32_16x16x32_bf16 v[32:35], v[206:209], v[170:173], v[32:35]
	v_mfma_f32_16x16x32_bf16 v[24:27], v[198:201], v[182:185], v[24:27]
	v_mfma_f32_16x16x32_bf16 v[16:19], v[206:209], v[182:185], v[16:19]
	v_mfma_f32_16x16x32_bf16 v[8:11], v[198:201], v[190:193], v[8:11]
	v_mfma_f32_16x16x32_bf16 v[0:3], v[206:209], v[190:193], v[0:3]
	s_add_i32 s45, s45, 2
	s_add_u32 s12, s12, 0x100
	s_addc_u32 s13, s13, 0
	s_add_u32 s43, s43, 0x100
	s_addc_u32 s44, s44, 0
	s_cmp_gt_u32 s45, 13
	s_barrier
; __device__ __forceinline__ unsigned cvtpk(float lo, float hi) { const f32x2 v = (f32x2){lo, hi}; const bf16v2 b = __builtin_convertvector(v, bf16v2); return __builtin_bit_cast(unsigned, b); }
; __device__ __forceinline__ float siluf_(float x) { return x * sigmoidf_(x); }
;     __device__ __forceinline__ void operator()(const f32x4 (&acc)[2][2][4][2], const pg8::Unit& u, int wr, int wc, int fr, int fq) const {
;         const int row0 = u.pm * 256 + wr * 64 + fr, col0 = u.pn * 128 + wc * 32 + 8 * fq;
; #pragma unroll
;         for (int ai = 0; ai < 2; ++ai)
; #pragma unroll
;             for (int m = 0; m < 4; ++m) { bf16_t* rowp = O + (size_t)(row0 + ai * 128 + m * 16) * ldc + col0;
;                 const f32x4 g0 = acc[ai][0][m][0], g1 = acc[ai][0][m][1], u0 = acc[ai][1][m][0], u1 = acc[ai][1][m][1];
;                 u32x4 w; w.x = cvtpk(siluf_(g0[0]) * u0[0], siluf_(g0[1]) * u0[1]); w.y = cvtpk(siluf_(g0[2]) * u0[2], siluf_(g0[3]) * u0[3]);
;                 w.z = cvtpk(siluf_(g1[0]) * u1[0], siluf_(g1[1]) * u1[1]); w.w = cvtpk(siluf_(g1[2]) * u1[2], siluf_(g1[3]) * u1[3]);
;                 *(u32x4*)rowp = w; }
	s_cbranch_scc0 .LBB0_114
	v_mul_f32_e32 v147, 0xbfb8aa3b, v124
	v_exp_f32_e32 v147, v147
	v_readlane_b32 s12, v253, 16
	v_lshl_add_u32 v146, s10, 8, v142
	v_lshl_or_b32 v140, s34, 7, v144
	v_add_f32_e32 v147, 1.0, v147
	v_rcp_f32_e32 v150, v147
	v_mul_f32_e32 v147, 0xbfb8aa3b, v125
	v_exp_f32_e32 v147, v147
	v_readlane_b32 s13, v253, 17
	v_ashrrev_i32_e32 v141, 31, v140
	v_lshlrev_b64 v[140:141], 1, v[140:141]
	v_add_f32_e32 v147, 1.0, v147
	v_rcp_f32_e32 v151, v147
	v_mov_b64_e32 v[138:139], s[12:13]
	v_mad_i64_i32 v[148:149], s[12:13], v146, s81, v[138:139]
	v_pk_mul_f32 v[124:125], v[124:125], v[150:151]
	v_lshl_add_u64 v[148:149], v[148:149], 0, v[140:141]
	v_pk_mul_f32 v[120:121], v[124:125], v[120:121]
	s_and_b64 vcc, exec, s[38:39]
	v_cvt_pk_bf16_f32 v120, v120, v121
	v_mul_f32_e32 v121, 0xbfb8aa3b, v126
	v_exp_f32_e32 v121, v121
	s_mov_b32 s34, s0
	s_mov_b32 s10, s4
	s_mov_b64 s[14:15], s[8:9]
	v_add_f32_e32 v121, 1.0, v121
	v_rcp_f32_e32 v124, v121
	v_mul_f32_e32 v121, 0xbfb8aa3b, v127
	v_exp_f32_e32 v121, v121
	s_nop 0
	v_add_f32_e32 v121, 1.0, v121
	v_rcp_f32_e32 v125, v121
	s_nop 0
	v_pk_mul_f32 v[124:125], v[126:127], v[124:125]
	s_nop 0
	v_pk_mul_f32 v[122:123], v[124:125], v[122:123]
	s_nop 0
	v_cvt_pk_bf16_f32 v121, v122, v123
	v_mul_f32_e32 v122, 0xbfb8aa3b, v116
	v_mul_f32_e32 v123, 0xbfb8aa3b, v117
	v_exp_f32_e32 v122, v122
	v_exp_f32_e32 v123, v123
	v_add_f32_e32 v122, 1.0, v122
	v_add_f32_e32 v123, 1.0, v123
	v_rcp_f32_e32 v122, v122
	v_rcp_f32_e32 v123, v123
	s_nop 0
	v_pk_mul_f32 v[116:117], v[116:117], v[122:123]
	s_nop 0
	v_pk_mul_f32 v[112:113], v[116:117], v[112:113]
	s_nop 0
	v_cvt_pk_bf16_f32 v122, v112, v113
	v_mul_f32_e32 v112, 0xbfb8aa3b, v118
	v_mul_f32_e32 v113, 0xbfb8aa3b, v119
	v_exp_f32_e32 v112, v112
	v_exp_f32_e32 v113, v113
	v_add_f32_e32 v112, 1.0, v112
	v_add_f32_e32 v113, 1.0, v113
	v_rcp_f32_e32 v112, v112
	v_rcp_f32_e32 v113, v113
	s_nop 0
	v_pk_mul_f32 v[112:113], v[118:119], v[112:113]
	s_nop 0
	v_pk_mul_f32 v[112:113], v[112:113], v[114:115]
	v_mul_f32_e32 v114, 0xbfb8aa3b, v108
	v_mul_f32_e32 v115, 0xbfb8aa3b, v109
	v_exp_f32_e32 v114, v114
	v_exp_f32_e32 v115, v115
	v_cvt_pk_bf16_f32 v123, v112, v113
	v_or_b32_e32 v112, 16, v146
	v_add_f32_e32 v114, 1.0, v114
	v_add_f32_e32 v115, 1.0, v115
	v_rcp_f32_e32 v114, v114
	v_rcp_f32_e32 v115, v115
	v_mad_i64_i32 v[112:113], s[12:13], v112, s81, v[138:139]
	v_lshl_add_u64 v[112:113], v[112:113], 0, v[140:141]
	v_pk_mul_f32 v[108:109], v[108:109], v[114:115]
	global_store_dwordx4 v[148:149], v[120:123], off
	v_pk_mul_f32 v[104:105], v[108:109], v[104:105]
	s_nop 0
	v_cvt_pk_bf16_f32 v104, v104, v105
	v_mul_f32_e32 v105, 0xbfb8aa3b, v110
	v_exp_f32_e32 v105, v105
	s_nop 0
	v_add_f32_e32 v105, 1.0, v105
	v_rcp_f32_e32 v108, v105
	v_mul_f32_e32 v105, 0xbfb8aa3b, v111
	v_exp_f32_e32 v105, v105
	s_nop 0
	v_add_f32_e32 v105, 1.0, v105
	v_rcp_f32_e32 v109, v105
	s_nop 0
	v_pk_mul_f32 v[108:109], v[110:111], v[108:109]
	s_nop 0
	v_pk_mul_f32 v[106:107], v[108:109], v[106:107]
	s_nop 0
	v_cvt_pk_bf16_f32 v105, v106, v107
	v_mul_f32_e32 v106, 0xbfb8aa3b, v100
	v_mul_f32_e32 v107, 0xbfb8aa3b, v101
	v_exp_f32_e32 v106, v106
	v_exp_f32_e32 v107, v107
	v_add_f32_e32 v106, 1.0, v106
	v_add_f32_e32 v107, 1.0, v107
	v_rcp_f32_e32 v106, v106
	v_rcp_f32_e32 v107, v107
	s_nop 0
	v_pk_mul_f32 v[100:101], v[100:101], v[106:107]
	s_nop 0
	v_pk_mul_f32 v[96:97], v[100:101], v[96:97]
	s_nop 0
	v_cvt_pk_bf16_f32 v106, v96, v97
	v_mul_f32_e32 v96, 0xbfb8aa3b, v102
	v_mul_f32_e32 v97, 0xbfb8aa3b, v103
	v_exp_f32_e32 v96, v96
	v_exp_f32_e32 v97, v97
	v_add_f32_e32 v96, 1.0, v96
	v_add_f32_e32 v97, 1.0, v97
	v_rcp_f32_e32 v96, v96
	v_rcp_f32_e32 v97, v97
	s_nop 0
	v_pk_mul_f32 v[96:97], v[102:103], v[96:97]
	s_nop 0
	v_pk_mul_f32 v[96:97], v[96:97], v[98:99]
	v_mul_f32_e32 v98, 0xbfb8aa3b, v92
	v_mul_f32_e32 v99, 0xbfb8aa3b, v93
	v_exp_f32_e32 v98, v98
	v_exp_f32_e32 v99, v99
	v_cvt_pk_bf16_f32 v107, v96, v97
	v_or_b32_e32 v96, 32, v146
	v_add_f32_e32 v98, 1.0, v98
	v_add_f32_e32 v99, 1.0, v99
	v_rcp_f32_e32 v98, v98
	v_rcp_f32_e32 v99, v99
	v_mad_i64_i32 v[96:97], s[12:13], v96, s81, v[138:139]
	v_lshl_add_u64 v[96:97], v[96:97], 0, v[140:141]
	v_pk_mul_f32 v[92:93], v[92:93], v[98:99]
	global_store_dwordx4 v[112:113], v[104:107], off
	v_pk_mul_f32 v[88:89], v[92:93], v[88:89]
	s_nop 0
	v_cvt_pk_bf16_f32 v88, v88, v89
	v_mul_f32_e32 v89, 0xbfb8aa3b, v94
	v_exp_f32_e32 v89, v89
	s_nop 0
	v_add_f32_e32 v89, 1.0, v89
	v_rcp_f32_e32 v92, v89
	v_mul_f32_e32 v89, 0xbfb8aa3b, v95
	v_exp_f32_e32 v89, v89
	s_nop 0
	v_add_f32_e32 v89, 1.0, v89
	v_rcp_f32_e32 v93, v89
	s_nop 0
	v_pk_mul_f32 v[92:93], v[94:95], v[92:93]
	s_nop 0
	v_pk_mul_f32 v[90:91], v[92:93], v[90:91]
	s_nop 0
	v_cvt_pk_bf16_f32 v89, v90, v91
	v_mul_f32_e32 v90, 0xbfb8aa3b, v84
	v_mul_f32_e32 v91, 0xbfb8aa3b, v85
	v_exp_f32_e32 v90, v90
	v_exp_f32_e32 v91, v91
	v_add_f32_e32 v90, 1.0, v90
	v_add_f32_e32 v91, 1.0, v91
	v_rcp_f32_e32 v90, v90
	v_rcp_f32_e32 v91, v91
	s_nop 0
	v_pk_mul_f32 v[84:85], v[84:85], v[90:91]
	s_nop 0
	v_pk_mul_f32 v[80:81], v[84:85], v[80:81]
	s_nop 0
	v_cvt_pk_bf16_f32 v90, v80, v81
	v_mul_f32_e32 v80, 0xbfb8aa3b, v86
	v_mul_f32_e32 v81, 0xbfb8aa3b, v87
	v_exp_f32_e32 v80, v80
	v_exp_f32_e32 v81, v81
	v_add_f32_e32 v80, 1.0, v80
	v_add_f32_e32 v81, 1.0, v81
	v_rcp_f32_e32 v80, v80
	v_rcp_f32_e32 v81, v81
	s_nop 0
	v_pk_mul_f32 v[80:81], v[86:87], v[80:81]
	s_nop 0
	v_pk_mul_f32 v[80:81], v[80:81], v[82:83]
	v_mul_f32_e32 v82, 0xbfb8aa3b, v76
	v_mul_f32_e32 v83, 0xbfb8aa3b, v77
	v_exp_f32_e32 v82, v82
	v_exp_f32_e32 v83, v83
	v_cvt_pk_bf16_f32 v91, v80, v81
	v_or_b32_e32 v80, 48, v146
; __device__ __forceinline__ unsigned cvtpk(float lo, float hi) { const f32x2 v = (f32x2){lo, hi}; const bf16v2 b = __builtin_convertvector(v, bf16v2); return __builtin_bit_cast(unsigned, b); }
; __device__ __forceinline__ float siluf_(float x) { return x * sigmoidf_(x); }
;     __device__ __forceinline__ void operator()(const f32x4 (&acc)[2][2][4][2], const pg8::Unit& u, int wr, int wc, int fr, int fq) const {
;     ...
;             for (int m = 0; m < 4; ++m) { bf16_t* rowp = O + (size_t)(row0 + ai * 128 + m * 16) * ldc + col0;
;                 const f32x4 g0 = acc[ai][0][m][0], g1 = acc[ai][0][m][1], u0 = acc[ai][1][m][0], u1 = acc[ai][1][m][1];
;                 u32x4 w; w.x = cvtpk(siluf_(g0[0]) * u0[0], siluf_(g0[1]) * u0[1]); w.y = cvtpk(siluf_(g0[2]) * u0[2], siluf_(g0[3]) * u0[3]);
;                 w.z = cvtpk(siluf_(g1[0]) * u1[0], siluf_(g1[1]) * u1[1]); w.w = cvtpk(siluf_(g1[2]) * u1[2], siluf_(g1[3]) * u1[3]);
;                 *(u32x4*)rowp = w; }
	v_add_f32_e32 v82, 1.0, v82
	v_add_f32_e32 v83, 1.0, v83
	v_rcp_f32_e32 v82, v82
	v_rcp_f32_e32 v83, v83
	v_mad_i64_i32 v[80:81], s[12:13], v80, s81, v[138:139]
	v_lshl_add_u64 v[80:81], v[80:81], 0, v[140:141]
	v_pk_mul_f32 v[76:77], v[76:77], v[82:83]
	global_store_dwordx4 v[96:97], v[88:91], off
	v_pk_mul_f32 v[72:73], v[76:77], v[72:73]
	s_nop 0
	v_cvt_pk_bf16_f32 v72, v72, v73
	v_mul_f32_e32 v73, 0xbfb8aa3b, v78
	v_exp_f32_e32 v73, v73
	s_nop 0
	v_add_f32_e32 v73, 1.0, v73
	v_rcp_f32_e32 v76, v73
	v_mul_f32_e32 v73, 0xbfb8aa3b, v79
	v_exp_f32_e32 v73, v73
	s_nop 0
	v_add_f32_e32 v73, 1.0, v73
	v_rcp_f32_e32 v77, v73
	s_nop 0
	v_pk_mul_f32 v[76:77], v[78:79], v[76:77]
	s_nop 0
	v_pk_mul_f32 v[74:75], v[76:77], v[74:75]
	s_nop 0
	v_cvt_pk_bf16_f32 v73, v74, v75
	v_mul_f32_e32 v74, 0xbfb8aa3b, v68
	v_mul_f32_e32 v75, 0xbfb8aa3b, v69
	v_exp_f32_e32 v74, v74
	v_exp_f32_e32 v75, v75
	v_add_f32_e32 v74, 1.0, v74
	v_add_f32_e32 v75, 1.0, v75
	v_rcp_f32_e32 v74, v74
	v_rcp_f32_e32 v75, v75
	s_nop 0
	v_pk_mul_f32 v[68:69], v[68:69], v[74:75]
	s_nop 0
	v_pk_mul_f32 v[64:65], v[68:69], v[64:65]
	s_nop 0
	v_cvt_pk_bf16_f32 v74, v64, v65
	v_mul_f32_e32 v64, 0xbfb8aa3b, v70
	v_mul_f32_e32 v65, 0xbfb8aa3b, v71
	v_exp_f32_e32 v64, v64
	v_exp_f32_e32 v65, v65
	v_add_f32_e32 v64, 1.0, v64
	v_add_f32_e32 v65, 1.0, v65
	v_rcp_f32_e32 v64, v64
	v_rcp_f32_e32 v65, v65
	s_nop 0
	v_pk_mul_f32 v[64:65], v[70:71], v[64:65]
	s_nop 0
	v_pk_mul_f32 v[64:65], v[64:65], v[66:67]
	v_mul_f32_e32 v66, 0xbfb8aa3b, v60
	v_mul_f32_e32 v67, 0xbfb8aa3b, v61
	v_exp_f32_e32 v66, v66
	v_exp_f32_e32 v67, v67
	v_cvt_pk_bf16_f32 v75, v64, v65
	v_add_u32_e32 v64, 0x80, v146
	v_add_f32_e32 v66, 1.0, v66
	v_add_f32_e32 v67, 1.0, v67
	v_rcp_f32_e32 v66, v66
	v_rcp_f32_e32 v67, v67
	v_mad_i64_i32 v[64:65], s[12:13], v64, s81, v[138:139]
	v_lshl_add_u64 v[64:65], v[64:65], 0, v[140:141]
	v_pk_mul_f32 v[60:61], v[60:61], v[66:67]
	global_store_dwordx4 v[80:81], v[72:75], off
	v_pk_mul_f32 v[56:57], v[60:61], v[56:57]
	s_nop 0
	v_cvt_pk_bf16_f32 v56, v56, v57
	v_mul_f32_e32 v57, 0xbfb8aa3b, v62
	v_exp_f32_e32 v57, v57
	s_nop 0
	v_add_f32_e32 v57, 1.0, v57
	v_rcp_f32_e32 v60, v57
	v_mul_f32_e32 v57, 0xbfb8aa3b, v63
	v_exp_f32_e32 v57, v57
	s_nop 0
	v_add_f32_e32 v57, 1.0, v57
	v_rcp_f32_e32 v61, v57
	s_nop 0
	v_pk_mul_f32 v[60:61], v[62:63], v[60:61]
	s_nop 0
	v_pk_mul_f32 v[58:59], v[60:61], v[58:59]
	s_nop 0
	v_cvt_pk_bf16_f32 v57, v58, v59
	v_mul_f32_e32 v58, 0xbfb8aa3b, v52
	v_mul_f32_e32 v59, 0xbfb8aa3b, v53
	v_exp_f32_e32 v58, v58
	v_exp_f32_e32 v59, v59
	v_add_f32_e32 v58, 1.0, v58
	v_add_f32_e32 v59, 1.0, v59
	v_rcp_f32_e32 v58, v58
	v_rcp_f32_e32 v59, v59
	s_nop 0
	v_pk_mul_f32 v[52:53], v[52:53], v[58:59]
	s_nop 0
	v_pk_mul_f32 v[48:49], v[52:53], v[48:49]
	s_nop 0
	v_cvt_pk_bf16_f32 v58, v48, v49
	v_mul_f32_e32 v48, 0xbfb8aa3b, v54
	v_mul_f32_e32 v49, 0xbfb8aa3b, v55
	v_exp_f32_e32 v48, v48
	v_exp_f32_e32 v49, v49
	v_add_f32_e32 v48, 1.0, v48
	v_add_f32_e32 v49, 1.0, v49
	v_rcp_f32_e32 v48, v48
	v_rcp_f32_e32 v49, v49
	s_nop 0
	v_pk_mul_f32 v[48:49], v[54:55], v[48:49]
	s_nop 0
	v_pk_mul_f32 v[48:49], v[48:49], v[50:51]
	v_mul_f32_e32 v50, 0xbfb8aa3b, v44
	v_mul_f32_e32 v51, 0xbfb8aa3b, v45
	v_exp_f32_e32 v50, v50
	v_exp_f32_e32 v51, v51
	v_cvt_pk_bf16_f32 v59, v48, v49
	v_add_u32_e32 v48, 0x90, v146
	v_add_f32_e32 v50, 1.0, v50
	v_add_f32_e32 v51, 1.0, v51
	v_rcp_f32_e32 v50, v50
	v_rcp_f32_e32 v51, v51
	v_mad_i64_i32 v[48:49], s[12:13], v48, s81, v[138:139]
	v_lshl_add_u64 v[48:49], v[48:49], 0, v[140:141]
	v_pk_mul_f32 v[44:45], v[44:45], v[50:51]
	global_store_dwordx4 v[64:65], v[56:59], off
	v_pk_mul_f32 v[40:41], v[44:45], v[40:41]
	s_nop 0
	v_cvt_pk_bf16_f32 v40, v40, v41
	v_mul_f32_e32 v41, 0xbfb8aa3b, v46
	v_exp_f32_e32 v41, v41
	s_nop 0
	v_add_f32_e32 v41, 1.0, v41
	v_rcp_f32_e32 v44, v41
	v_mul_f32_e32 v41, 0xbfb8aa3b, v47
	v_exp_f32_e32 v41, v41
	s_nop 0
	v_add_f32_e32 v41, 1.0, v41
	v_rcp_f32_e32 v45, v41
	s_nop 0
	v_pk_mul_f32 v[44:45], v[46:47], v[44:45]
	s_nop 0
	v_pk_mul_f32 v[42:43], v[44:45], v[42:43]
	s_nop 0
	v_cvt_pk_bf16_f32 v41, v42, v43
	v_mul_f32_e32 v42, 0xbfb8aa3b, v36
	v_mul_f32_e32 v43, 0xbfb8aa3b, v37
; __device__ __forceinline__ unsigned cvtpk(float lo, float hi) { const f32x2 v = (f32x2){lo, hi}; const bf16v2 b = __builtin_convertvector(v, bf16v2); return __builtin_bit_cast(unsigned, b); }
; __device__ __forceinline__ float siluf_(float x) { return x * sigmoidf_(x); }
; #define PG8_WAIT_V(n) asm volatile("s_waitcnt vmcnt(" #n ")" ::: "memory")
; #define PG8_BAR __builtin_amdgcn_s_barrier()
; template <class Epi, class Sched>
; __device__ __forceinline__ void gemm_phase(PG8_LAS unsigned char* lds, const Gemm g, const Sched& S, const Epi& E) {
;     ...
;         if (!has_next) break;
; #pragma unroll
;         for (int a = 0; a < 2; ++a)
; #pragma unroll
;             for (int b = 0; b < 2; ++b)
; #pragma unroll
;                 for (int m = 0; m < 4; ++m)
; #pragma unroll
;                     for (int n = 0; n < 2; ++n) acc[a][b][m][n] = (f32x4){0.f, 0.f, 0.f, 0.f};
;         cur = nxt; cA = nA; cB = nB; ++ui;
;     }
;     PG8_WAIT_V(0);
;     if (wr == 0) PG8_BAR;
;     PG8_BAR;
;     __device__ __forceinline__ void operator()(const f32x4 (&acc)[2][2][4][2], const pg8::Unit& u, int wr, int wc, int fr, int fq) const {
;     ...
;             for (int m = 0; m < 4; ++m) { bf16_t* rowp = O + (size_t)(row0 + ai * 128 + m * 16) * ldc + col0;
;                 const f32x4 g0 = acc[ai][0][m][0], g1 = acc[ai][0][m][1], u0 = acc[ai][1][m][0], u1 = acc[ai][1][m][1];
;                 u32x4 w; w.x = cvtpk(siluf_(g0[0]) * u0[0], siluf_(g0[1]) * u0[1]); w.y = cvtpk(siluf_(g0[2]) * u0[2], siluf_(g0[3]) * u0[3]);
;                 w.z = cvtpk(siluf_(g1[0]) * u1[0], siluf_(g1[1]) * u1[1]); w.w = cvtpk(siluf_(g1[2]) * u1[2], siluf_(g1[3]) * u1[3]);
;                 *(u32x4*)rowp = w; }
	v_exp_f32_e32 v42, v42
	v_exp_f32_e32 v43, v43
	v_add_f32_e32 v42, 1.0, v42
	v_add_f32_e32 v43, 1.0, v43
	v_rcp_f32_e32 v42, v42
	v_rcp_f32_e32 v43, v43
	s_nop 0
	v_pk_mul_f32 v[36:37], v[36:37], v[42:43]
	s_nop 0
	v_pk_mul_f32 v[32:33], v[36:37], v[32:33]
	s_nop 0
	v_cvt_pk_bf16_f32 v42, v32, v33
	v_mul_f32_e32 v32, 0xbfb8aa3b, v38
	v_mul_f32_e32 v33, 0xbfb8aa3b, v39
	v_exp_f32_e32 v32, v32
	v_exp_f32_e32 v33, v33
	v_add_f32_e32 v32, 1.0, v32
	v_add_f32_e32 v33, 1.0, v33
	v_rcp_f32_e32 v32, v32
	v_rcp_f32_e32 v33, v33
	s_nop 0
	v_pk_mul_f32 v[32:33], v[38:39], v[32:33]
	s_nop 0
	v_pk_mul_f32 v[32:33], v[32:33], v[34:35]
	v_mul_f32_e32 v34, 0xbfb8aa3b, v28
	v_mul_f32_e32 v35, 0xbfb8aa3b, v29
	v_exp_f32_e32 v34, v34
	v_exp_f32_e32 v35, v35
	v_cvt_pk_bf16_f32 v43, v32, v33
	v_add_u32_e32 v32, 0xa0, v146
	v_add_f32_e32 v34, 1.0, v34
	v_add_f32_e32 v35, 1.0, v35
	v_rcp_f32_e32 v34, v34
	v_rcp_f32_e32 v35, v35
	v_mad_i64_i32 v[32:33], s[12:13], v32, s81, v[138:139]
	v_lshl_add_u64 v[32:33], v[32:33], 0, v[140:141]
	v_pk_mul_f32 v[28:29], v[28:29], v[34:35]
	global_store_dwordx4 v[48:49], v[40:43], off
	v_pk_mul_f32 v[24:25], v[28:29], v[24:25]
	s_nop 0
	v_cvt_pk_bf16_f32 v24, v24, v25
	v_mul_f32_e32 v25, 0xbfb8aa3b, v30
	v_exp_f32_e32 v25, v25
	s_nop 0
	v_add_f32_e32 v25, 1.0, v25
	v_rcp_f32_e32 v28, v25
	v_mul_f32_e32 v25, 0xbfb8aa3b, v31
	v_exp_f32_e32 v25, v25
	s_nop 0
	v_add_f32_e32 v25, 1.0, v25
	v_rcp_f32_e32 v29, v25
	s_nop 0
	v_pk_mul_f32 v[28:29], v[30:31], v[28:29]
	s_nop 0
	v_pk_mul_f32 v[26:27], v[28:29], v[26:27]
	s_nop 0
	v_cvt_pk_bf16_f32 v25, v26, v27
	v_mul_f32_e32 v26, 0xbfb8aa3b, v20
	v_mul_f32_e32 v27, 0xbfb8aa3b, v21
	v_exp_f32_e32 v26, v26
	v_exp_f32_e32 v27, v27
	v_add_f32_e32 v26, 1.0, v26
	v_add_f32_e32 v27, 1.0, v27
	v_rcp_f32_e32 v26, v26
	v_rcp_f32_e32 v27, v27
	s_nop 0
	v_pk_mul_f32 v[20:21], v[20:21], v[26:27]
	s_nop 0
	v_pk_mul_f32 v[16:17], v[20:21], v[16:17]
	s_nop 0
	v_cvt_pk_bf16_f32 v26, v16, v17
	v_mul_f32_e32 v16, 0xbfb8aa3b, v22
	v_mul_f32_e32 v17, 0xbfb8aa3b, v23
	v_exp_f32_e32 v16, v16
	v_exp_f32_e32 v17, v17
	v_add_f32_e32 v16, 1.0, v16
	v_add_f32_e32 v17, 1.0, v17
	v_rcp_f32_e32 v16, v16
	v_rcp_f32_e32 v17, v17
	s_nop 0
	v_pk_mul_f32 v[16:17], v[22:23], v[16:17]
	s_nop 0
	v_pk_mul_f32 v[16:17], v[16:17], v[18:19]
	v_mul_f32_e32 v18, 0xbfb8aa3b, v12
	v_mul_f32_e32 v19, 0xbfb8aa3b, v13
	v_exp_f32_e32 v18, v18
	v_exp_f32_e32 v19, v19
	v_cvt_pk_bf16_f32 v27, v16, v17
	v_add_u32_e32 v16, 0xb0, v146
	v_add_f32_e32 v18, 1.0, v18
	v_add_f32_e32 v19, 1.0, v19
	v_rcp_f32_e32 v18, v18
	v_rcp_f32_e32 v19, v19
	v_mad_i64_i32 v[16:17], s[12:13], v16, s81, v[138:139]
	v_lshl_add_u64 v[16:17], v[16:17], 0, v[140:141]
	v_pk_mul_f32 v[12:13], v[12:13], v[18:19]
	s_mov_b64 s[12:13], s[6:7]
	v_pk_mul_f32 v[8:9], v[12:13], v[8:9]
	global_store_dwordx4 v[32:33], v[24:27], off
	v_cvt_pk_bf16_f32 v8, v8, v9
	v_mul_f32_e32 v9, 0xbfb8aa3b, v14
	v_exp_f32_e32 v9, v9
	s_nop 0
	v_add_f32_e32 v9, 1.0, v9
	v_rcp_f32_e32 v12, v9
	v_mul_f32_e32 v9, 0xbfb8aa3b, v15
	v_exp_f32_e32 v9, v9
	s_nop 0
	v_add_f32_e32 v9, 1.0, v9
	v_rcp_f32_e32 v13, v9
	s_nop 0
	v_pk_mul_f32 v[12:13], v[14:15], v[12:13]
	s_nop 0
	v_pk_mul_f32 v[10:11], v[12:13], v[10:11]
	s_nop 0
	v_cvt_pk_bf16_f32 v9, v10, v11
	v_mul_f32_e32 v10, 0xbfb8aa3b, v4
	v_mul_f32_e32 v11, 0xbfb8aa3b, v5
	v_exp_f32_e32 v10, v10
	v_exp_f32_e32 v11, v11
	v_add_f32_e32 v10, 1.0, v10
	v_add_f32_e32 v11, 1.0, v11
	v_rcp_f32_e32 v10, v10
	v_rcp_f32_e32 v11, v11
	s_nop 0
	v_pk_mul_f32 v[4:5], v[4:5], v[10:11]
	s_nop 0
	v_pk_mul_f32 v[0:1], v[4:5], v[0:1]
	s_nop 0
	v_cvt_pk_bf16_f32 v10, v0, v1
	v_mul_f32_e32 v0, 0xbfb8aa3b, v6
	v_mul_f32_e32 v1, 0xbfb8aa3b, v7
	v_exp_f32_e32 v0, v0
	v_exp_f32_e32 v1, v1
	v_add_f32_e32 v0, 1.0, v0
	v_add_f32_e32 v1, 1.0, v1
	v_rcp_f32_e32 v0, v0
	v_rcp_f32_e32 v1, v1
	s_nop 0
	v_pk_mul_f32 v[0:1], v[6:7], v[0:1]
	s_nop 0
	v_pk_mul_f32 v[0:1], v[0:1], v[2:3]
	s_nop 0
	v_cvt_pk_bf16_f32 v11, v0, v1
	global_store_dwordx4 v[16:17], v[8:11], off
	s_cbranch_vccz .LBB0_111
	s_waitcnt vmcnt(0)
	v_readlane_b32 s22, v255, 14
	s_cmpk_gt_u32 s19, 0xff
	v_readlane_b32 s23, v255, 15
	s_mov_b64 s[28:29], s[54:55]
	s_cbranch_scc1 .LBB0_118
	s_barrier

; #define PG8_STAGE(bufoff, gbase, voff) do { _Pragma("unroll") for (int _i = 0; _i < 2; ++_i) \
;         __builtin_amdgcn_global_load_lds((const unsigned*)((const char*)(gbase) + (voff)[_i]), (PG8_LAS unsigned*)(lds + (bufoff) + ldsw + _i * 8192), 16, 0, 0); } while (0)
; #define PG8_LDA(dst, b, h) do { _Pragma("unroll") for (int m = 0; m < 4; ++m) _Pragma("unroll") for (int k = 0; k < 2; ++k) dst[m][k] = *(const PG8_LAS bf16x8*)(lds + PG8_SA(b, h) + aoff + m * 2048 + k * 1024); } while (0)
; #define PG8_LDB(dst, b, h) do { _Pragma("unroll") for (int n = 0; n < 2; ++n) _Pragma("unroll") for (int k = 0; k < 2; ++k) dst[n][k] = *(const PG8_LAS bf16x8*)(lds + PG8_SB(b, h) + boff + n * 2048 + k * 1024); } while (0)
; #define PG8_WAIT_L(n) asm volatile("s_waitcnt lgkmcnt(" #n ")" ::: "memory")
; #define PG8_BAR __builtin_amdgcn_s_barrier()
; #define PG8_SCHED __builtin_amdgcn_sched_barrier(0)
; template <class Epi, class Sched>
; __device__ __forceinline__ void gemm_phase(PG8_LAS unsigned char* lds, const Gemm g, const Sched& S, const Epi& E) {
;     ...
;         const bool has_next = S.next(ui + 1, nxt);
;         const char* nA = has_next ? (const char*)g.A + (size_t)nxt.pm * tstep : cA; const char* nB = has_next ? (const char*)g.Bt + (size_t)nxt.pn * tstep : cB;
;         for (int t = 0; t < nt; t += 2) {
;             const bool last = (t == nt - 2);
;             const char* a1 = cA + (size_t)(t + 1) * kstep;
;             const char* a2 = last ? nA : cA + (size_t)(t + 2) * kstep; const char* b2 = last ? nB : cB + (size_t)(t + 2) * kstep;
;             const char* a3 = a2 + kstep; const char* b3 = b2 + kstep;
;             if (last && has_next) S.a_ready(nxt);
;             PG8_LDB(B0, 0, 0); PG8_SCHED; PG8_LDA(At, 0, 0); PG8_STAGE(PG8_SA(1, 1), a1 + hstep, voffA);
;             PG8_WAIT_L(8); PG8_BAR; PG8_WAIT_L(0); PG8_MMA(0, 0, At, B0); PG8_BAR; PG8_SCHED;
;     ...
; #pragma unroll
;         for (int a = 0; a < 2; ++a)
; #pragma unroll
;             for (int b = 0; b < 2; ++b)
; #pragma unroll
;                 for (int m = 0; m < 4; ++m)
; #pragma unroll
;                     for (int n = 0; n < 2; ++n) acc[a][b][m][n] = (f32x4){0.f, 0.f, 0.f, 0.f};
;         cur = nxt; cA = nA; cB = nB; ++ui;
.LBB0_136:
	v_mov_b64_e32 v[0:1], 0x100
	s_ashr_i32 s7, s6, 31
	v_cmp_lt_i64_e32 vcc, s[8:9], v[0:1]
	s_lshl_b64 s[8:9], s[6:7], 19
	s_add_u32 s8, s94, s8
	s_addc_u32 s9, s95, s9
	s_and_b64 s[10:11], vcc, exec
	s_cselect_b32 s7, s9, s13
	s_cselect_b32 s40, s8, s12
	s_ashr_i32 s5, s4, 31
	s_lshl_b64 s[10:11], s[4:5], 19
	v_readlane_b32 s16, v253, 10
	v_readlane_b32 s17, v253, 11
	s_add_u32 s10, s16, s10
	s_addc_u32 s11, s17, s11
	s_and_b64 s[16:17], vcc, exec
	s_cselect_b32 s5, s11, s15
	s_cselect_b32 s41, s10, s14
	s_add_u32 s12, s12, 0x40080
	s_addc_u32 s13, s13, 0
	s_add_u32 s43, s14, 0x100
	v_mov_b32_e32 v0, 0
	s_addc_u32 s44, s15, 0
	s_mov_b32 s45, -2
	v_mov_b32_e32 v1, v0
	v_mov_b32_e32 v2, v0
	v_mov_b32_e32 v3, v0
	v_mov_b32_e32 v4, v0
	v_mov_b32_e32 v5, v0
	v_mov_b32_e32 v6, v0
	v_mov_b32_e32 v7, v0
	v_mov_b32_e32 v8, v0
	v_mov_b32_e32 v9, v0
	v_mov_b32_e32 v10, v0
	v_mov_b32_e32 v11, v0
	v_mov_b32_e32 v12, v0
	v_mov_b32_e32 v13, v0
	v_mov_b32_e32 v14, v0
	v_mov_b32_e32 v15, v0
	v_mov_b32_e32 v24, v0
	v_mov_b32_e32 v25, v0
	v_mov_b32_e32 v26, v0
	v_mov_b32_e32 v27, v0
	v_mov_b32_e32 v28, v0
	v_mov_b32_e32 v29, v0
	v_mov_b32_e32 v30, v0
	v_mov_b32_e32 v31, v0
	v_mov_b32_e32 v40, v0
	v_mov_b32_e32 v41, v0
	v_mov_b32_e32 v42, v0
	v_mov_b32_e32 v43, v0
	v_mov_b32_e32 v44, v0
	v_mov_b32_e32 v45, v0
	v_mov_b32_e32 v46, v0
	v_mov_b32_e32 v47, v0
	v_mov_b32_e32 v16, v0
	v_mov_b32_e32 v17, v0
	v_mov_b32_e32 v18, v0
	v_mov_b32_e32 v19, v0
	v_mov_b32_e32 v20, v0
	v_mov_b32_e32 v21, v0
	v_mov_b32_e32 v22, v0
	v_mov_b32_e32 v23, v0
	v_mov_b32_e32 v32, v0
	v_mov_b32_e32 v33, v0
	v_mov_b32_e32 v34, v0
	v_mov_b32_e32 v35, v0
	v_mov_b32_e32 v36, v0
	v_mov_b32_e32 v37, v0
	v_mov_b32_e32 v38, v0
	v_mov_b32_e32 v39, v0
	v_mov_b32_e32 v48, v0
	v_mov_b32_e32 v49, v0
	v_mov_b32_e32 v50, v0
	v_mov_b32_e32 v51, v0
	v_mov_b32_e32 v52, v0
	v_mov_b32_e32 v53, v0
	v_mov_b32_e32 v54, v0
	v_mov_b32_e32 v55, v0
	v_mov_b32_e32 v56, v0
	v_mov_b32_e32 v57, v0
	v_mov_b32_e32 v58, v0
	v_mov_b32_e32 v59, v0
	v_mov_b32_e32 v60, v0
	v_mov_b32_e32 v61, v0
	v_mov_b32_e32 v62, v0
	v_mov_b32_e32 v63, v0
	v_mov_b32_e32 v64, v0
	v_mov_b32_e32 v65, v0
	v_mov_b32_e32 v66, v0
	v_mov_b32_e32 v67, v0
	v_mov_b32_e32 v68, v0
	v_mov_b32_e32 v69, v0
	v_mov_b32_e32 v70, v0
	v_mov_b32_e32 v71, v0
	v_mov_b32_e32 v72, v0
	v_mov_b32_e32 v73, v0
	v_mov_b32_e32 v74, v0
	v_mov_b32_e32 v75, v0
	v_mov_b32_e32 v76, v0
	v_mov_b32_e32 v77, v0
	v_mov_b32_e32 v78, v0
	v_mov_b32_e32 v79, v0
	v_mov_b32_e32 v88, v0
	v_mov_b32_e32 v89, v0
	v_mov_b32_e32 v90, v0
	v_mov_b32_e32 v91, v0
	v_mov_b32_e32 v92, v0
	v_mov_b32_e32 v93, v0
	v_mov_b32_e32 v94, v0
	v_mov_b32_e32 v95, v0
	v_mov_b32_e32 v104, v0
	v_mov_b32_e32 v105, v0
	v_mov_b32_e32 v106, v0
	v_mov_b32_e32 v107, v0
	v_mov_b32_e32 v108, v0
	v_mov_b32_e32 v109, v0
	v_mov_b32_e32 v110, v0
	v_mov_b32_e32 v111, v0
	v_mov_b32_e32 v80, v0
	v_mov_b32_e32 v81, v0
	v_mov_b32_e32 v82, v0
	v_mov_b32_e32 v83, v0
	v_mov_b32_e32 v84, v0
	v_mov_b32_e32 v85, v0
	v_mov_b32_e32 v86, v0
	v_mov_b32_e32 v87, v0
	v_mov_b32_e32 v96, v0
	v_mov_b32_e32 v97, v0
	v_mov_b32_e32 v98, v0
	v_mov_b32_e32 v99, v0
	v_mov_b32_e32 v100, v0
	v_mov_b32_e32 v101, v0
	v_mov_b32_e32 v102, v0
	v_mov_b32_e32 v103, v0
	v_mov_b32_e32 v112, v0
	v_mov_b32_e32 v113, v0
	v_mov_b32_e32 v114, v0
	v_mov_b32_e32 v115, v0
	v_mov_b32_e32 v116, v0
	v_mov_b32_e32 v117, v0
	v_mov_b32_e32 v118, v0
	v_mov_b32_e32 v119, v0
	v_mov_b32_e32 v120, v0
	v_mov_b32_e32 v121, v0
	v_mov_b32_e32 v122, v0
	v_mov_b32_e32 v123, v0
	v_mov_b32_e32 v124, v0
	v_mov_b32_e32 v125, v0
	v_mov_b32_e32 v126, v0
	v_mov_b32_e32 v127, v0
	v_readfirstlane_b32 s98, v245
	s_nop 3
	s_cmpk_lt_u32 s98, 0x100
	s_cbranch_scc1 .Lprio_skip2
	s_setprio 1
.Lprio_skip2:
.LBB0_137:
	s_add_u32 s14, s12, 0xfffc0080
	s_addc_u32 s15, s13, -1
	v_add_u32_e32 v154, 0x10000, v139
	ds_read_b128 v[142:145], v154
	ds_read_b128 v[146:149], v154 offset:1024
	ds_read_b128 v[150:153], v154 offset:2048
	ds_read_b128 v[154:157], v154 offset:3072
	s_cmp_eq_u32 s45, 12
	s_cselect_b32 s17, s7, s15
	s_cselect_b32 s16, s40, s14
	s_cselect_b32 s15, s5, s44
	s_cselect_b32 s14, s41, s43
	s_add_i32 m0, s1, 0xc000
	ds_read_b128 v[158:161], v141
	ds_read_b128 v[162:165], v141 offset:1024
	ds_read_b128 v[166:169], v141 offset:2048
	ds_read_b128 v[170:173], v141 offset:3072
	ds_read_b128 v[178:181], v141 offset:4096
	ds_read_b128 v[182:185], v141 offset:5120
	ds_read_b128 v[186:189], v141 offset:6144
	global_load_lds_dwordx4 v134, s[12:13]
	s_add_i32 m0, s1, 0xe000
	ds_read_b128 v[190:193], v141 offset:7168
	global_load_lds_dwordx4 v136, s[12:13]
	s_waitcnt lgkmcnt(8)
	s_barrier
	s_waitcnt lgkmcnt(0)
	v_mfma_f32_16x16x32_bf16 v[124:127], v[142:145], v[158:161], v[124:127]
	v_mfma_f32_16x16x32_bf16 v[120:123], v[150:153], v[158:161], v[120:123]
	v_mfma_f32_16x16x32_bf16 v[116:119], v[142:145], v[166:169], v[116:119]
	v_mfma_f32_16x16x32_bf16 v[112:115], v[150:153], v[166:169], v[112:115]
	v_mfma_f32_16x16x32_bf16 v[100:103], v[142:145], v[178:181], v[100:103]
	v_mfma_f32_16x16x32_bf16 v[96:99], v[150:153], v[178:181], v[96:99]
	v_mfma_f32_16x16x32_bf16 v[84:87], v[142:145], v[186:189], v[84:87]
	v_mfma_f32_16x16x32_bf16 v[80:83], v[150:153], v[186:189], v[80:83]
	v_mfma_f32_16x16x32_bf16 v[124:127], v[146:149], v[162:165], v[124:127]
	v_mfma_f32_16x16x32_bf16 v[120:123], v[154:157], v[162:165], v[120:123]
	v_mfma_f32_16x16x32_bf16 v[116:119], v[146:149], v[170:173], v[116:119]
	v_mfma_f32_16x16x32_bf16 v[112:115], v[154:157], v[170:173], v[112:115]
	v_mfma_f32_16x16x32_bf16 v[100:103], v[146:149], v[182:185], v[100:103]
	v_mfma_f32_16x16x32_bf16 v[96:99], v[154:157], v[182:185], v[96:99]
	v_mfma_f32_16x16x32_bf16 v[84:87], v[146:149], v[190:193], v[84:87]
	v_mfma_f32_16x16x32_bf16 v[80:83], v[154:157], v[190:193], v[80:83]
	s_barrier
; #define PG8_STAGE(bufoff, gbase, voff) do { _Pragma("unroll") for (int _i = 0; _i < 2; ++_i) \
;         __builtin_amdgcn_global_load_lds((const unsigned*)((const char*)(gbase) + (voff)[_i]), (PG8_LAS unsigned*)(lds + (bufoff) + ldsw + _i * 8192), 16, 0, 0); } while (0)
; #define PG8_LDA(dst, b, h) do { _Pragma("unroll") for (int m = 0; m < 4; ++m) _Pragma("unroll") for (int k = 0; k < 2; ++k) dst[m][k] = *(const PG8_LAS bf16x8*)(lds + PG8_SA(b, h) + aoff + m * 2048 + k * 1024); } while (0)
; #define PG8_LDB(dst, b, h) do { _Pragma("unroll") for (int n = 0; n < 2; ++n) _Pragma("unroll") for (int k = 0; k < 2; ++k) dst[n][k] = *(const PG8_LAS bf16x8*)(lds + PG8_SB(b, h) + boff + n * 2048 + k * 1024); } while (0)
; #define PG8_MMA(ai, bj, At, Bt) do { __builtin_amdgcn_s_setprio(1); _Pragma("unroll") for (int m = 0; m < 4; ++m) _Pragma("unroll") for (int n = 0; n < 2; ++n) _Pragma("unroll") for (int k = 0; k < 2; ++k) \
;         acc[ai][bj][m][n] = __builtin_amdgcn_mfma_f32_16x16x32_bf16(Bt[n][k], At[m][k], acc[ai][bj][m][n], 0, 0, 0); __builtin_amdgcn_s_setprio(0); } while (0)
; #define PG8_WAIT_V(n) asm volatile("s_waitcnt vmcnt(" #n ")" ::: "memory")
; #define PG8_WAIT_L(n) asm volatile("s_waitcnt lgkmcnt(" #n ")" ::: "memory")
; #define PG8_BAR __builtin_amdgcn_s_barrier()
; #define PG8_SCHED __builtin_amdgcn_sched_barrier(0)
; template <class Epi, class Sched>
; __device__ __forceinline__ void gemm_phase(PG8_LAS unsigned char* lds, const Gemm g, const Sched& S, const Epi& E) {
;     ...
;             PG8_LDB(B1, 0, 1); PG8_STAGE(PG8_SB(0, 0), b2, voffB);
;             PG8_BAR; PG8_WAIT_L(0); PG8_MMA(0, 1, At, B1); PG8_BAR;
;             PG8_LDA(At, 0, 1); PG8_STAGE(PG8_SA(0, 0), a2, voffA);
;             PG8_BAR; PG8_WAIT_L(0); PG8_MMA(1, 0, At, B0); PG8_BAR; PG8_SCHED;
;             PG8_STAGE(PG8_SB(0, 1), b2 + hstep, voffB);
;             PG8_WAIT_V(6); PG8_BAR; PG8_MMA(1, 1, At, B1); PG8_BAR;
;             PG8_LDB(B0, 1, 0); PG8_SCHED; PG8_LDA(At, 1, 0); PG8_STAGE(PG8_SA(0, 1), a2 + hstep, voffA);
	s_add_i32 s48, 0, 0x14000
	v_add_u32_e32 v174, 0x14000, v139
	ds_read_b128 v[194:197], v174
	ds_read_b128 v[198:201], v174 offset:1024
	s_add_u32 s98, s14, 0x80
	s_addc_u32 s99, s15, 0
	s_add_i32 m0, s20, 0x10000
	ds_read_b128 v[202:205], v174 offset:2048
	global_load_lds_dwordx4 v176, s[14:15]
	s_add_i32 m0, s20, 0x12000
	ds_read_b128 v[206:209], v174 offset:3072
	global_load_lds_dwordx4 v128, s[14:15]
	s_barrier
	s_waitcnt lgkmcnt(0)
	v_mfma_f32_16x16x32_bf16 v[108:111], v[194:197], v[158:161], v[108:111]
	v_mfma_f32_16x16x32_bf16 v[104:107], v[202:205], v[158:161], v[104:107]
	v_mfma_f32_16x16x32_bf16 v[92:95], v[194:197], v[166:169], v[92:95]
	v_mfma_f32_16x16x32_bf16 v[88:91], v[202:205], v[166:169], v[88:91]
	v_mfma_f32_16x16x32_bf16 v[76:79], v[194:197], v[178:181], v[76:79]
	v_mfma_f32_16x16x32_bf16 v[72:75], v[202:205], v[178:181], v[72:75]
	v_mfma_f32_16x16x32_bf16 v[68:71], v[194:197], v[186:189], v[68:71]
	v_mfma_f32_16x16x32_bf16 v[64:67], v[202:205], v[186:189], v[64:67]
	v_mfma_f32_16x16x32_bf16 v[108:111], v[198:201], v[162:165], v[108:111]
	v_mfma_f32_16x16x32_bf16 v[104:107], v[206:209], v[162:165], v[104:107]
	v_mfma_f32_16x16x32_bf16 v[92:95], v[198:201], v[170:173], v[92:95]
	v_mfma_f32_16x16x32_bf16 v[88:91], v[206:209], v[170:173], v[88:91]
	v_mfma_f32_16x16x32_bf16 v[76:79], v[198:201], v[182:185], v[76:79]
	v_mfma_f32_16x16x32_bf16 v[72:75], v[206:209], v[182:185], v[72:75]
	v_mfma_f32_16x16x32_bf16 v[68:71], v[198:201], v[190:193], v[68:71]
	v_mfma_f32_16x16x32_bf16 v[64:67], v[206:209], v[190:193], v[64:67]
	s_mov_b32 m0, s1
	s_add_u32 s100, s16, 0x80
	s_addc_u32 s101, s17, 0
	s_barrier
	ds_read_b128 v[158:161], v141 offset:16384
	ds_read_b128 v[162:165], v141 offset:17408
	ds_read_b128 v[166:169], v141 offset:18432
	ds_read_b128 v[170:173], v141 offset:19456
	ds_read_b128 v[178:181], v141 offset:20480
	ds_read_b128 v[182:185], v141 offset:21504
	ds_read_b128 v[186:189], v141 offset:22528
	global_load_lds_dwordx4 v132, s[16:17]
	s_mov_b32 m0, s22
	ds_read_b128 v[190:193], v141 offset:23552
	global_load_lds_dwordx4 v130, s[16:17]
	s_barrier
	s_waitcnt lgkmcnt(0)
	v_mfma_f32_16x16x32_bf16 v[60:63], v[142:145], v[158:161], v[60:63]
	v_mfma_f32_16x16x32_bf16 v[56:59], v[150:153], v[158:161], v[56:59]
	v_mfma_f32_16x16x32_bf16 v[52:55], v[142:145], v[166:169], v[52:55]
	v_mfma_f32_16x16x32_bf16 v[48:51], v[150:153], v[166:169], v[48:51]
	v_mfma_f32_16x16x32_bf16 v[36:39], v[142:145], v[178:181], v[36:39]
	v_mfma_f32_16x16x32_bf16 v[32:35], v[150:153], v[178:181], v[32:35]
	v_mfma_f32_16x16x32_bf16 v[20:23], v[142:145], v[186:189], v[20:23]
	v_mfma_f32_16x16x32_bf16 v[16:19], v[150:153], v[186:189], v[16:19]
	v_mfma_f32_16x16x32_bf16 v[60:63], v[146:149], v[162:165], v[60:63]
	v_mfma_f32_16x16x32_bf16 v[56:59], v[154:157], v[162:165], v[56:59]
	v_mfma_f32_16x16x32_bf16 v[52:55], v[146:149], v[170:173], v[52:55]
	v_mfma_f32_16x16x32_bf16 v[48:51], v[154:157], v[170:173], v[48:51]
	v_mfma_f32_16x16x32_bf16 v[36:39], v[146:149], v[182:185], v[36:39]
	v_mfma_f32_16x16x32_bf16 v[32:35], v[154:157], v[182:185], v[32:35]
	v_mfma_f32_16x16x32_bf16 v[20:23], v[146:149], v[190:193], v[20:23]
	v_mfma_f32_16x16x32_bf16 v[16:19], v[154:157], v[190:193], v[16:19]
	s_barrier
	s_add_u32 s46, s14, 0x40000
	s_addc_u32 s47, s15, 0
	s_add_i32 m0, s20, 0x14000
	s_nop 0
	global_load_lds_dwordx4 v176, s[46:47]
	s_add_i32 m0, s20, 0x16000
	s_nop 0
	global_load_lds_dwordx4 v128, s[46:47]
	s_waitcnt vmcnt(6)
	s_barrier
	v_mfma_f32_16x16x32_bf16 v[44:47], v[194:197], v[158:161], v[44:47]
	v_mfma_f32_16x16x32_bf16 v[40:43], v[202:205], v[158:161], v[40:43]
	v_mfma_f32_16x16x32_bf16 v[28:31], v[194:197], v[166:169], v[28:31]
	v_mfma_f32_16x16x32_bf16 v[24:27], v[202:205], v[166:169], v[24:27]
	v_mfma_f32_16x16x32_bf16 v[12:15], v[194:197], v[178:181], v[12:15]
	v_mfma_f32_16x16x32_bf16 v[8:11], v[202:205], v[178:181], v[8:11]
	v_mfma_f32_16x16x32_bf16 v[4:7], v[194:197], v[186:189], v[4:7]
	v_mfma_f32_16x16x32_bf16 v[0:3], v[202:205], v[186:189], v[0:3]
	v_mfma_f32_16x16x32_bf16 v[44:47], v[198:201], v[162:165], v[44:47]
	v_mfma_f32_16x16x32_bf16 v[40:43], v[206:209], v[162:165], v[40:43]
	v_mfma_f32_16x16x32_bf16 v[28:31], v[198:201], v[170:173], v[28:31]
	v_mfma_f32_16x16x32_bf16 v[24:27], v[206:209], v[170:173], v[24:27]
	v_mfma_f32_16x16x32_bf16 v[12:15], v[198:201], v[182:185], v[12:15]
	v_mfma_f32_16x16x32_bf16 v[8:11], v[206:209], v[182:185], v[8:11]
	v_mfma_f32_16x16x32_bf16 v[4:7], v[198:201], v[190:193], v[4:7]
	v_mfma_f32_16x16x32_bf16 v[0:3], v[206:209], v[190:193], v[0:3]
	v_add_u32_e32 v154, 0x18000, v139
	s_barrier
	ds_read_b128 v[142:145], v154
	ds_read_b128 v[146:149], v154 offset:1024
	ds_read_b128 v[150:153], v154 offset:2048
	ds_read_b128 v[154:157], v154 offset:3072
	s_add_u32 s16, s16, 0x40000
	s_addc_u32 s17, s17, 0
	s_mov_b32 m0, s23
	ds_read_b128 v[158:161], v141 offset:32768
	ds_read_b128 v[162:165], v141 offset:33792
	ds_read_b128 v[166:169], v141 offset:34816
	ds_read_b128 v[170:173], v141 offset:35840
	ds_read_b128 v[178:181], v141 offset:36864
	ds_read_b128 v[182:185], v141 offset:37888
	ds_read_b128 v[186:189], v141 offset:38912
	global_load_lds_dwordx4 v132, s[16:17]
	s_mov_b32 m0, s26
	ds_read_b128 v[190:193], v141 offset:39936
	global_load_lds_dwordx4 v130, s[16:17]
	s_waitcnt lgkmcnt(8)
	s_barrier
; #define PG8_STAGE(bufoff, gbase, voff) do { _Pragma("unroll") for (int _i = 0; _i < 2; ++_i) \
;         __builtin_amdgcn_global_load_lds((const unsigned*)((const char*)(gbase) + (voff)[_i]), (PG8_LAS unsigned*)(lds + (bufoff) + ldsw + _i * 8192), 16, 0, 0); } while (0)
; #define PG8_LDA(dst, b, h) do { _Pragma("unroll") for (int m = 0; m < 4; ++m) _Pragma("unroll") for (int k = 0; k < 2; ++k) dst[m][k] = *(const PG8_LAS bf16x8*)(lds + PG8_SA(b, h) + aoff + m * 2048 + k * 1024); } while (0)
; #define PG8_LDB(dst, b, h) do { _Pragma("unroll") for (int n = 0; n < 2; ++n) _Pragma("unroll") for (int k = 0; k < 2; ++k) dst[n][k] = *(const PG8_LAS bf16x8*)(lds + PG8_SB(b, h) + boff + n * 2048 + k * 1024); } while (0)
; #define PG8_MMA(ai, bj, At, Bt) do { __builtin_amdgcn_s_setprio(1); _Pragma("unroll") for (int m = 0; m < 4; ++m) _Pragma("unroll") for (int n = 0; n < 2; ++n) _Pragma("unroll") for (int k = 0; k < 2; ++k) \
;         acc[ai][bj][m][n] = __builtin_amdgcn_mfma_f32_16x16x32_bf16(Bt[n][k], At[m][k], acc[ai][bj][m][n], 0, 0, 0); __builtin_amdgcn_s_setprio(0); } while (0)
; #define PG8_WAIT_V(n) asm volatile("s_waitcnt vmcnt(" #n ")" ::: "memory")
; #define PG8_WAIT_L(n) asm volatile("s_waitcnt lgkmcnt(" #n ")" ::: "memory")
; #define PG8_BAR __builtin_amdgcn_s_barrier()
; #define PG8_SCHED __builtin_amdgcn_sched_barrier(0)
; template <class Epi, class Sched>
; __device__ __forceinline__ void gemm_phase(PG8_LAS unsigned char* lds, const Gemm g, const Sched& S, const Epi& E) {
;     ...
;             PG8_WAIT_L(8); PG8_BAR; PG8_WAIT_L(0); PG8_MMA(0, 0, At, B0); PG8_BAR; PG8_SCHED;
;             PG8_LDB(B1, 1, 1); PG8_STAGE(PG8_SB(1, 0), b3, voffB);
;             PG8_BAR; PG8_WAIT_L(0); PG8_MMA(0, 1, At, B1); PG8_BAR;
;             PG8_LDA(At, 1, 1); PG8_STAGE(PG8_SA(1, 0), a3, voffA);
;             PG8_BAR; PG8_WAIT_L(0); PG8_MMA(1, 0, At, B0); PG8_BAR; PG8_SCHED;
;             PG8_STAGE(PG8_SB(1, 1), b3 + hstep, voffB);
;             PG8_WAIT_V(6); PG8_BAR; PG8_MMA(1, 1, At, B1); PG8_BAR;
	s_waitcnt lgkmcnt(0)
	v_mfma_f32_16x16x32_bf16 v[124:127], v[142:145], v[158:161], v[124:127]
	v_mfma_f32_16x16x32_bf16 v[120:123], v[150:153], v[158:161], v[120:123]
	v_mfma_f32_16x16x32_bf16 v[116:119], v[142:145], v[166:169], v[116:119]
	v_mfma_f32_16x16x32_bf16 v[112:115], v[150:153], v[166:169], v[112:115]
	v_mfma_f32_16x16x32_bf16 v[100:103], v[142:145], v[178:181], v[100:103]
	v_mfma_f32_16x16x32_bf16 v[96:99], v[150:153], v[178:181], v[96:99]
	v_mfma_f32_16x16x32_bf16 v[84:87], v[142:145], v[186:189], v[84:87]
	v_mfma_f32_16x16x32_bf16 v[80:83], v[150:153], v[186:189], v[80:83]
	v_mfma_f32_16x16x32_bf16 v[124:127], v[146:149], v[162:165], v[124:127]
	v_mfma_f32_16x16x32_bf16 v[120:123], v[154:157], v[162:165], v[120:123]
	v_mfma_f32_16x16x32_bf16 v[116:119], v[146:149], v[170:173], v[116:119]
	v_mfma_f32_16x16x32_bf16 v[112:115], v[154:157], v[170:173], v[112:115]
	v_mfma_f32_16x16x32_bf16 v[100:103], v[146:149], v[182:185], v[100:103]
	v_mfma_f32_16x16x32_bf16 v[96:99], v[154:157], v[182:185], v[96:99]
	v_mfma_f32_16x16x32_bf16 v[84:87], v[146:149], v[190:193], v[84:87]
	v_mfma_f32_16x16x32_bf16 v[80:83], v[154:157], v[190:193], v[80:83]
	s_barrier
	v_add_u32_e32 v206, 0x1c000, v139
	s_add_i32 m0, s20, 0x18000
	ds_read_b128 v[194:197], v206
	ds_read_b128 v[198:201], v206 offset:1024
	ds_read_b128 v[202:205], v206 offset:2048
	global_load_lds_dwordx4 v176, s[98:99]
	s_add_i32 m0, s20, 0x1a000
	ds_read_b128 v[206:209], v206 offset:3072
	global_load_lds_dwordx4 v128, s[98:99]
	s_barrier
	s_waitcnt lgkmcnt(0)
	v_mfma_f32_16x16x32_bf16 v[108:111], v[194:197], v[158:161], v[108:111]
	v_mfma_f32_16x16x32_bf16 v[104:107], v[202:205], v[158:161], v[104:107]
	v_mfma_f32_16x16x32_bf16 v[92:95], v[194:197], v[166:169], v[92:95]
	v_mfma_f32_16x16x32_bf16 v[88:91], v[202:205], v[166:169], v[88:91]
	v_mfma_f32_16x16x32_bf16 v[76:79], v[194:197], v[178:181], v[76:79]
	v_mfma_f32_16x16x32_bf16 v[72:75], v[202:205], v[178:181], v[72:75]
	v_mfma_f32_16x16x32_bf16 v[68:71], v[194:197], v[186:189], v[68:71]
	v_mfma_f32_16x16x32_bf16 v[64:67], v[202:205], v[186:189], v[64:67]
	v_mfma_f32_16x16x32_bf16 v[108:111], v[198:201], v[162:165], v[108:111]
	v_mfma_f32_16x16x32_bf16 v[104:107], v[206:209], v[162:165], v[104:107]
	v_mfma_f32_16x16x32_bf16 v[92:95], v[198:201], v[170:173], v[92:95]
	v_mfma_f32_16x16x32_bf16 v[88:91], v[206:209], v[170:173], v[88:91]
	v_mfma_f32_16x16x32_bf16 v[76:79], v[198:201], v[182:185], v[76:79]
	v_mfma_f32_16x16x32_bf16 v[72:75], v[206:209], v[182:185], v[72:75]
	v_mfma_f32_16x16x32_bf16 v[68:71], v[198:201], v[190:193], v[68:71]
	v_mfma_f32_16x16x32_bf16 v[64:67], v[206:209], v[190:193], v[64:67]
	s_mov_b32 m0, s28
	s_barrier
	ds_read_b128 v[158:161], v141 offset:49152
	ds_read_b128 v[162:165], v141 offset:50176
	ds_read_b128 v[166:169], v141 offset:51200
	ds_read_b128 v[170:173], v141 offset:52224
	ds_read_b128 v[178:181], v141 offset:53248
	ds_read_b128 v[182:185], v141 offset:54272
	ds_read_b128 v[186:189], v141 offset:55296
	global_load_lds_dwordx4 v132, s[100:101]
	s_mov_b32 m0, s29
	ds_read_b128 v[190:193], v141 offset:56320
	global_load_lds_dwordx4 v130, s[100:101]
	s_barrier
	s_waitcnt lgkmcnt(0)
	v_mfma_f32_16x16x32_bf16 v[60:63], v[142:145], v[158:161], v[60:63]
	v_mfma_f32_16x16x32_bf16 v[56:59], v[150:153], v[158:161], v[56:59]
	v_mfma_f32_16x16x32_bf16 v[52:55], v[142:145], v[166:169], v[52:55]
	v_mfma_f32_16x16x32_bf16 v[48:51], v[150:153], v[166:169], v[48:51]
	v_mfma_f32_16x16x32_bf16 v[36:39], v[142:145], v[178:181], v[36:39]
	v_mfma_f32_16x16x32_bf16 v[32:35], v[150:153], v[178:181], v[32:35]
	v_mfma_f32_16x16x32_bf16 v[20:23], v[142:145], v[186:189], v[20:23]
	v_mfma_f32_16x16x32_bf16 v[16:19], v[150:153], v[186:189], v[16:19]
	v_mfma_f32_16x16x32_bf16 v[60:63], v[146:149], v[162:165], v[60:63]
	v_mfma_f32_16x16x32_bf16 v[56:59], v[154:157], v[162:165], v[56:59]
	v_mfma_f32_16x16x32_bf16 v[52:55], v[146:149], v[170:173], v[52:55]
	v_mfma_f32_16x16x32_bf16 v[48:51], v[154:157], v[170:173], v[48:51]
	v_mfma_f32_16x16x32_bf16 v[36:39], v[146:149], v[182:185], v[36:39]
	v_mfma_f32_16x16x32_bf16 v[32:35], v[154:157], v[182:185], v[32:35]
	v_mfma_f32_16x16x32_bf16 v[20:23], v[146:149], v[190:193], v[20:23]
	v_mfma_f32_16x16x32_bf16 v[16:19], v[154:157], v[190:193], v[16:19]
	s_barrier
	s_add_u32 s14, s14, 0x40080
	s_addc_u32 s15, s15, 0
	s_add_i32 m0, s20, 0x1c000
	s_nop 0
	global_load_lds_dwordx4 v176, s[14:15]
	s_add_i32 m0, s20, 0x1e000
	s_nop 0
	global_load_lds_dwordx4 v128, s[14:15]
	s_waitcnt vmcnt(6)
	s_barrier
	v_mfma_f32_16x16x32_bf16 v[44:47], v[194:197], v[158:161], v[44:47]
	v_mfma_f32_16x16x32_bf16 v[40:43], v[202:205], v[158:161], v[40:43]
	v_mfma_f32_16x16x32_bf16 v[28:31], v[194:197], v[166:169], v[28:31]
	v_mfma_f32_16x16x32_bf16 v[24:27], v[202:205], v[166:169], v[24:27]
	v_mfma_f32_16x16x32_bf16 v[12:15], v[194:197], v[178:181], v[12:15]
	v_mfma_f32_16x16x32_bf16 v[8:11], v[202:205], v[178:181], v[8:11]
	v_mfma_f32_16x16x32_bf16 v[4:7], v[194:197], v[186:189], v[4:7]
	v_mfma_f32_16x16x32_bf16 v[0:3], v[202:205], v[186:189], v[0:3]
	v_mfma_f32_16x16x32_bf16 v[44:47], v[198:201], v[162:165], v[44:47]
	v_mfma_f32_16x16x32_bf16 v[40:43], v[206:209], v[162:165], v[40:43]
	v_mfma_f32_16x16x32_bf16 v[28:31], v[198:201], v[170:173], v[28:31]
	v_mfma_f32_16x16x32_bf16 v[24:27], v[206:209], v[170:173], v[24:27]
	v_mfma_f32_16x16x32_bf16 v[12:15], v[198:201], v[182:185], v[12:15]
	v_mfma_f32_16x16x32_bf16 v[8:11], v[206:209], v[182:185], v[8:11]
	v_mfma_f32_16x16x32_bf16 v[4:7], v[198:201], v[190:193], v[4:7]
	v_mfma_f32_16x16x32_bf16 v[0:3], v[206:209], v[190:193], v[0:3]
	s_add_i32 s45, s45, 2
	s_add_u32 s12, s12, 0x100
	s_addc_u32 s13, s13, 0
	s_add_u32 s43, s43, 0x100
	s_addc_u32 s44, s44, 0
	s_cmp_gt_u32 s45, 13
	s_barrier
; __device__ __forceinline__ unsigned cvtpk(float lo, float hi) { const f32x2 v = (f32x2){lo, hi}; const bf16v2 b = __builtin_convertvector(v, bf16v2); return __builtin_bit_cast(unsigned, b); }
; #define PG8_WAIT_V(n) asm volatile("s_waitcnt vmcnt(" #n ")" ::: "memory")
; #define PG8_BAR __builtin_amdgcn_s_barrier()
; template <class Epi, class Sched>
; __device__ __forceinline__ void gemm_phase(PG8_LAS unsigned char* lds, const Gemm g, const Sched& S, const Epi& E) {
;     ...
;         if constexpr (!Epi::AFTER_DRAIN) { E(acc, cur, wr, wc, fr, fq); S.done(cur); }
;         if (!has_next) break;
; #pragma unroll
;         for (int a = 0; a < 2; ++a)
; #pragma unroll
;             for (int b = 0; b < 2; ++b)
; #pragma unroll
;                 for (int m = 0; m < 4; ++m)
; #pragma unroll
;                     for (int n = 0; n < 2; ++n) acc[a][b][m][n] = (f32x4){0.f, 0.f, 0.f, 0.f};
;         cur = nxt; cA = nA; cB = nB; ++ui;
;     }
;     PG8_WAIT_V(0);
;     if (wr == 0) PG8_BAR;
;     PG8_BAR;
;     __device__ __forceinline__ void operator()(const f32x4 (&acc)[2][2][4][2], const pg8::Unit& u, int wr, int wc, int fr, int fq) const {
;         const int row0 = u.pm * 256 + wr * 64 + fr, col0 = u.pn * 256 + wc * 32 + 8 * fq;
; #pragma unroll
;         for (int ai = 0; ai < 2; ++ai)
; #pragma unroll
;             for (int m = 0; m < 4; ++m) { bf16_t* rowp = O + (size_t)(row0 + ai * 128 + m * 16) * ldc + col0;
; #pragma unroll
;                 for (int bj = 0; bj < 2; ++bj) { const f32x4 v0 = acc[ai][bj][m][0], v1 = acc[ai][bj][m][1];
;                     u32x4 w; w.x = cvtpk(v0[0], v0[1]); w.y = cvtpk(v0[2], v0[3]); w.z = cvtpk(v1[0], v1[1]); w.w = cvtpk(v1[2], v1[3]);
;                     *(u32x4*)(rowp + bj * 128) = w; } }
	s_cbranch_scc0 .LBB0_137
	v_lshl_add_u32 v142, s0, 8, v138
	v_lshl_or_b32 v144, s34, 8, v140
	v_ashrrev_i32_e32 v143, 31, v142
	v_readlane_b32 s12, v253, 18
	v_ashrrev_i32_e32 v145, 31, v144
	v_lshlrev_b64 v[146:147], 11, v[142:143]
	v_readlane_b32 s13, v253, 19
	v_cvt_pk_bf16_f32 v108, v108, v109
	v_cvt_pk_bf16_f32 v109, v110, v111
	v_cvt_pk_bf16_f32 v110, v104, v105
	v_or_b32_e32 v104, 16, v142
	v_cvt_pk_bf16_f32 v92, v92, v93
	v_cvt_pk_bf16_f32 v93, v94, v95
	v_cvt_pk_bf16_f32 v94, v88, v89
	v_or_b32_e32 v88, 32, v142
	v_cvt_pk_bf16_f32 v76, v76, v77
	v_cvt_pk_bf16_f32 v77, v78, v79
	v_cvt_pk_bf16_f32 v78, v72, v73
	v_or_b32_e32 v72, 48, v142
	v_lshl_add_u64 v[146:147], s[12:13], 0, v[146:147]
	v_lshlrev_b64 v[144:145], 1, v[144:145]
	v_ashrrev_i32_e32 v105, 31, v104
	v_ashrrev_i32_e32 v89, 31, v88
	v_ashrrev_i32_e32 v73, 31, v72
	v_lshl_add_u64 v[146:147], v[146:147], 0, v[144:145]
	v_lshlrev_b64 v[104:105], 11, v[104:105]
	v_lshlrev_b64 v[88:89], 11, v[88:89]
	v_lshlrev_b64 v[72:73], 11, v[72:73]
	v_lshl_add_u64 v[104:105], s[12:13], 0, v[104:105]
	v_lshl_add_u64 v[88:89], s[12:13], 0, v[88:89]
	v_lshl_add_u64 v[72:73], s[12:13], 0, v[72:73]
	s_mov_b64 s[12:13], 0x40000
	v_cvt_pk_bf16_f32 v60, v60, v61
	v_cvt_pk_bf16_f32 v61, v62, v63
	v_cvt_pk_bf16_f32 v62, v56, v57
	v_add_co_u32_e32 v56, vcc, s2, v146
	v_cvt_pk_bf16_f32 v68, v68, v69
	v_cvt_pk_bf16_f32 v69, v70, v71
	v_cvt_pk_bf16_f32 v70, v64, v65
	v_lshl_add_u64 v[64:65], v[146:147], 0, s[12:13]
	v_addc_co_u32_e32 v57, vcc, 0, v147, vcc
	v_cvt_pk_bf16_f32 v44, v44, v45
	v_cvt_pk_bf16_f32 v45, v46, v47
	v_cvt_pk_bf16_f32 v46, v40, v41
	v_cvt_pk_bf16_f32 v47, v42, v43
	s_mov_b32 s0, 0x48000
	global_store_dwordx4 v[64:65], v[44:47], off offset:256
	s_mov_b64 s[12:13], 0x48000
	v_cvt_pk_bf16_f32 v28, v28, v29
	v_add_co_u32_e32 v46, vcc, s0, v146
	v_lshl_add_u64 v[44:45], v[146:147], 0, s[12:13]
	s_nop 0
	v_addc_co_u32_e32 v47, vcc, 0, v147, vcc
	v_cvt_pk_bf16_f32 v29, v30, v31
	v_cvt_pk_bf16_f32 v30, v24, v25
	v_cvt_pk_bf16_f32 v31, v26, v27
	s_mov_b32 s0, 0x50000
	global_store_dwordx4 v[44:45], v[28:31], off offset:256
	s_mov_b64 s[12:13], 0x50000
	v_cvt_pk_bf16_f32 v111, v106, v107
	v_add_co_u32_e32 v30, vcc, s0, v146
	v_lshl_add_u64 v[28:29], v[146:147], 0, s[12:13]
	s_nop 0
	v_addc_co_u32_e32 v31, vcc, 0, v147, vcc
	v_cvt_pk_bf16_f32 v12, v12, v13
	v_cvt_pk_bf16_f32 v13, v14, v15
	v_cvt_pk_bf16_f32 v14, v8, v9
	v_cvt_pk_bf16_f32 v15, v10, v11
	s_mov_b32 s0, 0x58000
	global_store_dwordx4 v[146:147], v[108:111], off offset:256
	v_cvt_pk_bf16_f32 v95, v90, v91
	global_store_dwordx4 v[28:29], v[12:15], off offset:256
	v_lshl_add_u64 v[108:109], v[104:105], 0, v[144:145]
	global_store_dwordx4 v[108:109], v[92:95], off offset:256
	v_add_co_u32_e32 v14, vcc, s0, v146
	s_nop 0
	v_lshl_add_u64 v[92:93], v[88:89], 0, v[144:145]
	v_cvt_pk_bf16_f32 v79, v74, v75
	s_mov_b64 s[12:13], 0x58000
	v_addc_co_u32_e32 v15, vcc, 0, v147, vcc
	v_cvt_pk_bf16_f32 v124, v124, v125
	v_cvt_pk_bf16_f32 v125, v126, v127
	v_cvt_pk_bf16_f32 v126, v120, v121
	v_cvt_pk_bf16_f32 v127, v122, v123
	v_cvt_pk_bf16_f32 v104, v116, v117
	v_cvt_pk_bf16_f32 v105, v118, v119
	v_cvt_pk_bf16_f32 v106, v112, v113
	v_cvt_pk_bf16_f32 v107, v114, v115
	v_cvt_pk_bf16_f32 v88, v100, v101
	v_cvt_pk_bf16_f32 v89, v102, v103
	v_cvt_pk_bf16_f32 v90, v96, v97
	v_cvt_pk_bf16_f32 v91, v98, v99
	global_store_dwordx4 v[92:93], v[76:79], off offset:256
	v_cvt_pk_bf16_f32 v74, v80, v81
	v_cvt_pk_bf16_f32 v75, v82, v83
	v_lshl_add_u64 v[76:77], v[72:73], 0, v[144:145]
	v_cvt_pk_bf16_f32 v72, v84, v85
	v_cvt_pk_bf16_f32 v73, v86, v87
	v_cvt_pk_bf16_f32 v71, v66, v67
	v_cvt_pk_bf16_f32 v63, v58, v59
	v_cvt_pk_bf16_f32 v40, v52, v53
	v_cvt_pk_bf16_f32 v41, v54, v55
	v_cvt_pk_bf16_f32 v42, v48, v49
	v_cvt_pk_bf16_f32 v43, v50, v51
	v_cvt_pk_bf16_f32 v24, v36, v37
	v_cvt_pk_bf16_f32 v25, v38, v39
	v_cvt_pk_bf16_f32 v26, v32, v33
	v_cvt_pk_bf16_f32 v27, v34, v35
	v_lshl_add_u64 v[12:13], v[146:147], 0, s[12:13]
	v_cvt_pk_bf16_f32 v8, v20, v21
	v_cvt_pk_bf16_f32 v9, v22, v23
	v_cvt_pk_bf16_f32 v10, v16, v17
	v_cvt_pk_bf16_f32 v11, v18, v19
	v_cvt_pk_bf16_f32 v4, v4, v5
	v_cvt_pk_bf16_f32 v5, v6, v7
	v_cvt_pk_bf16_f32 v6, v0, v1
	v_cvt_pk_bf16_f32 v7, v2, v3
	s_and_b64 vcc, exec, s[38:39]
	s_mov_b32 s34, s4
	s_mov_b32 s0, s6
	s_mov_b64 s[14:15], s[10:11]
	s_mov_b64 s[12:13], s[8:9]
	global_store_dwordx4 v[146:147], v[124:127], off
	global_store_dwordx4 v[108:109], v[104:107], off
	global_store_dwordx4 v[92:93], v[88:91], off
	global_store_dwordx4 v[76:77], v[72:75], off
	global_store_dwordx4 v[76:77], v[68:71], off offset:256
	global_store_dwordx4 v[56:57], v[60:63], off
	global_store_dwordx4 v[46:47], v[40:43], off
	global_store_dwordx4 v[30:31], v[24:27], off
	global_store_dwordx4 v[14:15], v[8:11], off
	global_store_dwordx4 v[12:13], v[4:7], off offset:256
	s_cbranch_vccz .LBB0_134
	s_waitcnt vmcnt(0)
	v_readlane_b32 s22, v255, 14
	s_cmpk_gt_u32 s19, 0xff
	v_readlane_b32 s23, v255, 15
	s_mov_b64 s[28:29], s[54:55]
	s_cbranch_scc1 .LBB0_141
	s_barrier

; #define PG8_STAGE(bufoff, gbase, voff) do { _Pragma("unroll") for (int _i = 0; _i < 2; ++_i) \
;         __builtin_amdgcn_global_load_lds((const unsigned*)((const char*)(gbase) + (voff)[_i]), (PG8_LAS unsigned*)(lds + (bufoff) + ldsw + _i * 8192), 16, 0, 0); } while (0)
; #define PG8_LDA(dst, b, h) do { _Pragma("unroll") for (int m = 0; m < 4; ++m) _Pragma("unroll") for (int k = 0; k < 2; ++k) dst[m][k] = *(const PG8_LAS bf16x8*)(lds + PG8_SA(b, h) + aoff + m * 2048 + k * 1024); } while (0)
; #define PG8_LDB(dst, b, h) do { _Pragma("unroll") for (int n = 0; n < 2; ++n) _Pragma("unroll") for (int k = 0; k < 2; ++k) dst[n][k] = *(const PG8_LAS bf16x8*)(lds + PG8_SB(b, h) + boff + n * 2048 + k * 1024); } while (0)
; #define PG8_WAIT_L(n) asm volatile("s_waitcnt lgkmcnt(" #n ")" ::: "memory")
; #define PG8_BAR __builtin_amdgcn_s_barrier()
; #define PG8_SCHED __builtin_amdgcn_sched_barrier(0)
; template <class Epi, class Sched>
; __device__ __forceinline__ void gemm_phase(PG8_LAS unsigned char* lds, const Gemm g, const Sched& S, const Epi& E) {
;     ...
;         const bool has_next = S.next(ui + 1, nxt);
;         const char* nA = has_next ? (const char*)g.A + (size_t)nxt.pm * tstep : cA; const char* nB = has_next ? (const char*)g.Bt + (size_t)nxt.pn * tstep : cB;
;         for (int t = 0; t < nt; t += 2) {
;             const bool last = (t == nt - 2);
;             const char* a1 = cA + (size_t)(t + 1) * kstep;
;             const char* a2 = last ? nA : cA + (size_t)(t + 2) * kstep; const char* b2 = last ? nB : cB + (size_t)(t + 2) * kstep;
;             const char* a3 = a2 + kstep; const char* b3 = b2 + kstep;
;             if (last && has_next) S.a_ready(nxt);
;             PG8_LDB(B0, 0, 0); PG8_SCHED; PG8_LDA(At, 0, 0); PG8_STAGE(PG8_SA(1, 1), a1 + hstep, voffA);
;             PG8_WAIT_L(8); PG8_BAR; PG8_WAIT_L(0); PG8_MMA(0, 0, At, B0); PG8_BAR; PG8_SCHED;
;     ...
; #pragma unroll
;         for (int a = 0; a < 2; ++a)
; #pragma unroll
;             for (int b = 0; b < 2; ++b)
; #pragma unroll
;                 for (int m = 0; m < 4; ++m)
; #pragma unroll
;                     for (int n = 0; n < 2; ++n) acc[a][b][m][n] = (f32x4){0.f, 0.f, 0.f, 0.f};
;         cur = nxt; cA = nA; cB = nB; ++ui;
.LBB0_357:
	v_mov_b64_e32 v[0:1], 0x2c0
	s_ashr_i32 s7, s6, 31
	v_cmp_lt_i64_e32 vcc, s[8:9], v[0:1]
	s_lshl_b64 s[8:9], s[6:7], 19
	s_add_u32 s8, s94, s8
	s_addc_u32 s9, s95, s9
	s_and_b64 s[10:11], vcc, exec
	s_cselect_b32 s7, s9, s13
	s_cselect_b32 s40, s8, s12
	s_ashr_i32 s5, s4, 31
	s_lshl_b64 s[10:11], s[4:5], 19
	s_add_u32 s10, s92, s10
	s_addc_u32 s11, s93, s11
	s_and_b64 s[16:17], vcc, exec
	s_cselect_b32 s5, s11, s15
	s_cselect_b32 s41, s10, s14
	s_add_u32 s12, s12, 0x40080
	s_addc_u32 s13, s13, 0
	s_add_u32 s43, s14, 0x100
	v_mov_b32_e32 v0, 0
	s_addc_u32 s44, s15, 0
	s_mov_b32 s45, -2
	v_mov_b32_e32 v1, v0
	v_mov_b32_e32 v2, v0
	v_mov_b32_e32 v3, v0
	v_mov_b32_e32 v4, v0
	v_mov_b32_e32 v5, v0
	v_mov_b32_e32 v6, v0
	v_mov_b32_e32 v7, v0
	v_mov_b32_e32 v8, v0
	v_mov_b32_e32 v9, v0
	v_mov_b32_e32 v10, v0
	v_mov_b32_e32 v11, v0
	v_mov_b32_e32 v12, v0
	v_mov_b32_e32 v13, v0
	v_mov_b32_e32 v14, v0
	v_mov_b32_e32 v15, v0
	v_mov_b32_e32 v24, v0
	v_mov_b32_e32 v25, v0
	v_mov_b32_e32 v26, v0
	v_mov_b32_e32 v27, v0
	v_mov_b32_e32 v28, v0
	v_mov_b32_e32 v29, v0
	v_mov_b32_e32 v30, v0
	v_mov_b32_e32 v31, v0
	v_mov_b32_e32 v40, v0
	v_mov_b32_e32 v41, v0
	v_mov_b32_e32 v42, v0
	v_mov_b32_e32 v43, v0
	v_mov_b32_e32 v44, v0
	v_mov_b32_e32 v45, v0
	v_mov_b32_e32 v46, v0
	v_mov_b32_e32 v47, v0
	v_mov_b32_e32 v16, v0
	v_mov_b32_e32 v17, v0
	v_mov_b32_e32 v18, v0
	v_mov_b32_e32 v19, v0
	v_mov_b32_e32 v20, v0
	v_mov_b32_e32 v21, v0
	v_mov_b32_e32 v22, v0
	v_mov_b32_e32 v23, v0
	v_mov_b32_e32 v32, v0
	v_mov_b32_e32 v33, v0
	v_mov_b32_e32 v34, v0
	v_mov_b32_e32 v35, v0
	v_mov_b32_e32 v36, v0
	v_mov_b32_e32 v37, v0
	v_mov_b32_e32 v38, v0
	v_mov_b32_e32 v39, v0
	v_mov_b32_e32 v48, v0
	v_mov_b32_e32 v49, v0
	v_mov_b32_e32 v50, v0
	v_mov_b32_e32 v51, v0
	v_mov_b32_e32 v52, v0
	v_mov_b32_e32 v53, v0
	v_mov_b32_e32 v54, v0
	v_mov_b32_e32 v55, v0
	v_mov_b32_e32 v56, v0
	v_mov_b32_e32 v57, v0
	v_mov_b32_e32 v58, v0
	v_mov_b32_e32 v59, v0
	v_mov_b32_e32 v60, v0
	v_mov_b32_e32 v61, v0
	v_mov_b32_e32 v62, v0
	v_mov_b32_e32 v63, v0
	v_mov_b32_e32 v64, v0
	v_mov_b32_e32 v65, v0
	v_mov_b32_e32 v66, v0
	v_mov_b32_e32 v67, v0
	v_mov_b32_e32 v68, v0
	v_mov_b32_e32 v69, v0
	v_mov_b32_e32 v70, v0
	v_mov_b32_e32 v71, v0
	v_mov_b32_e32 v72, v0
	v_mov_b32_e32 v73, v0
	v_mov_b32_e32 v74, v0
	v_mov_b32_e32 v75, v0
	v_mov_b32_e32 v76, v0
	v_mov_b32_e32 v77, v0
	v_mov_b32_e32 v78, v0
	v_mov_b32_e32 v79, v0
	v_mov_b32_e32 v88, v0
	v_mov_b32_e32 v89, v0
	v_mov_b32_e32 v90, v0
	v_mov_b32_e32 v91, v0
	v_mov_b32_e32 v92, v0
	v_mov_b32_e32 v93, v0
	v_mov_b32_e32 v94, v0
	v_mov_b32_e32 v95, v0
	v_mov_b32_e32 v104, v0
	v_mov_b32_e32 v105, v0
	v_mov_b32_e32 v106, v0
	v_mov_b32_e32 v107, v0
	v_mov_b32_e32 v108, v0
	v_mov_b32_e32 v109, v0
	v_mov_b32_e32 v110, v0
	v_mov_b32_e32 v111, v0
	v_mov_b32_e32 v80, v0
	v_mov_b32_e32 v81, v0
	v_mov_b32_e32 v82, v0
	v_mov_b32_e32 v83, v0
	v_mov_b32_e32 v84, v0
	v_mov_b32_e32 v85, v0
	v_mov_b32_e32 v86, v0
	v_mov_b32_e32 v87, v0
	v_mov_b32_e32 v96, v0
	v_mov_b32_e32 v97, v0
	v_mov_b32_e32 v98, v0
	v_mov_b32_e32 v99, v0
	v_mov_b32_e32 v100, v0
	v_mov_b32_e32 v101, v0
	v_mov_b32_e32 v102, v0
	v_mov_b32_e32 v103, v0
	v_mov_b32_e32 v112, v0
	v_mov_b32_e32 v113, v0
	v_mov_b32_e32 v114, v0
	v_mov_b32_e32 v115, v0
	v_mov_b32_e32 v116, v0
	v_mov_b32_e32 v117, v0
	v_mov_b32_e32 v118, v0
	v_mov_b32_e32 v119, v0
	v_mov_b32_e32 v120, v0
	v_mov_b32_e32 v121, v0
	v_mov_b32_e32 v122, v0
	v_mov_b32_e32 v123, v0
	v_mov_b32_e32 v124, v0
	v_mov_b32_e32 v125, v0
	v_mov_b32_e32 v126, v0
	v_mov_b32_e32 v127, v0
	v_readfirstlane_b32 s98, v245
	s_nop 3
	s_cmpk_lt_u32 s98, 0x100
	s_cbranch_scc1 .Lprio_skip3
	s_setprio 1
.Lprio_skip3:
.LBB0_358:
	s_add_u32 s14, s12, 0xfffc0080
	s_addc_u32 s15, s13, -1
	v_add_u32_e32 v154, 0x10000, v139
	ds_read_b128 v[142:145], v154
	ds_read_b128 v[146:149], v154 offset:1024
	ds_read_b128 v[150:153], v154 offset:2048
	ds_read_b128 v[154:157], v154 offset:3072
	s_cmp_eq_u32 s45, 12
	s_cselect_b32 s17, s7, s15
	s_cselect_b32 s16, s40, s14
	s_cselect_b32 s15, s5, s44
	s_cselect_b32 s14, s41, s43
	s_add_i32 m0, s1, 0xc000
	ds_read_b128 v[158:161], v141
	ds_read_b128 v[162:165], v141 offset:1024
	ds_read_b128 v[166:169], v141 offset:2048
	ds_read_b128 v[170:173], v141 offset:3072
	ds_read_b128 v[182:185], v141 offset:4096
	ds_read_b128 v[190:193], v141 offset:5120
	ds_read_b128 v[194:197], v141 offset:6144
	global_load_lds_dwordx4 v134, s[12:13]
	s_add_i32 m0, s1, 0xe000
	ds_read_b128 v[198:201], v141 offset:7168
	global_load_lds_dwordx4 v136, s[12:13]
	s_waitcnt lgkmcnt(8)
	s_barrier
	s_waitcnt lgkmcnt(0)
	v_mfma_f32_16x16x32_bf16 v[124:127], v[142:145], v[158:161], v[124:127]
	v_mfma_f32_16x16x32_bf16 v[120:123], v[150:153], v[158:161], v[120:123]
	v_mfma_f32_16x16x32_bf16 v[116:119], v[142:145], v[166:169], v[116:119]
	v_mfma_f32_16x16x32_bf16 v[112:115], v[150:153], v[166:169], v[112:115]
	v_mfma_f32_16x16x32_bf16 v[100:103], v[142:145], v[182:185], v[100:103]
	v_mfma_f32_16x16x32_bf16 v[96:99], v[150:153], v[182:185], v[96:99]
	v_mfma_f32_16x16x32_bf16 v[84:87], v[142:145], v[194:197], v[84:87]
	v_mfma_f32_16x16x32_bf16 v[80:83], v[150:153], v[194:197], v[80:83]
	v_mfma_f32_16x16x32_bf16 v[124:127], v[146:149], v[162:165], v[124:127]
	v_mfma_f32_16x16x32_bf16 v[120:123], v[154:157], v[162:165], v[120:123]
	v_mfma_f32_16x16x32_bf16 v[116:119], v[146:149], v[170:173], v[116:119]
	v_mfma_f32_16x16x32_bf16 v[112:115], v[154:157], v[170:173], v[112:115]
	v_mfma_f32_16x16x32_bf16 v[100:103], v[146:149], v[190:193], v[100:103]
	v_mfma_f32_16x16x32_bf16 v[96:99], v[154:157], v[190:193], v[96:99]
	v_mfma_f32_16x16x32_bf16 v[84:87], v[146:149], v[198:201], v[84:87]
	v_mfma_f32_16x16x32_bf16 v[80:83], v[154:157], v[198:201], v[80:83]
	s_barrier
; #define PG8_STAGE(bufoff, gbase, voff) do { _Pragma("unroll") for (int _i = 0; _i < 2; ++_i) \
;         __builtin_amdgcn_global_load_lds((const unsigned*)((const char*)(gbase) + (voff)[_i]), (PG8_LAS unsigned*)(lds + (bufoff) + ldsw + _i * 8192), 16, 0, 0); } while (0)
; #define PG8_LDA(dst, b, h) do { _Pragma("unroll") for (int m = 0; m < 4; ++m) _Pragma("unroll") for (int k = 0; k < 2; ++k) dst[m][k] = *(const PG8_LAS bf16x8*)(lds + PG8_SA(b, h) + aoff + m * 2048 + k * 1024); } while (0)
; #define PG8_LDB(dst, b, h) do { _Pragma("unroll") for (int n = 0; n < 2; ++n) _Pragma("unroll") for (int k = 0; k < 2; ++k) dst[n][k] = *(const PG8_LAS bf16x8*)(lds + PG8_SB(b, h) + boff + n * 2048 + k * 1024); } while (0)
; #define PG8_MMA(ai, bj, At, Bt) do { __builtin_amdgcn_s_setprio(1); _Pragma("unroll") for (int m = 0; m < 4; ++m) _Pragma("unroll") for (int n = 0; n < 2; ++n) _Pragma("unroll") for (int k = 0; k < 2; ++k) \
;         acc[ai][bj][m][n] = __builtin_amdgcn_mfma_f32_16x16x32_bf16(Bt[n][k], At[m][k], acc[ai][bj][m][n], 0, 0, 0); __builtin_amdgcn_s_setprio(0); } while (0)
; #define PG8_WAIT_V(n) asm volatile("s_waitcnt vmcnt(" #n ")" ::: "memory")
; #define PG8_WAIT_L(n) asm volatile("s_waitcnt lgkmcnt(" #n ")" ::: "memory")
; #define PG8_BAR __builtin_amdgcn_s_barrier()
; #define PG8_SCHED __builtin_amdgcn_sched_barrier(0)
; template <class Epi, class Sched>
; __device__ __forceinline__ void gemm_phase(PG8_LAS unsigned char* lds, const Gemm g, const Sched& S, const Epi& E) {
;     ...
;             PG8_LDB(B1, 0, 1); PG8_STAGE(PG8_SB(0, 0), b2, voffB);
;             PG8_BAR; PG8_WAIT_L(0); PG8_MMA(0, 1, At, B1); PG8_BAR;
;             PG8_LDA(At, 0, 1); PG8_STAGE(PG8_SA(0, 0), a2, voffA);
;             PG8_BAR; PG8_WAIT_L(0); PG8_MMA(1, 0, At, B0); PG8_BAR; PG8_SCHED;
;             PG8_STAGE(PG8_SB(0, 1), b2 + hstep, voffB);
;             PG8_WAIT_V(6); PG8_BAR; PG8_MMA(1, 1, At, B1); PG8_BAR;
;             PG8_LDB(B0, 1, 0); PG8_SCHED; PG8_LDA(At, 1, 0); PG8_STAGE(PG8_SA(0, 1), a2 + hstep, voffA);
;             PG8_WAIT_L(8); PG8_BAR; PG8_WAIT_L(0); PG8_MMA(0, 0, At, B0); PG8_BAR; PG8_SCHED;
	s_add_i32 s48, 0, 0x14000
	v_add_u32_e32 v174, 0x14000, v139
	ds_read_b128 v[202:205], v174
	ds_read_b128 v[206:209], v174 offset:1024
	s_add_u32 s98, s14, 0x80
	s_addc_u32 s99, s15, 0
	s_add_i32 m0, s20, 0x10000
	ds_read_b128 v[210:213], v174 offset:2048
	global_load_lds_dwordx4 v176, s[14:15]
	s_add_i32 m0, s20, 0x12000
	ds_read_b128 v[214:217], v174 offset:3072
	global_load_lds_dwordx4 v128, s[14:15]
	s_barrier
	s_waitcnt lgkmcnt(0)
	v_mfma_f32_16x16x32_bf16 v[108:111], v[202:205], v[158:161], v[108:111]
	v_mfma_f32_16x16x32_bf16 v[104:107], v[210:213], v[158:161], v[104:107]
	v_mfma_f32_16x16x32_bf16 v[92:95], v[202:205], v[166:169], v[92:95]
	v_mfma_f32_16x16x32_bf16 v[88:91], v[210:213], v[166:169], v[88:91]
	v_mfma_f32_16x16x32_bf16 v[76:79], v[202:205], v[182:185], v[76:79]
	v_mfma_f32_16x16x32_bf16 v[72:75], v[210:213], v[182:185], v[72:75]
	v_mfma_f32_16x16x32_bf16 v[68:71], v[202:205], v[194:197], v[68:71]
	v_mfma_f32_16x16x32_bf16 v[64:67], v[210:213], v[194:197], v[64:67]
	v_mfma_f32_16x16x32_bf16 v[108:111], v[206:209], v[162:165], v[108:111]
	v_mfma_f32_16x16x32_bf16 v[104:107], v[214:217], v[162:165], v[104:107]
	v_mfma_f32_16x16x32_bf16 v[92:95], v[206:209], v[170:173], v[92:95]
	v_mfma_f32_16x16x32_bf16 v[88:91], v[214:217], v[170:173], v[88:91]
	v_mfma_f32_16x16x32_bf16 v[76:79], v[206:209], v[190:193], v[76:79]
	v_mfma_f32_16x16x32_bf16 v[72:75], v[214:217], v[190:193], v[72:75]
	v_mfma_f32_16x16x32_bf16 v[68:71], v[206:209], v[198:201], v[68:71]
	v_mfma_f32_16x16x32_bf16 v[64:67], v[214:217], v[198:201], v[64:67]
	s_mov_b32 m0, s1
	s_add_u32 s100, s16, 0x80
	s_addc_u32 s101, s17, 0
	s_barrier
	ds_read_b128 v[158:161], v141 offset:16384
	ds_read_b128 v[162:165], v141 offset:17408
	ds_read_b128 v[166:169], v141 offset:18432
	ds_read_b128 v[170:173], v141 offset:19456
	ds_read_b128 v[182:185], v141 offset:20480
	ds_read_b128 v[190:193], v141 offset:21504
	ds_read_b128 v[194:197], v141 offset:22528
	global_load_lds_dwordx4 v132, s[16:17]
	s_mov_b32 m0, s22
	ds_read_b128 v[198:201], v141 offset:23552
	global_load_lds_dwordx4 v130, s[16:17]
	s_barrier
	s_waitcnt lgkmcnt(0)
	v_mfma_f32_16x16x32_bf16 v[60:63], v[142:145], v[158:161], v[60:63]
	v_mfma_f32_16x16x32_bf16 v[56:59], v[150:153], v[158:161], v[56:59]
	v_mfma_f32_16x16x32_bf16 v[52:55], v[142:145], v[166:169], v[52:55]
	v_mfma_f32_16x16x32_bf16 v[48:51], v[150:153], v[166:169], v[48:51]
	v_mfma_f32_16x16x32_bf16 v[36:39], v[142:145], v[182:185], v[36:39]
	v_mfma_f32_16x16x32_bf16 v[32:35], v[150:153], v[182:185], v[32:35]
	v_mfma_f32_16x16x32_bf16 v[20:23], v[142:145], v[194:197], v[20:23]
	v_mfma_f32_16x16x32_bf16 v[16:19], v[150:153], v[194:197], v[16:19]
	v_mfma_f32_16x16x32_bf16 v[60:63], v[146:149], v[162:165], v[60:63]
	v_mfma_f32_16x16x32_bf16 v[56:59], v[154:157], v[162:165], v[56:59]
	v_mfma_f32_16x16x32_bf16 v[52:55], v[146:149], v[170:173], v[52:55]
	v_mfma_f32_16x16x32_bf16 v[48:51], v[154:157], v[170:173], v[48:51]
	v_mfma_f32_16x16x32_bf16 v[36:39], v[146:149], v[190:193], v[36:39]
	v_mfma_f32_16x16x32_bf16 v[32:35], v[154:157], v[190:193], v[32:35]
	v_mfma_f32_16x16x32_bf16 v[20:23], v[146:149], v[198:201], v[20:23]
	v_mfma_f32_16x16x32_bf16 v[16:19], v[154:157], v[198:201], v[16:19]
	s_barrier
	s_add_u32 s46, s14, 0x40000
	s_addc_u32 s47, s15, 0
	s_add_i32 m0, s20, 0x14000
	s_nop 0
	global_load_lds_dwordx4 v176, s[46:47]
	s_add_i32 m0, s20, 0x16000
	s_nop 0
	global_load_lds_dwordx4 v128, s[46:47]
	s_waitcnt vmcnt(6)
	s_barrier
	v_mfma_f32_16x16x32_bf16 v[44:47], v[202:205], v[158:161], v[44:47]
	v_mfma_f32_16x16x32_bf16 v[40:43], v[210:213], v[158:161], v[40:43]
	v_mfma_f32_16x16x32_bf16 v[28:31], v[202:205], v[166:169], v[28:31]
	v_mfma_f32_16x16x32_bf16 v[24:27], v[210:213], v[166:169], v[24:27]
	v_mfma_f32_16x16x32_bf16 v[12:15], v[202:205], v[182:185], v[12:15]
	v_mfma_f32_16x16x32_bf16 v[8:11], v[210:213], v[182:185], v[8:11]
	v_mfma_f32_16x16x32_bf16 v[4:7], v[202:205], v[194:197], v[4:7]
	v_mfma_f32_16x16x32_bf16 v[0:3], v[210:213], v[194:197], v[0:3]
	v_mfma_f32_16x16x32_bf16 v[44:47], v[206:209], v[162:165], v[44:47]
	v_mfma_f32_16x16x32_bf16 v[40:43], v[214:217], v[162:165], v[40:43]
	v_mfma_f32_16x16x32_bf16 v[28:31], v[206:209], v[170:173], v[28:31]
	v_mfma_f32_16x16x32_bf16 v[24:27], v[214:217], v[170:173], v[24:27]
	v_mfma_f32_16x16x32_bf16 v[12:15], v[206:209], v[190:193], v[12:15]
	v_mfma_f32_16x16x32_bf16 v[8:11], v[214:217], v[190:193], v[8:11]
	v_mfma_f32_16x16x32_bf16 v[4:7], v[206:209], v[198:201], v[4:7]
	v_mfma_f32_16x16x32_bf16 v[0:3], v[214:217], v[198:201], v[0:3]
	v_add_u32_e32 v154, 0x18000, v139
	s_barrier
	ds_read_b128 v[142:145], v154
	ds_read_b128 v[146:149], v154 offset:1024
	ds_read_b128 v[150:153], v154 offset:2048
	ds_read_b128 v[154:157], v154 offset:3072
	s_add_u32 s16, s16, 0x40000
	s_addc_u32 s17, s17, 0
	s_mov_b32 m0, s23
	ds_read_b128 v[158:161], v141 offset:32768
	ds_read_b128 v[162:165], v141 offset:33792
	ds_read_b128 v[166:169], v141 offset:34816
	ds_read_b128 v[170:173], v141 offset:35840
	ds_read_b128 v[182:185], v141 offset:36864
	ds_read_b128 v[190:193], v141 offset:37888
	ds_read_b128 v[194:197], v141 offset:38912
	global_load_lds_dwordx4 v132, s[16:17]
	s_mov_b32 m0, s26
	ds_read_b128 v[198:201], v141 offset:39936
	global_load_lds_dwordx4 v130, s[16:17]
	s_waitcnt lgkmcnt(8)
	s_barrier
; #define PG8_STAGE(bufoff, gbase, voff) do { _Pragma("unroll") for (int _i = 0; _i < 2; ++_i) \
;         __builtin_amdgcn_global_load_lds((const unsigned*)((const char*)(gbase) + (voff)[_i]), (PG8_LAS unsigned*)(lds + (bufoff) + ldsw + _i * 8192), 16, 0, 0); } while (0)
; #define PG8_LDA(dst, b, h) do { _Pragma("unroll") for (int m = 0; m < 4; ++m) _Pragma("unroll") for (int k = 0; k < 2; ++k) dst[m][k] = *(const PG8_LAS bf16x8*)(lds + PG8_SA(b, h) + aoff + m * 2048 + k * 1024); } while (0)
; #define PG8_LDB(dst, b, h) do { _Pragma("unroll") for (int n = 0; n < 2; ++n) _Pragma("unroll") for (int k = 0; k < 2; ++k) dst[n][k] = *(const PG8_LAS bf16x8*)(lds + PG8_SB(b, h) + boff + n * 2048 + k * 1024); } while (0)
; #define PG8_MMA(ai, bj, At, Bt) do { __builtin_amdgcn_s_setprio(1); _Pragma("unroll") for (int m = 0; m < 4; ++m) _Pragma("unroll") for (int n = 0; n < 2; ++n) _Pragma("unroll") for (int k = 0; k < 2; ++k) \
;         acc[ai][bj][m][n] = __builtin_amdgcn_mfma_f32_16x16x32_bf16(Bt[n][k], At[m][k], acc[ai][bj][m][n], 0, 0, 0); __builtin_amdgcn_s_setprio(0); } while (0)
; #define PG8_WAIT_V(n) asm volatile("s_waitcnt vmcnt(" #n ")" ::: "memory")
; #define PG8_WAIT_L(n) asm volatile("s_waitcnt lgkmcnt(" #n ")" ::: "memory")
; #define PG8_BAR __builtin_amdgcn_s_barrier()
; #define PG8_SCHED __builtin_amdgcn_sched_barrier(0)
; template <class Epi, class Sched>
; __device__ __forceinline__ void gemm_phase(PG8_LAS unsigned char* lds, const Gemm g, const Sched& S, const Epi& E) {
;     ...
;             PG8_WAIT_L(8); PG8_BAR; PG8_WAIT_L(0); PG8_MMA(0, 0, At, B0); PG8_BAR; PG8_SCHED;
;             PG8_LDB(B1, 1, 1); PG8_STAGE(PG8_SB(1, 0), b3, voffB);
;             PG8_BAR; PG8_WAIT_L(0); PG8_MMA(0, 1, At, B1); PG8_BAR;
;             PG8_LDA(At, 1, 1); PG8_STAGE(PG8_SA(1, 0), a3, voffA);
;             PG8_BAR; PG8_WAIT_L(0); PG8_MMA(1, 0, At, B0); PG8_BAR; PG8_SCHED;
;             PG8_STAGE(PG8_SB(1, 1), b3 + hstep, voffB);
;             PG8_WAIT_V(6); PG8_BAR; PG8_MMA(1, 1, At, B1); PG8_BAR;
	s_waitcnt lgkmcnt(0)
	v_mfma_f32_16x16x32_bf16 v[124:127], v[142:145], v[158:161], v[124:127]
	v_mfma_f32_16x16x32_bf16 v[120:123], v[150:153], v[158:161], v[120:123]
	v_mfma_f32_16x16x32_bf16 v[116:119], v[142:145], v[166:169], v[116:119]
	v_mfma_f32_16x16x32_bf16 v[112:115], v[150:153], v[166:169], v[112:115]
	v_mfma_f32_16x16x32_bf16 v[100:103], v[142:145], v[182:185], v[100:103]
	v_mfma_f32_16x16x32_bf16 v[96:99], v[150:153], v[182:185], v[96:99]
	v_mfma_f32_16x16x32_bf16 v[84:87], v[142:145], v[194:197], v[84:87]
	v_mfma_f32_16x16x32_bf16 v[80:83], v[150:153], v[194:197], v[80:83]
	v_mfma_f32_16x16x32_bf16 v[124:127], v[146:149], v[162:165], v[124:127]
	v_mfma_f32_16x16x32_bf16 v[120:123], v[154:157], v[162:165], v[120:123]
	v_mfma_f32_16x16x32_bf16 v[116:119], v[146:149], v[170:173], v[116:119]
	v_mfma_f32_16x16x32_bf16 v[112:115], v[154:157], v[170:173], v[112:115]
	v_mfma_f32_16x16x32_bf16 v[100:103], v[146:149], v[190:193], v[100:103]
	v_mfma_f32_16x16x32_bf16 v[96:99], v[154:157], v[190:193], v[96:99]
	v_mfma_f32_16x16x32_bf16 v[84:87], v[146:149], v[198:201], v[84:87]
	v_mfma_f32_16x16x32_bf16 v[80:83], v[154:157], v[198:201], v[80:83]
	s_barrier
	v_add_u32_e32 v188, 0x1c000, v139
	s_add_i32 m0, s20, 0x18000
	ds_read_b128 v[202:205], v188
	ds_read_b128 v[206:209], v188 offset:1024
	ds_read_b128 v[210:213], v188 offset:2048
	global_load_lds_dwordx4 v176, s[98:99]
	s_add_i32 m0, s20, 0x1a000
	ds_read_b128 v[214:217], v188 offset:3072
	global_load_lds_dwordx4 v128, s[98:99]
	s_barrier
	s_waitcnt lgkmcnt(0)
	v_mfma_f32_16x16x32_bf16 v[108:111], v[202:205], v[158:161], v[108:111]
	v_mfma_f32_16x16x32_bf16 v[104:107], v[210:213], v[158:161], v[104:107]
	v_mfma_f32_16x16x32_bf16 v[92:95], v[202:205], v[166:169], v[92:95]
	v_mfma_f32_16x16x32_bf16 v[88:91], v[210:213], v[166:169], v[88:91]
	v_mfma_f32_16x16x32_bf16 v[76:79], v[202:205], v[182:185], v[76:79]
	v_mfma_f32_16x16x32_bf16 v[72:75], v[210:213], v[182:185], v[72:75]
	v_mfma_f32_16x16x32_bf16 v[68:71], v[202:205], v[194:197], v[68:71]
	v_mfma_f32_16x16x32_bf16 v[64:67], v[210:213], v[194:197], v[64:67]
	v_mfma_f32_16x16x32_bf16 v[108:111], v[206:209], v[162:165], v[108:111]
	v_mfma_f32_16x16x32_bf16 v[104:107], v[214:217], v[162:165], v[104:107]
	v_mfma_f32_16x16x32_bf16 v[92:95], v[206:209], v[170:173], v[92:95]
	v_mfma_f32_16x16x32_bf16 v[88:91], v[214:217], v[170:173], v[88:91]
	v_mfma_f32_16x16x32_bf16 v[76:79], v[206:209], v[190:193], v[76:79]
	v_mfma_f32_16x16x32_bf16 v[72:75], v[214:217], v[190:193], v[72:75]
	v_mfma_f32_16x16x32_bf16 v[68:71], v[206:209], v[198:201], v[68:71]
	v_mfma_f32_16x16x32_bf16 v[64:67], v[214:217], v[198:201], v[64:67]
	s_mov_b32 m0, s28
	s_barrier
	ds_read_b128 v[158:161], v141 offset:49152
	ds_read_b128 v[162:165], v141 offset:50176
	ds_read_b128 v[166:169], v141 offset:51200
	ds_read_b128 v[170:173], v141 offset:52224
	ds_read_b128 v[182:185], v141 offset:53248
	ds_read_b128 v[190:193], v141 offset:54272
	ds_read_b128 v[194:197], v141 offset:55296
	global_load_lds_dwordx4 v132, s[100:101]
	s_mov_b32 m0, s29
	ds_read_b128 v[198:201], v141 offset:56320
	global_load_lds_dwordx4 v130, s[100:101]
	s_barrier
	s_waitcnt lgkmcnt(0)
	v_mfma_f32_16x16x32_bf16 v[60:63], v[142:145], v[158:161], v[60:63]
	v_mfma_f32_16x16x32_bf16 v[56:59], v[150:153], v[158:161], v[56:59]
	v_mfma_f32_16x16x32_bf16 v[52:55], v[142:145], v[166:169], v[52:55]
	v_mfma_f32_16x16x32_bf16 v[48:51], v[150:153], v[166:169], v[48:51]
	v_mfma_f32_16x16x32_bf16 v[36:39], v[142:145], v[182:185], v[36:39]
	v_mfma_f32_16x16x32_bf16 v[32:35], v[150:153], v[182:185], v[32:35]
	v_mfma_f32_16x16x32_bf16 v[20:23], v[142:145], v[194:197], v[20:23]
	v_mfma_f32_16x16x32_bf16 v[16:19], v[150:153], v[194:197], v[16:19]
	v_mfma_f32_16x16x32_bf16 v[60:63], v[146:149], v[162:165], v[60:63]
	v_mfma_f32_16x16x32_bf16 v[56:59], v[154:157], v[162:165], v[56:59]
	v_mfma_f32_16x16x32_bf16 v[52:55], v[146:149], v[170:173], v[52:55]
	v_mfma_f32_16x16x32_bf16 v[48:51], v[154:157], v[170:173], v[48:51]
	v_mfma_f32_16x16x32_bf16 v[36:39], v[146:149], v[190:193], v[36:39]
	v_mfma_f32_16x16x32_bf16 v[32:35], v[154:157], v[190:193], v[32:35]
	v_mfma_f32_16x16x32_bf16 v[20:23], v[146:149], v[198:201], v[20:23]
	v_mfma_f32_16x16x32_bf16 v[16:19], v[154:157], v[198:201], v[16:19]
	s_barrier
	s_add_u32 s14, s14, 0x40080
	s_addc_u32 s15, s15, 0
	s_add_i32 m0, s20, 0x1c000
	s_nop 0
	global_load_lds_dwordx4 v176, s[14:15]
	s_add_i32 m0, s20, 0x1e000
	s_nop 0
	global_load_lds_dwordx4 v128, s[14:15]
	s_waitcnt vmcnt(6)
	s_barrier
	v_mfma_f32_16x16x32_bf16 v[44:47], v[202:205], v[158:161], v[44:47]
	v_mfma_f32_16x16x32_bf16 v[40:43], v[210:213], v[158:161], v[40:43]
	v_mfma_f32_16x16x32_bf16 v[28:31], v[202:205], v[166:169], v[28:31]
	v_mfma_f32_16x16x32_bf16 v[24:27], v[210:213], v[166:169], v[24:27]
	v_mfma_f32_16x16x32_bf16 v[12:15], v[202:205], v[182:185], v[12:15]
	v_mfma_f32_16x16x32_bf16 v[8:11], v[210:213], v[182:185], v[8:11]
	v_mfma_f32_16x16x32_bf16 v[4:7], v[202:205], v[194:197], v[4:7]
	v_mfma_f32_16x16x32_bf16 v[0:3], v[210:213], v[194:197], v[0:3]
	v_mfma_f32_16x16x32_bf16 v[44:47], v[206:209], v[162:165], v[44:47]
	v_mfma_f32_16x16x32_bf16 v[40:43], v[214:217], v[162:165], v[40:43]
	v_mfma_f32_16x16x32_bf16 v[28:31], v[206:209], v[170:173], v[28:31]
	v_mfma_f32_16x16x32_bf16 v[24:27], v[214:217], v[170:173], v[24:27]
	v_mfma_f32_16x16x32_bf16 v[12:15], v[206:209], v[190:193], v[12:15]
	v_mfma_f32_16x16x32_bf16 v[8:11], v[214:217], v[190:193], v[8:11]
	v_mfma_f32_16x16x32_bf16 v[4:7], v[206:209], v[198:201], v[4:7]
	v_mfma_f32_16x16x32_bf16 v[0:3], v[214:217], v[198:201], v[0:3]
	s_add_i32 s45, s45, 2
	s_add_u32 s12, s12, 0x100
	s_addc_u32 s13, s13, 0
	s_add_u32 s43, s43, 0x100
	s_addc_u32 s44, s44, 0
	s_cmp_gt_u32 s45, 13
	s_barrier
; __device__ __forceinline__ unsigned cvtpk(float lo, float hi) { const f32x2 v = (f32x2){lo, hi}; const bf16v2 b = __builtin_convertvector(v, bf16v2); return __builtin_bit_cast(unsigned, b); }
; template <class Epi, class Sched>
; __device__ __forceinline__ void gemm_phase(PG8_LAS unsigned char* lds, const Gemm g, const Sched& S, const Epi& E) {
;     ...
;         if constexpr (!Epi::AFTER_DRAIN) { E(acc, cur, wr, wc, fr, fq); S.done(cur); }
;         if (!has_next) break;
; #pragma unroll
;         for (int a = 0; a < 2; ++a)
; #pragma unroll
;             for (int b = 0; b < 2; ++b)
; #pragma unroll
;                 for (int m = 0; m < 4; ++m)
; #pragma unroll
;                     for (int n = 0; n < 2; ++n) acc[a][b][m][n] = (f32x4){0.f, 0.f, 0.f, 0.f};
;         cur = nxt; cA = nA; cB = nB; ++ui;
;     __device__ __forceinline__ void operator()(const f32x4 (&acc)[2][2][4][2], const pg8::Unit& u, int wr, int wc, int fr, int fq) const {
;         const int row0 = u.pm * 256 + wr * 64 + fr, col0 = u.pn * 256 + wc * 32 + 8 * fq;
; #pragma unroll
;         for (int ai = 0; ai < 2; ++ai)
; #pragma unroll
;             for (int m = 0; m < 4; ++m) { bf16_t* rowp = O + (size_t)(row0 + ai * 128 + m * 16) * ldc + col0;
; #pragma unroll
;                 for (int bj = 0; bj < 2; ++bj) { const f32x4 v0 = acc[ai][bj][m][0], v1 = acc[ai][bj][m][1];
;                     u32x4 w; w.x = cvtpk(v0[0], v0[1]); w.y = cvtpk(v0[2], v0[3]); w.z = cvtpk(v1[0], v1[1]); w.w = cvtpk(v1[2], v1[3]);
;                     *(u32x4*)(rowp + bj * 128) = w; } }
;     }
	s_cbranch_scc0 .LBB0_358
	v_readlane_b32 s12, v253, 16
	v_lshl_add_u32 v148, s0, 8, v138
	v_lshl_or_b32 v142, s34, 8, v140
	v_readlane_b32 s13, v253, 17
	v_ashrrev_i32_e32 v143, 31, v142
	v_cvt_pk_bf16_f32 v68, v68, v69
	v_mov_b64_e32 v[144:145], s[12:13]
	v_cvt_pk_bf16_f32 v69, v70, v71
	v_cvt_pk_bf16_f32 v70, v64, v65
	v_add_u32_e32 v64, 0x80, v148
	v_mad_i64_i32 v[146:147], s[12:13], v148, s81, v[144:145]
	v_lshlrev_b64 v[142:143], 1, v[142:143]
	v_cvt_pk_bf16_f32 v108, v108, v109
	v_cvt_pk_bf16_f32 v109, v110, v111
	v_cvt_pk_bf16_f32 v110, v104, v105
	v_or_b32_e32 v104, 16, v148
	v_mad_i64_i32 v[64:65], s[12:13], v64, s81, v[144:145]
	v_cvt_pk_bf16_f32 v44, v44, v45
	v_cvt_pk_bf16_f32 v45, v46, v47
	v_cvt_pk_bf16_f32 v46, v40, v41
	v_add_u32_e32 v40, 0x90, v148
	v_lshl_add_u64 v[146:147], v[146:147], 0, v[142:143]
	v_cvt_pk_bf16_f32 v111, v106, v107
	v_mad_i64_i32 v[104:105], s[12:13], v104, s81, v[144:145]
	v_cvt_pk_bf16_f32 v92, v92, v93
	v_cvt_pk_bf16_f32 v93, v94, v95
	v_cvt_pk_bf16_f32 v94, v88, v89
	v_or_b32_e32 v88, 32, v148
	v_lshl_add_u64 v[64:65], v[64:65], 0, v[142:143]
	v_cvt_pk_bf16_f32 v47, v42, v43
	v_mad_i64_i32 v[40:41], s[12:13], v40, s81, v[144:145]
	v_cvt_pk_bf16_f32 v28, v28, v29
	v_cvt_pk_bf16_f32 v29, v30, v31
	v_cvt_pk_bf16_f32 v30, v24, v25
	v_add_u32_e32 v24, 0xa0, v148
	global_store_dwordx4 v[146:147], v[108:111], off offset:256
	v_cvt_pk_bf16_f32 v95, v90, v91
	v_mad_i64_i32 v[88:89], s[12:13], v88, s81, v[144:145]
	v_lshl_add_u64 v[108:109], v[104:105], 0, v[142:143]
	v_cvt_pk_bf16_f32 v76, v76, v77
	v_cvt_pk_bf16_f32 v77, v78, v79
	v_cvt_pk_bf16_f32 v78, v72, v73
	v_or_b32_e32 v72, 48, v148
	global_store_dwordx4 v[64:65], v[44:47], off offset:256
	v_cvt_pk_bf16_f32 v31, v26, v27
	v_mad_i64_i32 v[24:25], s[12:13], v24, s81, v[144:145]
	v_lshl_add_u64 v[44:45], v[40:41], 0, v[142:143]
	v_cvt_pk_bf16_f32 v12, v12, v13
	v_cvt_pk_bf16_f32 v13, v14, v15
	v_cvt_pk_bf16_f32 v14, v8, v9
	v_add_u32_e32 v8, 0xb0, v148
	global_store_dwordx4 v[108:109], v[92:95], off offset:256
	v_cvt_pk_bf16_f32 v79, v74, v75
	v_mad_i64_i32 v[72:73], s[12:13], v72, s81, v[144:145]
	v_lshl_add_u64 v[92:93], v[88:89], 0, v[142:143]
	global_store_dwordx4 v[44:45], v[28:31], off offset:256
	v_cvt_pk_bf16_f32 v15, v10, v11
	v_mad_i64_i32 v[8:9], s[12:13], v8, s81, v[144:145]
	v_lshl_add_u64 v[28:29], v[24:25], 0, v[142:143]
	v_cvt_pk_bf16_f32 v124, v124, v125
	v_cvt_pk_bf16_f32 v125, v126, v127
	v_cvt_pk_bf16_f32 v126, v120, v121
	v_cvt_pk_bf16_f32 v127, v122, v123
	v_cvt_pk_bf16_f32 v104, v116, v117
	v_cvt_pk_bf16_f32 v105, v118, v119
	v_cvt_pk_bf16_f32 v106, v112, v113
	v_cvt_pk_bf16_f32 v107, v114, v115
	v_cvt_pk_bf16_f32 v88, v100, v101
	v_cvt_pk_bf16_f32 v89, v102, v103
	v_cvt_pk_bf16_f32 v90, v96, v97
	v_cvt_pk_bf16_f32 v91, v98, v99
	global_store_dwordx4 v[92:93], v[76:79], off offset:256
	v_cvt_pk_bf16_f32 v74, v80, v81
	v_cvt_pk_bf16_f32 v75, v82, v83
	v_lshl_add_u64 v[76:77], v[72:73], 0, v[142:143]
	v_cvt_pk_bf16_f32 v72, v84, v85
	v_cvt_pk_bf16_f32 v73, v86, v87
	v_cvt_pk_bf16_f32 v71, v66, v67
	v_cvt_pk_bf16_f32 v60, v60, v61
	v_cvt_pk_bf16_f32 v61, v62, v63
	v_cvt_pk_bf16_f32 v62, v56, v57
	v_cvt_pk_bf16_f32 v63, v58, v59
	v_cvt_pk_bf16_f32 v40, v52, v53
	v_cvt_pk_bf16_f32 v41, v54, v55
	v_cvt_pk_bf16_f32 v42, v48, v49
	v_cvt_pk_bf16_f32 v43, v50, v51
	v_cvt_pk_bf16_f32 v24, v36, v37
	v_cvt_pk_bf16_f32 v25, v38, v39
	v_cvt_pk_bf16_f32 v26, v32, v33
	v_cvt_pk_bf16_f32 v27, v34, v35
	global_store_dwordx4 v[28:29], v[12:15], off offset:256
	v_cvt_pk_bf16_f32 v10, v16, v17
	v_cvt_pk_bf16_f32 v11, v18, v19
	v_lshl_add_u64 v[12:13], v[8:9], 0, v[142:143]
	v_cvt_pk_bf16_f32 v8, v20, v21
	v_cvt_pk_bf16_f32 v9, v22, v23
	v_cvt_pk_bf16_f32 v4, v4, v5
	v_cvt_pk_bf16_f32 v5, v6, v7
	v_cvt_pk_bf16_f32 v6, v0, v1
	v_cvt_pk_bf16_f32 v7, v2, v3
	s_and_b64 vcc, exec, s[38:39]
	s_mov_b32 s34, s4
	s_mov_b32 s0, s6
	s_mov_b64 s[14:15], s[10:11]
	s_mov_b64 s[12:13], s[8:9]
	global_store_dwordx4 v[146:147], v[124:127], off
	global_store_dwordx4 v[108:109], v[104:107], off
	global_store_dwordx4 v[92:93], v[88:91], off
	global_store_dwordx4 v[76:77], v[72:75], off
	global_store_dwordx4 v[76:77], v[68:71], off offset:256
	global_store_dwordx4 v[64:65], v[60:63], off
	global_store_dwordx4 v[44:45], v[40:43], off
	global_store_dwordx4 v[28:29], v[24:27], off
	global_store_dwordx4 v[12:13], v[8:11], off
	global_store_dwordx4 v[12:13], v[4:7], off offset:256
	s_cbranch_vccz .LBB0_355
	s_waitcnt vmcnt(0)
	v_readlane_b32 s22, v255, 14
	s_cmpk_gt_u32 s19, 0xff
	v_readlane_b32 s23, v255, 15
	s_mov_b64 s[28:29], s[54:55]
	s_cbranch_scc1 .LBB0_362
	s_barrier
